# DSA indexer scoring rewritten as software-pipelined loop: permlane16_swap transpose instead of ds_swizzle, double-buffered LDS reads, saddr scratch stores
# speedup vs baseline: 1.0534x; 1.0116x over previous
.LBB0_891:
	s_add_i32 s4, s66, 15
	s_lshr_b32 s4, s4, 8
	s_add_i32 s4, s4, 1
	v_readfirstlane_b32 s8, v24
	v_readfirstlane_b32 s9, v25
	v_lshlrev_b32_e32 v168, 2, v242
	v_mov_b32_e32 v169, 0
	v_add_u32_e32 v166, 0x10000, v124
	v_add_u32_e32 v167, 0x10000, v125
	s_nop 1
	s_add_u32 s14, s8, 0x1000
	s_addc_u32 s15, s9, 0
	s_add_u32 s46, s8, 0x2000
	s_addc_u32 s47, s9, 0
	s_add_u32 s68, s8, 0x3000
	s_addc_u32 s69, s9, 0
	s_add_u32 s48, s48, 0x10000
	s_addc_u32 s49, s49, 0
.Lsc_h0:
	s_cmp_gt_u32 s4, 2
	s_cbranch_scc0 .Lsc_ni0
	v_lshl_add_u64 v[170:171], s[48:49], 0, v[0:1]
	s_add_i32 m0, s1, 0x10000
	s_nop 0
	global_load_lds_dwordx4 v[170:171], off
	v_lshl_add_u64 v[170:171], s[48:49], 0, v[18:19]
	s_add_i32 m0, s1, 0x12000
	s_nop 0
	global_load_lds_dwordx4 v[170:171], off
	v_lshl_add_u64 v[170:171], s[48:49], 0, v[20:21]
	s_add_i32 m0, s1, 0x14000
	s_nop 0
	global_load_lds_dwordx4 v[170:171], off
	v_lshl_add_u64 v[170:171], s[48:49], 0, v[22:23]
	s_add_i32 m0, s1, 0x16000
	s_nop 0
	global_load_lds_dwordx4 v[170:171], off
	s_add_u32 s48, s48, 0x8000
	s_addc_u32 s49, s49, 0
	s_waitcnt vmcnt(8)
	s_branch .Lsc_b0
.Lsc_ni0:
	s_cmp_gt_u32 s4, 1
	s_cbranch_scc0 .Lsc_w00
	s_waitcnt vmcnt(4)
	s_branch .Lsc_b0

.Lsc_b0:
	s_barrier
	ds_read_b128 v[26:29], v124
	ds_read_b128 v[30:33], v124 offset:2048
	ds_read_b128 v[34:37], v124 offset:4096
	ds_read_b128 v[38:41], v124 offset:6144
	ds_read_b128 v[42:45], v125
	ds_read_b128 v[46:49], v125 offset:2048
	ds_read_b128 v[50:53], v125 offset:4096
	ds_read_b128 v[54:57], v125 offset:6144
	ds_read_b128 v[58:61], v124 offset:8192
	ds_read_b128 v[62:65], v124 offset:10240
	ds_read_b128 v[66:69], v124 offset:12288
	ds_read_b128 v[70:73], v124 offset:14336
	ds_read_b128 v[74:77], v125 offset:8192
	ds_read_b128 v[78:81], v125 offset:10240
	ds_read_b128 v[82:85], v125 offset:12288
	ds_read_b128 v[86:89], v125 offset:14336
	s_waitcnt lgkmcnt(8)
	v_mfma_f32_16x16x32_bf16 v[90:93], v[10:13], v[26:29], 0
	v_mfma_f32_16x16x32_bf16 v[94:97], v[10:13], v[30:33], 0
	v_mfma_f32_16x16x32_bf16 v[98:101], v[10:13], v[34:37], 0
	v_mfma_f32_16x16x32_bf16 v[102:105], v[10:13], v[38:41], 0
	v_mfma_f32_16x16x32_bf16 v[90:93], v[6:9], v[42:45], v[90:93]
	v_mfma_f32_16x16x32_bf16 v[94:97], v[6:9], v[46:49], v[94:97]
	v_mfma_f32_16x16x32_bf16 v[98:101], v[6:9], v[50:53], v[98:101]
	v_mfma_f32_16x16x32_bf16 v[102:105], v[6:9], v[54:57], v[102:105]
	ds_read_b128 v[26:29], v124 offset:16384
	ds_read_b128 v[30:33], v124 offset:18432
	ds_read_b128 v[34:37], v124 offset:20480
	ds_read_b128 v[38:41], v124 offset:22528
	ds_read_b128 v[42:45], v125 offset:16384
	ds_read_b128 v[46:49], v125 offset:18432
	ds_read_b128 v[50:53], v125 offset:20480
	ds_read_b128 v[54:57], v125 offset:22528
	s_waitcnt lgkmcnt(8)
	v_mfma_f32_16x16x32_bf16 v[106:109], v[10:13], v[58:61], 0
	s_sub_i32 s5, s57, 0
	s_add_i32 s67, s5, 1
	v_med3_f32 v90, v90, 0, v240
	v_med3_f32 v91, v91, 0, v240
	v_med3_f32 v92, v92, 0, v240
	v_med3_f32 v93, v93, 0, v240
	v_mul_f32_e32 v160, v2, v90
	v_mul_f32_e32 v161, v3, v91
	v_mfma_f32_16x16x32_bf16 v[110:113], v[10:13], v[62:65], 0
	v_mul_f32_e32 v162, v4, v92
	v_mul_f32_e32 v163, v5, v93
	v_add_f32_e32 v156, v160, v161
	v_add_f32_e32 v156, v162, v156
	v_add_f32_e32 v156, v163, v156
	v_med3_f32 v94, v94, 0, v240
	v_med3_f32 v95, v95, 0, v240
	v_med3_f32 v96, v96, 0, v240
	v_mfma_f32_16x16x32_bf16 v[114:117], v[10:13], v[66:69], 0
	v_med3_f32 v97, v97, 0, v240
	v_mul_f32_e32 v160, v2, v94
	v_mul_f32_e32 v161, v3, v95
	v_mul_f32_e32 v162, v4, v96
	v_mul_f32_e32 v163, v5, v97
	v_add_f32_e32 v157, v160, v161
	v_add_f32_e32 v157, v162, v157
	v_add_f32_e32 v157, v163, v157
	v_mfma_f32_16x16x32_bf16 v[118:121], v[10:13], v[70:73], 0
	v_med3_f32 v98, v98, 0, v240
	v_med3_f32 v99, v99, 0, v240
	v_med3_f32 v100, v100, 0, v240
	v_med3_f32 v101, v101, 0, v240
	v_mul_f32_e32 v160, v2, v98
	v_mul_f32_e32 v161, v3, v99
	v_mul_f32_e32 v162, v4, v100
	v_mul_f32_e32 v163, v5, v101
	v_mfma_f32_16x16x32_bf16 v[106:109], v[6:9], v[74:77], v[106:109]
	v_add_f32_e32 v158, v160, v161
	v_add_f32_e32 v158, v162, v158
	v_add_f32_e32 v158, v163, v158
	v_med3_f32 v102, v102, 0, v240
	v_med3_f32 v103, v103, 0, v240
	v_med3_f32 v104, v104, 0, v240
	v_med3_f32 v105, v105, 0, v240
	v_mul_f32_e32 v160, v2, v102
	v_mfma_f32_16x16x32_bf16 v[110:113], v[6:9], v[78:81], v[110:113]
	v_mul_f32_e32 v161, v3, v103
	v_mul_f32_e32 v162, v4, v104
	v_mul_f32_e32 v163, v5, v105
	v_add_f32_e32 v159, v160, v161
	v_add_f32_e32 v159, v162, v159
	v_add_f32_e32 v159, v163, v159
	s_nop 1
	v_permlane16_swap_b32_e32 v156, v157
	v_mfma_f32_16x16x32_bf16 v[114:117], v[6:9], v[82:85], v[114:117]
	v_permlane16_swap_b32_e32 v158, v159
	v_add_f32_e32 v156, v156, v157
	v_add_f32_e32 v158, v158, v159
	s_nop 1
	v_permlane32_swap_b32_e32 v156, v158
	v_ashrrev_i32_e32 v164, 31, v156
	v_ashrrev_i32_e32 v165, 31, v158
	v_or_b32_e32 v164, 0x80000000, v164
	v_mfma_f32_16x16x32_bf16 v[118:121], v[6:9], v[86:89], v[118:121]
	v_or_b32_e32 v165, 0x80000000, v165
	v_xor_b32_e32 v164, v156, v164
	v_xor_b32_e32 v165, v158, v165
	v_and_b32_e32 v164, 0xffffff00, v164
	v_and_b32_e32 v165, 0xffffff00, v165
	v_cmp_ge_i32_e32 vcc, s5, v242
	s_nop 1
	v_cndmask_b32_e32 v152, 0, v164, vcc
	v_cmp_ge_i32_e32 vcc, s67, v242
	s_nop 1
	v_cndmask_b32_e32 v165, 0, v165, vcc
	global_store_dword v168, v165, s[8:9]
	ds_read_b128 v[58:61], v124 offset:24576
	ds_read_b128 v[62:65], v124 offset:26624
	ds_read_b128 v[66:69], v124 offset:28672
	ds_read_b128 v[70:73], v124 offset:30720
	ds_read_b128 v[74:77], v125 offset:24576
	ds_read_b128 v[78:81], v125 offset:26624
	ds_read_b128 v[82:85], v125 offset:28672
	ds_read_b128 v[86:89], v125 offset:30720
	s_waitcnt lgkmcnt(8)
	v_mfma_f32_16x16x32_bf16 v[90:93], v[10:13], v[26:29], 0
	s_sub_i32 s5, s57, 64
	s_add_i32 s67, s5, 1
	v_med3_f32 v106, v106, 0, v240
	v_med3_f32 v107, v107, 0, v240
	v_med3_f32 v108, v108, 0, v240
	v_med3_f32 v109, v109, 0, v240
	v_mul_f32_e32 v160, v2, v106
	v_mul_f32_e32 v161, v3, v107
	v_mfma_f32_16x16x32_bf16 v[94:97], v[10:13], v[30:33], 0
	v_mul_f32_e32 v162, v4, v108
	v_mul_f32_e32 v163, v5, v109
	v_add_f32_e32 v156, v160, v161
	v_add_f32_e32 v156, v162, v156
	v_add_f32_e32 v156, v163, v156
	v_med3_f32 v110, v110, 0, v240
	v_med3_f32 v111, v111, 0, v240
	v_med3_f32 v112, v112, 0, v240
	v_mfma_f32_16x16x32_bf16 v[98:101], v[10:13], v[34:37], 0
	v_med3_f32 v113, v113, 0, v240
	v_mul_f32_e32 v160, v2, v110
	v_mul_f32_e32 v161, v3, v111
	v_mul_f32_e32 v162, v4, v112
	v_mul_f32_e32 v163, v5, v113
	v_add_f32_e32 v157, v160, v161
	v_add_f32_e32 v157, v162, v157
	v_add_f32_e32 v157, v163, v157
	v_mfma_f32_16x16x32_bf16 v[102:105], v[10:13], v[38:41], 0
	v_med3_f32 v114, v114, 0, v240
	v_med3_f32 v115, v115, 0, v240
	v_med3_f32 v116, v116, 0, v240
	v_med3_f32 v117, v117, 0, v240
	v_mul_f32_e32 v160, v2, v114
	v_mul_f32_e32 v161, v3, v115
	v_mul_f32_e32 v162, v4, v116
	v_mul_f32_e32 v163, v5, v117
	v_mfma_f32_16x16x32_bf16 v[90:93], v[6:9], v[42:45], v[90:93]
	v_add_f32_e32 v158, v160, v161
	v_add_f32_e32 v158, v162, v158
	v_add_f32_e32 v158, v163, v158
	v_med3_f32 v118, v118, 0, v240
	v_med3_f32 v119, v119, 0, v240
	v_med3_f32 v120, v120, 0, v240
	v_med3_f32 v121, v121, 0, v240
	v_mul_f32_e32 v160, v2, v118
	v_mfma_f32_16x16x32_bf16 v[94:97], v[6:9], v[46:49], v[94:97]
	v_mul_f32_e32 v161, v3, v119
	v_mul_f32_e32 v162, v4, v120
	v_mul_f32_e32 v163, v5, v121
	v_add_f32_e32 v159, v160, v161
	v_add_f32_e32 v159, v162, v159
	v_add_f32_e32 v159, v163, v159
	s_nop 1
	v_permlane16_swap_b32_e32 v156, v157
	v_mfma_f32_16x16x32_bf16 v[98:101], v[6:9], v[50:53], v[98:101]
	v_permlane16_swap_b32_e32 v158, v159
	v_add_f32_e32 v156, v156, v157
	v_add_f32_e32 v158, v158, v159
	s_nop 1
	v_permlane32_swap_b32_e32 v156, v158
	v_ashrrev_i32_e32 v164, 31, v156
	v_ashrrev_i32_e32 v165, 31, v158
	v_or_b32_e32 v164, 0x80000000, v164
	v_mfma_f32_16x16x32_bf16 v[102:105], v[6:9], v[54:57], v[102:105]
	v_or_b32_e32 v165, 0x80000000, v165
	v_xor_b32_e32 v164, v156, v164
	v_xor_b32_e32 v165, v158, v165
	v_and_b32_e32 v164, 0xffffff00, v164
	v_and_b32_e32 v165, 0xffffff00, v165
	v_cmp_ge_i32_e32 vcc, s5, v242
	s_nop 1
	v_cndmask_b32_e32 v153, 0, v164, vcc
	v_cmp_ge_i32_e32 vcc, s67, v242
	s_nop 1
	v_cndmask_b32_e32 v165, 0, v165, vcc
	global_store_dword v168, v165, s[8:9] offset:256
	s_waitcnt lgkmcnt(0)
	v_mfma_f32_16x16x32_bf16 v[106:109], v[10:13], v[58:61], 0
	s_sub_i32 s5, s57, 128
	s_add_i32 s67, s5, 1
	v_med3_f32 v90, v90, 0, v240
	v_med3_f32 v91, v91, 0, v240
	v_med3_f32 v92, v92, 0, v240
	v_med3_f32 v93, v93, 0, v240
	v_mul_f32_e32 v160, v2, v90
	v_mul_f32_e32 v161, v3, v91
	v_mfma_f32_16x16x32_bf16 v[110:113], v[10:13], v[62:65], 0
	v_mul_f32_e32 v162, v4, v92
	v_mul_f32_e32 v163, v5, v93
	v_add_f32_e32 v156, v160, v161
	v_add_f32_e32 v156, v162, v156
	v_add_f32_e32 v156, v163, v156
	v_med3_f32 v94, v94, 0, v240
	v_med3_f32 v95, v95, 0, v240
	v_med3_f32 v96, v96, 0, v240
	v_mfma_f32_16x16x32_bf16 v[114:117], v[10:13], v[66:69], 0
	v_med3_f32 v97, v97, 0, v240
	v_mul_f32_e32 v160, v2, v94
	v_mul_f32_e32 v161, v3, v95
	v_mul_f32_e32 v162, v4, v96
	v_mul_f32_e32 v163, v5, v97
	v_add_f32_e32 v157, v160, v161
	v_add_f32_e32 v157, v162, v157
	v_add_f32_e32 v157, v163, v157
	v_mfma_f32_16x16x32_bf16 v[118:121], v[10:13], v[70:73], 0
	v_med3_f32 v98, v98, 0, v240
	v_med3_f32 v99, v99, 0, v240
	v_med3_f32 v100, v100, 0, v240
	v_med3_f32 v101, v101, 0, v240
	v_mul_f32_e32 v160, v2, v98
	v_mul_f32_e32 v161, v3, v99
	v_mul_f32_e32 v162, v4, v100
	v_mul_f32_e32 v163, v5, v101
	v_mfma_f32_16x16x32_bf16 v[106:109], v[6:9], v[74:77], v[106:109]
	v_add_f32_e32 v158, v160, v161
	v_add_f32_e32 v158, v162, v158
	v_add_f32_e32 v158, v163, v158
	v_med3_f32 v102, v102, 0, v240
	v_med3_f32 v103, v103, 0, v240
	v_med3_f32 v104, v104, 0, v240
	v_med3_f32 v105, v105, 0, v240
	v_mul_f32_e32 v160, v2, v102
	v_mfma_f32_16x16x32_bf16 v[110:113], v[6:9], v[78:81], v[110:113]
	v_mul_f32_e32 v161, v3, v103
	v_mul_f32_e32 v162, v4, v104
	v_mul_f32_e32 v163, v5, v105
	v_add_f32_e32 v159, v160, v161
	v_add_f32_e32 v159, v162, v159
	v_add_f32_e32 v159, v163, v159
	s_nop 1
	v_permlane16_swap_b32_e32 v156, v157
	v_mfma_f32_16x16x32_bf16 v[114:117], v[6:9], v[82:85], v[114:117]
	v_permlane16_swap_b32_e32 v158, v159
	v_add_f32_e32 v156, v156, v157
	v_add_f32_e32 v158, v158, v159
	s_nop 1
	v_permlane32_swap_b32_e32 v156, v158
	v_ashrrev_i32_e32 v164, 31, v156
	v_ashrrev_i32_e32 v165, 31, v158
	v_or_b32_e32 v164, 0x80000000, v164
	v_mfma_f32_16x16x32_bf16 v[118:121], v[6:9], v[86:89], v[118:121]
	v_or_b32_e32 v165, 0x80000000, v165
	v_xor_b32_e32 v164, v156, v164
	v_xor_b32_e32 v165, v158, v165
	v_and_b32_e32 v164, 0xffffff00, v164
	v_and_b32_e32 v165, 0xffffff00, v165
	v_cmp_ge_i32_e32 vcc, s5, v242
	s_nop 1
	v_cndmask_b32_e32 v154, 0, v164, vcc
	v_cmp_ge_i32_e32 vcc, s67, v242
	s_nop 1
	v_cndmask_b32_e32 v165, 0, v165, vcc
	global_store_dword v168, v165, s[8:9] offset:512
.Lsc_h1:
	s_cmp_le_u32 s4, 1
	s_cbranch_scc1 .Lsc_drain1
	s_cmp_gt_u32 s4, 3
	s_cbranch_scc0 .Lsc_ni1
	v_lshl_add_u64 v[170:171], s[48:49], 0, v[0:1]
	s_add_i32 m0, s1, 0x18000
	s_nop 0
	global_load_lds_dwordx4 v[170:171], off
	v_lshl_add_u64 v[170:171], s[48:49], 0, v[18:19]
	s_add_i32 m0, s1, 0x1a000
	s_nop 0
	global_load_lds_dwordx4 v[170:171], off
	v_lshl_add_u64 v[170:171], s[48:49], 0, v[20:21]
	s_add_i32 m0, s1, 0x1c000
	s_nop 0
	global_load_lds_dwordx4 v[170:171], off
	v_lshl_add_u64 v[170:171], s[48:49], 0, v[22:23]
	s_add_i32 m0, s1, 0x1e000
	s_nop 0
	global_load_lds_dwordx4 v[170:171], off
	s_add_u32 s48, s48, 0x8000
	s_addc_u32 s49, s49, 0
	s_waitcnt vmcnt(8)
	s_branch .Lsc_b1
.Lsc_ni1:
	s_cmp_gt_u32 s4, 2
	s_cbranch_scc0 .Lsc_w01
	s_waitcnt vmcnt(4)
	s_branch .Lsc_b1

.Lsc_b1:
	s_barrier
	ds_read_b128 v[26:29], v124 offset:32768
	ds_read_b128 v[30:33], v124 offset:34816
	ds_read_b128 v[34:37], v124 offset:36864
	ds_read_b128 v[38:41], v124 offset:38912
	ds_read_b128 v[42:45], v125 offset:32768
	ds_read_b128 v[46:49], v125 offset:34816
	ds_read_b128 v[50:53], v125 offset:36864
	ds_read_b128 v[54:57], v125 offset:38912
	ds_read_b128 v[58:61], v124 offset:40960
	ds_read_b128 v[62:65], v124 offset:43008
	ds_read_b128 v[66:69], v124 offset:45056
	ds_read_b128 v[70:73], v124 offset:47104
	ds_read_b128 v[74:77], v125 offset:40960
	ds_read_b128 v[78:81], v125 offset:43008
	ds_read_b128 v[82:85], v125 offset:45056
	ds_read_b128 v[86:89], v125 offset:47104
	s_sub_i32 s5, s57, 192
	s_add_i32 s67, s5, 1
	v_med3_f32 v106, v106, 0, v240
	v_med3_f32 v107, v107, 0, v240
	v_med3_f32 v108, v108, 0, v240
	v_med3_f32 v109, v109, 0, v240
	v_mul_f32_e32 v160, v2, v106
	v_mul_f32_e32 v161, v3, v107
	v_mul_f32_e32 v162, v4, v108
	v_mul_f32_e32 v163, v5, v109
	v_add_f32_e32 v156, v160, v161
	v_add_f32_e32 v156, v162, v156
	v_add_f32_e32 v156, v163, v156
	v_med3_f32 v110, v110, 0, v240
	v_med3_f32 v111, v111, 0, v240
	v_med3_f32 v112, v112, 0, v240
	v_med3_f32 v113, v113, 0, v240
	v_mul_f32_e32 v160, v2, v110
	v_mul_f32_e32 v161, v3, v111
	v_mul_f32_e32 v162, v4, v112
	v_mul_f32_e32 v163, v5, v113
	v_add_f32_e32 v157, v160, v161
	v_add_f32_e32 v157, v162, v157
	v_add_f32_e32 v157, v163, v157
	v_med3_f32 v114, v114, 0, v240
	v_med3_f32 v115, v115, 0, v240
	v_med3_f32 v116, v116, 0, v240
	v_med3_f32 v117, v117, 0, v240
	v_mul_f32_e32 v160, v2, v114
	v_mul_f32_e32 v161, v3, v115
	v_mul_f32_e32 v162, v4, v116
	v_mul_f32_e32 v163, v5, v117
	v_add_f32_e32 v158, v160, v161
	v_add_f32_e32 v158, v162, v158
	s_waitcnt lgkmcnt(8)
	v_mfma_f32_16x16x32_bf16 v[90:93], v[10:13], v[26:29], 0
	v_add_f32_e32 v158, v163, v158
	v_med3_f32 v118, v118, 0, v240
	v_med3_f32 v119, v119, 0, v240
	v_med3_f32 v120, v120, 0, v240
	v_mfma_f32_16x16x32_bf16 v[94:97], v[10:13], v[30:33], 0
	v_med3_f32 v121, v121, 0, v240
	v_mul_f32_e32 v160, v2, v118
	v_mul_f32_e32 v161, v3, v119
	v_mul_f32_e32 v162, v4, v120
	v_mfma_f32_16x16x32_bf16 v[98:101], v[10:13], v[34:37], 0
	v_mul_f32_e32 v163, v5, v121
	v_add_f32_e32 v159, v160, v161
	v_add_f32_e32 v159, v162, v159
	v_add_f32_e32 v159, v163, v159
	v_mfma_f32_16x16x32_bf16 v[102:105], v[10:13], v[38:41], 0
	s_nop 1
	v_permlane16_swap_b32_e32 v156, v157
	v_permlane16_swap_b32_e32 v158, v159
	v_add_f32_e32 v156, v156, v157
	v_mfma_f32_16x16x32_bf16 v[90:93], v[6:9], v[42:45], v[90:93]
	v_add_f32_e32 v158, v158, v159
	s_nop 1
	v_permlane32_swap_b32_e32 v156, v158
	v_ashrrev_i32_e32 v164, 31, v156
	v_mfma_f32_16x16x32_bf16 v[94:97], v[6:9], v[46:49], v[94:97]
	v_ashrrev_i32_e32 v165, 31, v158
	v_or_b32_e32 v164, 0x80000000, v164
	v_or_b32_e32 v165, 0x80000000, v165
	v_xor_b32_e32 v164, v156, v164
	v_mfma_f32_16x16x32_bf16 v[98:101], v[6:9], v[50:53], v[98:101]
	v_xor_b32_e32 v165, v158, v165
	v_and_b32_e32 v164, 0xffffff00, v164
	v_and_b32_e32 v165, 0xffffff00, v165
	v_cmp_ge_i32_e32 vcc, s5, v242
	v_mfma_f32_16x16x32_bf16 v[102:105], v[6:9], v[54:57], v[102:105]
	s_nop 1
	v_cndmask_b32_e32 v155, 0, v164, vcc
	v_cmp_ge_i32_e32 vcc, s67, v242
	s_nop 1
	v_cndmask_b32_e32 v165, 0, v165, vcc
	global_store_dword v168, v165, s[8:9] offset:768
	ds_read_b128 v[26:29], v124 offset:49152
	ds_read_b128 v[30:33], v124 offset:51200
	ds_read_b128 v[34:37], v124 offset:53248
	ds_read_b128 v[38:41], v124 offset:55296
	ds_read_b128 v[42:45], v125 offset:49152
	ds_read_b128 v[46:49], v125 offset:51200
	ds_read_b128 v[50:53], v125 offset:53248
	ds_read_b128 v[54:57], v125 offset:55296
	s_waitcnt lgkmcnt(8)
	v_mfma_f32_16x16x32_bf16 v[106:109], v[10:13], v[58:61], 0
	s_sub_i32 s5, s57, 256
	s_add_i32 s67, s5, 1
	v_med3_f32 v90, v90, 0, v240
	v_med3_f32 v91, v91, 0, v240
	v_med3_f32 v92, v92, 0, v240
	v_med3_f32 v93, v93, 0, v240
	v_mul_f32_e32 v160, v2, v90
	v_mul_f32_e32 v161, v3, v91
	v_mfma_f32_16x16x32_bf16 v[110:113], v[10:13], v[62:65], 0
	v_mul_f32_e32 v162, v4, v92
	v_mul_f32_e32 v163, v5, v93
	v_add_f32_e32 v156, v160, v161
	v_add_f32_e32 v156, v162, v156
	v_add_f32_e32 v156, v163, v156
	v_med3_f32 v94, v94, 0, v240
	v_med3_f32 v95, v95, 0, v240
	v_med3_f32 v96, v96, 0, v240
	v_mfma_f32_16x16x32_bf16 v[114:117], v[10:13], v[66:69], 0
	v_med3_f32 v97, v97, 0, v240
	v_mul_f32_e32 v160, v2, v94
	v_mul_f32_e32 v161, v3, v95
	v_mul_f32_e32 v162, v4, v96
	v_mul_f32_e32 v163, v5, v97
	v_add_f32_e32 v157, v160, v161
	v_add_f32_e32 v157, v162, v157
	v_add_f32_e32 v157, v163, v157
	v_mfma_f32_16x16x32_bf16 v[118:121], v[10:13], v[70:73], 0
	v_med3_f32 v98, v98, 0, v240
	v_med3_f32 v99, v99, 0, v240
	v_med3_f32 v100, v100, 0, v240
	v_med3_f32 v101, v101, 0, v240
	v_mul_f32_e32 v160, v2, v98
	v_mul_f32_e32 v161, v3, v99
	v_mul_f32_e32 v162, v4, v100
	v_mul_f32_e32 v163, v5, v101
	v_mfma_f32_16x16x32_bf16 v[106:109], v[6:9], v[74:77], v[106:109]
	v_add_f32_e32 v158, v160, v161
	v_add_f32_e32 v158, v162, v158
	v_add_f32_e32 v158, v163, v158
	v_med3_f32 v102, v102, 0, v240
	v_med3_f32 v103, v103, 0, v240
	v_med3_f32 v104, v104, 0, v240
	v_med3_f32 v105, v105, 0, v240
	v_mul_f32_e32 v160, v2, v102
	v_mfma_f32_16x16x32_bf16 v[110:113], v[6:9], v[78:81], v[110:113]
	v_mul_f32_e32 v161, v3, v103
	v_mul_f32_e32 v162, v4, v104
	v_mul_f32_e32 v163, v5, v105
	v_add_f32_e32 v159, v160, v161
	v_add_f32_e32 v159, v162, v159
	v_add_f32_e32 v159, v163, v159
	s_nop 1
	v_permlane16_swap_b32_e32 v156, v157
	v_mfma_f32_16x16x32_bf16 v[114:117], v[6:9], v[82:85], v[114:117]
	v_permlane16_swap_b32_e32 v158, v159
	v_add_f32_e32 v156, v156, v157
	v_add_f32_e32 v158, v158, v159
	s_nop 1
	v_permlane32_swap_b32_e32 v156, v158
	v_ashrrev_i32_e32 v164, 31, v156
	v_ashrrev_i32_e32 v165, 31, v158
	v_or_b32_e32 v164, 0x80000000, v164
	v_mfma_f32_16x16x32_bf16 v[118:121], v[6:9], v[86:89], v[118:121]
	v_or_b32_e32 v165, 0x80000000, v165
	v_xor_b32_e32 v164, v156, v164
	v_xor_b32_e32 v165, v158, v165
	v_and_b32_e32 v164, 0xffffff00, v164
	v_and_b32_e32 v165, 0xffffff00, v165
	v_cmp_ge_i32_e32 vcc, s5, v242
	s_nop 1
	v_cndmask_b32_e32 v212, 0, v164, vcc
	v_cmp_ge_i32_e32 vcc, s67, v242
	s_nop 1
	v_cndmask_b32_e32 v165, 0, v165, vcc
	global_store_dword v168, v165, s[8:9] offset:1024
	ds_read_b128 v[58:61], v124 offset:57344
	ds_read_b128 v[62:65], v124 offset:59392
	ds_read_b128 v[66:69], v124 offset:61440
	ds_read_b128 v[70:73], v124 offset:63488
	ds_read_b128 v[74:77], v125 offset:57344
	ds_read_b128 v[78:81], v125 offset:59392
	ds_read_b128 v[82:85], v125 offset:61440
	ds_read_b128 v[86:89], v125 offset:63488
	s_waitcnt lgkmcnt(8)
	v_mfma_f32_16x16x32_bf16 v[90:93], v[10:13], v[26:29], 0
	s_sub_i32 s5, s57, 320
	s_add_i32 s67, s5, 1
	v_med3_f32 v106, v106, 0, v240
	v_med3_f32 v107, v107, 0, v240
	v_med3_f32 v108, v108, 0, v240
	v_med3_f32 v109, v109, 0, v240
	v_mul_f32_e32 v160, v2, v106
	v_mul_f32_e32 v161, v3, v107
	v_mfma_f32_16x16x32_bf16 v[94:97], v[10:13], v[30:33], 0
	v_mul_f32_e32 v162, v4, v108
	v_mul_f32_e32 v163, v5, v109
	v_add_f32_e32 v156, v160, v161
	v_add_f32_e32 v156, v162, v156
	v_add_f32_e32 v156, v163, v156
	v_med3_f32 v110, v110, 0, v240
	v_med3_f32 v111, v111, 0, v240
	v_med3_f32 v112, v112, 0, v240
	v_mfma_f32_16x16x32_bf16 v[98:101], v[10:13], v[34:37], 0
	v_med3_f32 v113, v113, 0, v240
	v_mul_f32_e32 v160, v2, v110
	v_mul_f32_e32 v161, v3, v111
	v_mul_f32_e32 v162, v4, v112
	v_mul_f32_e32 v163, v5, v113
	v_add_f32_e32 v157, v160, v161
	v_add_f32_e32 v157, v162, v157
	v_add_f32_e32 v157, v163, v157
	v_mfma_f32_16x16x32_bf16 v[102:105], v[10:13], v[38:41], 0
	v_med3_f32 v114, v114, 0, v240
	v_med3_f32 v115, v115, 0, v240
	v_med3_f32 v116, v116, 0, v240
	v_med3_f32 v117, v117, 0, v240
	v_mul_f32_e32 v160, v2, v114
	v_mul_f32_e32 v161, v3, v115
	v_mul_f32_e32 v162, v4, v116
	v_mul_f32_e32 v163, v5, v117
	v_mfma_f32_16x16x32_bf16 v[90:93], v[6:9], v[42:45], v[90:93]
	v_add_f32_e32 v158, v160, v161
	v_add_f32_e32 v158, v162, v158
	v_add_f32_e32 v158, v163, v158
	v_med3_f32 v118, v118, 0, v240
	v_med3_f32 v119, v119, 0, v240
	v_med3_f32 v120, v120, 0, v240
	v_med3_f32 v121, v121, 0, v240
	v_mul_f32_e32 v160, v2, v118
	v_mfma_f32_16x16x32_bf16 v[94:97], v[6:9], v[46:49], v[94:97]
	v_mul_f32_e32 v161, v3, v119
	v_mul_f32_e32 v162, v4, v120
	v_mul_f32_e32 v163, v5, v121
	v_add_f32_e32 v159, v160, v161
	v_add_f32_e32 v159, v162, v159
	v_add_f32_e32 v159, v163, v159
	s_nop 1
	v_permlane16_swap_b32_e32 v156, v157
	v_mfma_f32_16x16x32_bf16 v[98:101], v[6:9], v[50:53], v[98:101]
	v_permlane16_swap_b32_e32 v158, v159
	v_add_f32_e32 v156, v156, v157
	v_add_f32_e32 v158, v158, v159
	s_nop 1
	v_permlane32_swap_b32_e32 v156, v158
	v_ashrrev_i32_e32 v164, 31, v156
	v_ashrrev_i32_e32 v165, 31, v158
	v_or_b32_e32 v164, 0x80000000, v164
	v_mfma_f32_16x16x32_bf16 v[102:105], v[6:9], v[54:57], v[102:105]
	v_or_b32_e32 v165, 0x80000000, v165
	v_xor_b32_e32 v164, v156, v164
	v_xor_b32_e32 v165, v158, v165
	v_and_b32_e32 v164, 0xffffff00, v164
	v_and_b32_e32 v165, 0xffffff00, v165
	v_cmp_ge_i32_e32 vcc, s5, v242
	s_nop 1
	v_cndmask_b32_e32 v217, 0, v164, vcc
	v_cmp_ge_i32_e32 vcc, s67, v242
	s_nop 1
	v_cndmask_b32_e32 v165, 0, v165, vcc
	global_store_dword v168, v165, s[8:9] offset:1280
	s_waitcnt lgkmcnt(0)
	v_mfma_f32_16x16x32_bf16 v[106:109], v[10:13], v[58:61], 0
	s_sub_i32 s5, s57, 384
	s_add_i32 s67, s5, 1
	v_med3_f32 v90, v90, 0, v240
	v_med3_f32 v91, v91, 0, v240
	v_med3_f32 v92, v92, 0, v240
	v_med3_f32 v93, v93, 0, v240
	v_mul_f32_e32 v160, v2, v90
	v_mul_f32_e32 v161, v3, v91
	v_mfma_f32_16x16x32_bf16 v[110:113], v[10:13], v[62:65], 0
	v_mul_f32_e32 v162, v4, v92
	v_mul_f32_e32 v163, v5, v93
	v_add_f32_e32 v156, v160, v161
	v_add_f32_e32 v156, v162, v156
	v_add_f32_e32 v156, v163, v156
	v_med3_f32 v94, v94, 0, v240
	v_med3_f32 v95, v95, 0, v240
	v_med3_f32 v96, v96, 0, v240
	v_mfma_f32_16x16x32_bf16 v[114:117], v[10:13], v[66:69], 0
	v_med3_f32 v97, v97, 0, v240
	v_mul_f32_e32 v160, v2, v94
	v_mul_f32_e32 v161, v3, v95
	v_mul_f32_e32 v162, v4, v96
	v_mul_f32_e32 v163, v5, v97
	v_add_f32_e32 v157, v160, v161
	v_add_f32_e32 v157, v162, v157
	v_add_f32_e32 v157, v163, v157
	v_mfma_f32_16x16x32_bf16 v[118:121], v[10:13], v[70:73], 0
	v_med3_f32 v98, v98, 0, v240
	v_med3_f32 v99, v99, 0, v240
	v_med3_f32 v100, v100, 0, v240
	v_med3_f32 v101, v101, 0, v240
	v_mul_f32_e32 v160, v2, v98
	v_mul_f32_e32 v161, v3, v99
	v_mul_f32_e32 v162, v4, v100
	v_mul_f32_e32 v163, v5, v101
	v_mfma_f32_16x16x32_bf16 v[106:109], v[6:9], v[74:77], v[106:109]
	v_add_f32_e32 v158, v160, v161
	v_add_f32_e32 v158, v162, v158
	v_add_f32_e32 v158, v163, v158
	v_med3_f32 v102, v102, 0, v240
	v_med3_f32 v103, v103, 0, v240
	v_med3_f32 v104, v104, 0, v240
	v_med3_f32 v105, v105, 0, v240
	v_mul_f32_e32 v160, v2, v102
	v_mfma_f32_16x16x32_bf16 v[110:113], v[6:9], v[78:81], v[110:113]
	v_mul_f32_e32 v161, v3, v103
	v_mul_f32_e32 v162, v4, v104
	v_mul_f32_e32 v163, v5, v105
	v_add_f32_e32 v159, v160, v161
	v_add_f32_e32 v159, v162, v159
	v_add_f32_e32 v159, v163, v159
	s_nop 1
	v_permlane16_swap_b32_e32 v156, v157
	v_mfma_f32_16x16x32_bf16 v[114:117], v[6:9], v[82:85], v[114:117]
	v_permlane16_swap_b32_e32 v158, v159
	v_add_f32_e32 v156, v156, v157
	v_add_f32_e32 v158, v158, v159
	s_nop 1
	v_permlane32_swap_b32_e32 v156, v158
	v_ashrrev_i32_e32 v164, 31, v156
	v_ashrrev_i32_e32 v165, 31, v158
	v_or_b32_e32 v164, 0x80000000, v164
	v_mfma_f32_16x16x32_bf16 v[118:121], v[6:9], v[86:89], v[118:121]
	v_or_b32_e32 v165, 0x80000000, v165
	v_xor_b32_e32 v164, v156, v164
	v_xor_b32_e32 v165, v158, v165
	v_and_b32_e32 v164, 0xffffff00, v164
	v_and_b32_e32 v165, 0xffffff00, v165
	v_cmp_ge_i32_e32 vcc, s5, v242
	s_nop 1
	v_cndmask_b32_e32 v218, 0, v164, vcc
	v_cmp_ge_i32_e32 vcc, s67, v242
	s_nop 1
	v_cndmask_b32_e32 v165, 0, v165, vcc
	global_store_dword v168, v165, s[8:9] offset:1536
.Lsc_h2:
	s_cmp_le_u32 s4, 2
	s_cbranch_scc1 .Lsc_drain2
	s_cmp_gt_u32 s4, 4
	s_cbranch_scc0 .Lsc_ni2
	v_lshl_add_u64 v[170:171], s[48:49], 0, v[0:1]
	s_add_i32 m0, s1, 0x0
	s_nop 0
	global_load_lds_dwordx4 v[170:171], off
	v_lshl_add_u64 v[170:171], s[48:49], 0, v[18:19]
	s_add_i32 m0, s1, 0x2000
	s_nop 0
	global_load_lds_dwordx4 v[170:171], off
	v_lshl_add_u64 v[170:171], s[48:49], 0, v[20:21]
	s_add_i32 m0, s1, 0x4000
	s_nop 0
	global_load_lds_dwordx4 v[170:171], off
	v_lshl_add_u64 v[170:171], s[48:49], 0, v[22:23]
	s_add_i32 m0, s1, 0x6000
	s_nop 0
	global_load_lds_dwordx4 v[170:171], off
	s_add_u32 s48, s48, 0x8000
	s_addc_u32 s49, s49, 0
	s_waitcnt vmcnt(8)
	s_branch .Lsc_b2
.Lsc_ni2:
	s_cmp_gt_u32 s4, 3
	s_cbranch_scc0 .Lsc_w02
	s_waitcnt vmcnt(4)
	s_branch .Lsc_b2

.Lsc_b2:
	s_barrier
	ds_read_b128 v[26:29], v166
	ds_read_b128 v[30:33], v166 offset:2048
	ds_read_b128 v[34:37], v166 offset:4096
	ds_read_b128 v[38:41], v166 offset:6144
	ds_read_b128 v[42:45], v167
	ds_read_b128 v[46:49], v167 offset:2048
	ds_read_b128 v[50:53], v167 offset:4096
	ds_read_b128 v[54:57], v167 offset:6144
	ds_read_b128 v[58:61], v166 offset:8192
	ds_read_b128 v[62:65], v166 offset:10240
	ds_read_b128 v[66:69], v166 offset:12288
	ds_read_b128 v[70:73], v166 offset:14336
	ds_read_b128 v[74:77], v167 offset:8192
	ds_read_b128 v[78:81], v167 offset:10240
	ds_read_b128 v[82:85], v167 offset:12288
	ds_read_b128 v[86:89], v167 offset:14336
	s_sub_i32 s5, s57, 448
	s_add_i32 s67, s5, 1
	v_med3_f32 v106, v106, 0, v240
	v_med3_f32 v107, v107, 0, v240
	v_med3_f32 v108, v108, 0, v240
	v_med3_f32 v109, v109, 0, v240
	v_mul_f32_e32 v160, v2, v106
	v_mul_f32_e32 v161, v3, v107
	v_mul_f32_e32 v162, v4, v108
	v_mul_f32_e32 v163, v5, v109
	v_add_f32_e32 v156, v160, v161
	v_add_f32_e32 v156, v162, v156
	v_add_f32_e32 v156, v163, v156
	v_med3_f32 v110, v110, 0, v240
	v_med3_f32 v111, v111, 0, v240
	v_med3_f32 v112, v112, 0, v240
	v_med3_f32 v113, v113, 0, v240
	v_mul_f32_e32 v160, v2, v110
	v_mul_f32_e32 v161, v3, v111
	v_mul_f32_e32 v162, v4, v112
	v_mul_f32_e32 v163, v5, v113
	v_add_f32_e32 v157, v160, v161
	v_add_f32_e32 v157, v162, v157
	v_add_f32_e32 v157, v163, v157
	v_med3_f32 v114, v114, 0, v240
	v_med3_f32 v115, v115, 0, v240
	v_med3_f32 v116, v116, 0, v240
	v_med3_f32 v117, v117, 0, v240
	v_mul_f32_e32 v160, v2, v114
	v_mul_f32_e32 v161, v3, v115
	v_mul_f32_e32 v162, v4, v116
	v_mul_f32_e32 v163, v5, v117
	v_add_f32_e32 v158, v160, v161
	v_add_f32_e32 v158, v162, v158
	s_waitcnt lgkmcnt(8)
	v_mfma_f32_16x16x32_bf16 v[90:93], v[10:13], v[26:29], 0
	v_add_f32_e32 v158, v163, v158
	v_med3_f32 v118, v118, 0, v240
	v_med3_f32 v119, v119, 0, v240
	v_med3_f32 v120, v120, 0, v240
	v_mfma_f32_16x16x32_bf16 v[94:97], v[10:13], v[30:33], 0
	v_med3_f32 v121, v121, 0, v240
	v_mul_f32_e32 v160, v2, v118
	v_mul_f32_e32 v161, v3, v119
	v_mul_f32_e32 v162, v4, v120
	v_mfma_f32_16x16x32_bf16 v[98:101], v[10:13], v[34:37], 0
	v_mul_f32_e32 v163, v5, v121
	v_add_f32_e32 v159, v160, v161
	v_add_f32_e32 v159, v162, v159
	v_add_f32_e32 v159, v163, v159
	v_mfma_f32_16x16x32_bf16 v[102:105], v[10:13], v[38:41], 0
	s_nop 1
	v_permlane16_swap_b32_e32 v156, v157
	v_permlane16_swap_b32_e32 v158, v159
	v_add_f32_e32 v156, v156, v157
	v_mfma_f32_16x16x32_bf16 v[90:93], v[6:9], v[42:45], v[90:93]
	v_add_f32_e32 v158, v158, v159
	s_nop 1
	v_permlane32_swap_b32_e32 v156, v158
	v_ashrrev_i32_e32 v164, 31, v156
	v_mfma_f32_16x16x32_bf16 v[94:97], v[6:9], v[46:49], v[94:97]
	v_ashrrev_i32_e32 v165, 31, v158
	v_or_b32_e32 v164, 0x80000000, v164
	v_or_b32_e32 v165, 0x80000000, v165
	v_xor_b32_e32 v164, v156, v164
	v_mfma_f32_16x16x32_bf16 v[98:101], v[6:9], v[50:53], v[98:101]
	v_xor_b32_e32 v165, v158, v165
	v_and_b32_e32 v164, 0xffffff00, v164
	v_and_b32_e32 v165, 0xffffff00, v165
	v_cmp_ge_i32_e32 vcc, s5, v242
	v_mfma_f32_16x16x32_bf16 v[102:105], v[6:9], v[54:57], v[102:105]
	s_nop 1
	v_cndmask_b32_e32 v219, 0, v164, vcc
	v_cmp_ge_i32_e32 vcc, s67, v242
	s_nop 1
	v_cndmask_b32_e32 v165, 0, v165, vcc
	global_store_dword v168, v165, s[8:9] offset:1792
	ds_read_b128 v[26:29], v166 offset:16384
	ds_read_b128 v[30:33], v166 offset:18432
	ds_read_b128 v[34:37], v166 offset:20480
	ds_read_b128 v[38:41], v166 offset:22528
	ds_read_b128 v[42:45], v167 offset:16384
	ds_read_b128 v[46:49], v167 offset:18432
	ds_read_b128 v[50:53], v167 offset:20480
	ds_read_b128 v[54:57], v167 offset:22528
	s_waitcnt lgkmcnt(8)
	v_mfma_f32_16x16x32_bf16 v[106:109], v[10:13], v[58:61], 0
	s_sub_i32 s5, s57, 512
	s_add_i32 s67, s5, 1
	v_med3_f32 v90, v90, 0, v240
	v_med3_f32 v91, v91, 0, v240
	v_med3_f32 v92, v92, 0, v240
	v_med3_f32 v93, v93, 0, v240
	v_mul_f32_e32 v160, v2, v90
	v_mul_f32_e32 v161, v3, v91
	v_mfma_f32_16x16x32_bf16 v[110:113], v[10:13], v[62:65], 0
	v_mul_f32_e32 v162, v4, v92
	v_mul_f32_e32 v163, v5, v93
	v_add_f32_e32 v156, v160, v161
	v_add_f32_e32 v156, v162, v156
	v_add_f32_e32 v156, v163, v156
	v_med3_f32 v94, v94, 0, v240
	v_med3_f32 v95, v95, 0, v240
	v_med3_f32 v96, v96, 0, v240
	v_mfma_f32_16x16x32_bf16 v[114:117], v[10:13], v[66:69], 0
	v_med3_f32 v97, v97, 0, v240
	v_mul_f32_e32 v160, v2, v94
	v_mul_f32_e32 v161, v3, v95
	v_mul_f32_e32 v162, v4, v96
	v_mul_f32_e32 v163, v5, v97
	v_add_f32_e32 v157, v160, v161
	v_add_f32_e32 v157, v162, v157
	v_add_f32_e32 v157, v163, v157
	v_mfma_f32_16x16x32_bf16 v[118:121], v[10:13], v[70:73], 0
	v_med3_f32 v98, v98, 0, v240
	v_med3_f32 v99, v99, 0, v240
	v_med3_f32 v100, v100, 0, v240
	v_med3_f32 v101, v101, 0, v240
	v_mul_f32_e32 v160, v2, v98
	v_mul_f32_e32 v161, v3, v99
	v_mul_f32_e32 v162, v4, v100
	v_mul_f32_e32 v163, v5, v101
	v_mfma_f32_16x16x32_bf16 v[106:109], v[6:9], v[74:77], v[106:109]
	v_add_f32_e32 v158, v160, v161
	v_add_f32_e32 v158, v162, v158
	v_add_f32_e32 v158, v163, v158
	v_med3_f32 v102, v102, 0, v240
	v_med3_f32 v103, v103, 0, v240
	v_med3_f32 v104, v104, 0, v240
	v_med3_f32 v105, v105, 0, v240
	v_mul_f32_e32 v160, v2, v102
	v_mfma_f32_16x16x32_bf16 v[110:113], v[6:9], v[78:81], v[110:113]
	v_mul_f32_e32 v161, v3, v103
	v_mul_f32_e32 v162, v4, v104
	v_mul_f32_e32 v163, v5, v105
	v_add_f32_e32 v159, v160, v161
	v_add_f32_e32 v159, v162, v159
	v_add_f32_e32 v159, v163, v159
	s_nop 1
	v_permlane16_swap_b32_e32 v156, v157
	v_mfma_f32_16x16x32_bf16 v[114:117], v[6:9], v[82:85], v[114:117]
	v_permlane16_swap_b32_e32 v158, v159
	v_add_f32_e32 v156, v156, v157
	v_add_f32_e32 v158, v158, v159
	s_nop 1
	v_permlane32_swap_b32_e32 v156, v158
	v_ashrrev_i32_e32 v164, 31, v156
	v_ashrrev_i32_e32 v165, 31, v158
	v_or_b32_e32 v164, 0x80000000, v164
	v_mfma_f32_16x16x32_bf16 v[118:121], v[6:9], v[86:89], v[118:121]
	v_or_b32_e32 v165, 0x80000000, v165
	v_xor_b32_e32 v164, v156, v164
	v_xor_b32_e32 v165, v158, v165
	v_and_b32_e32 v164, 0xffffff00, v164
	v_and_b32_e32 v165, 0xffffff00, v165
	v_cmp_ge_i32_e32 vcc, s5, v242
	s_nop 1
	v_cndmask_b32_e32 v220, 0, v164, vcc
	v_cmp_ge_i32_e32 vcc, s67, v242
	s_nop 1
	v_cndmask_b32_e32 v165, 0, v165, vcc
	global_store_dword v168, v165, s[8:9] offset:2048
	ds_read_b128 v[58:61], v166 offset:24576
	ds_read_b128 v[62:65], v166 offset:26624
	ds_read_b128 v[66:69], v166 offset:28672
	ds_read_b128 v[70:73], v166 offset:30720
	ds_read_b128 v[74:77], v167 offset:24576
	ds_read_b128 v[78:81], v167 offset:26624
	ds_read_b128 v[82:85], v167 offset:28672
	ds_read_b128 v[86:89], v167 offset:30720
	s_waitcnt lgkmcnt(8)
	v_mfma_f32_16x16x32_bf16 v[90:93], v[10:13], v[26:29], 0
	s_sub_i32 s5, s57, 576
	s_add_i32 s67, s5, 1
	v_med3_f32 v106, v106, 0, v240
	v_med3_f32 v107, v107, 0, v240
	v_med3_f32 v108, v108, 0, v240
	v_med3_f32 v109, v109, 0, v240
	v_mul_f32_e32 v160, v2, v106
	v_mul_f32_e32 v161, v3, v107
	v_mfma_f32_16x16x32_bf16 v[94:97], v[10:13], v[30:33], 0
	v_mul_f32_e32 v162, v4, v108
	v_mul_f32_e32 v163, v5, v109
	v_add_f32_e32 v156, v160, v161
	v_add_f32_e32 v156, v162, v156
	v_add_f32_e32 v156, v163, v156
	v_med3_f32 v110, v110, 0, v240
	v_med3_f32 v111, v111, 0, v240
	v_med3_f32 v112, v112, 0, v240
	v_mfma_f32_16x16x32_bf16 v[98:101], v[10:13], v[34:37], 0
	v_med3_f32 v113, v113, 0, v240
	v_mul_f32_e32 v160, v2, v110
	v_mul_f32_e32 v161, v3, v111
	v_mul_f32_e32 v162, v4, v112
	v_mul_f32_e32 v163, v5, v113
	v_add_f32_e32 v157, v160, v161
	v_add_f32_e32 v157, v162, v157
	v_add_f32_e32 v157, v163, v157
	v_mfma_f32_16x16x32_bf16 v[102:105], v[10:13], v[38:41], 0
	v_med3_f32 v114, v114, 0, v240
	v_med3_f32 v115, v115, 0, v240
	v_med3_f32 v116, v116, 0, v240
	v_med3_f32 v117, v117, 0, v240
	v_mul_f32_e32 v160, v2, v114
	v_mul_f32_e32 v161, v3, v115
	v_mul_f32_e32 v162, v4, v116
	v_mul_f32_e32 v163, v5, v117
	v_mfma_f32_16x16x32_bf16 v[90:93], v[6:9], v[42:45], v[90:93]
	v_add_f32_e32 v158, v160, v161
	v_add_f32_e32 v158, v162, v158
	v_add_f32_e32 v158, v163, v158
	v_med3_f32 v118, v118, 0, v240
	v_med3_f32 v119, v119, 0, v240
	v_med3_f32 v120, v120, 0, v240
	v_med3_f32 v121, v121, 0, v240
	v_mul_f32_e32 v160, v2, v118
	v_mfma_f32_16x16x32_bf16 v[94:97], v[6:9], v[46:49], v[94:97]
	v_mul_f32_e32 v161, v3, v119
	v_mul_f32_e32 v162, v4, v120
	v_mul_f32_e32 v163, v5, v121
	v_add_f32_e32 v159, v160, v161
	v_add_f32_e32 v159, v162, v159
	v_add_f32_e32 v159, v163, v159
	s_nop 1
	v_permlane16_swap_b32_e32 v156, v157
	v_mfma_f32_16x16x32_bf16 v[98:101], v[6:9], v[50:53], v[98:101]
	v_permlane16_swap_b32_e32 v158, v159
	v_add_f32_e32 v156, v156, v157
	v_add_f32_e32 v158, v158, v159
	s_nop 1
	v_permlane32_swap_b32_e32 v156, v158
	v_ashrrev_i32_e32 v164, 31, v156
	v_ashrrev_i32_e32 v165, 31, v158
	v_or_b32_e32 v164, 0x80000000, v164
	v_mfma_f32_16x16x32_bf16 v[102:105], v[6:9], v[54:57], v[102:105]
	v_or_b32_e32 v165, 0x80000000, v165
	v_xor_b32_e32 v164, v156, v164
	v_xor_b32_e32 v165, v158, v165
	v_and_b32_e32 v164, 0xffffff00, v164
	v_and_b32_e32 v165, 0xffffff00, v165
	v_cmp_ge_i32_e32 vcc, s5, v242
	s_nop 1
	v_cndmask_b32_e32 v221, 0, v164, vcc
	v_cmp_ge_i32_e32 vcc, s67, v242
	s_nop 1
	v_cndmask_b32_e32 v165, 0, v165, vcc
	global_store_dword v168, v165, s[8:9] offset:2304
	s_waitcnt lgkmcnt(0)
	v_mfma_f32_16x16x32_bf16 v[106:109], v[10:13], v[58:61], 0
	s_sub_i32 s5, s57, 640
	s_add_i32 s67, s5, 1
	v_med3_f32 v90, v90, 0, v240
	v_med3_f32 v91, v91, 0, v240
	v_med3_f32 v92, v92, 0, v240
	v_med3_f32 v93, v93, 0, v240
	v_mul_f32_e32 v160, v2, v90
	v_mul_f32_e32 v161, v3, v91
	v_mfma_f32_16x16x32_bf16 v[110:113], v[10:13], v[62:65], 0
	v_mul_f32_e32 v162, v4, v92
	v_mul_f32_e32 v163, v5, v93
	v_add_f32_e32 v156, v160, v161
	v_add_f32_e32 v156, v162, v156
	v_add_f32_e32 v156, v163, v156
	v_med3_f32 v94, v94, 0, v240
	v_med3_f32 v95, v95, 0, v240
	v_med3_f32 v96, v96, 0, v240
	v_mfma_f32_16x16x32_bf16 v[114:117], v[10:13], v[66:69], 0
	v_med3_f32 v97, v97, 0, v240
	v_mul_f32_e32 v160, v2, v94
	v_mul_f32_e32 v161, v3, v95
	v_mul_f32_e32 v162, v4, v96
	v_mul_f32_e32 v163, v5, v97
	v_add_f32_e32 v157, v160, v161
	v_add_f32_e32 v157, v162, v157
	v_add_f32_e32 v157, v163, v157
	v_mfma_f32_16x16x32_bf16 v[118:121], v[10:13], v[70:73], 0
	v_med3_f32 v98, v98, 0, v240
	v_med3_f32 v99, v99, 0, v240
	v_med3_f32 v100, v100, 0, v240
	v_med3_f32 v101, v101, 0, v240
	v_mul_f32_e32 v160, v2, v98
	v_mul_f32_e32 v161, v3, v99
	v_mul_f32_e32 v162, v4, v100
	v_mul_f32_e32 v163, v5, v101
	v_mfma_f32_16x16x32_bf16 v[106:109], v[6:9], v[74:77], v[106:109]
	v_add_f32_e32 v158, v160, v161
	v_add_f32_e32 v158, v162, v158
	v_add_f32_e32 v158, v163, v158
	v_med3_f32 v102, v102, 0, v240
	v_med3_f32 v103, v103, 0, v240
	v_med3_f32 v104, v104, 0, v240
	v_med3_f32 v105, v105, 0, v240
	v_mul_f32_e32 v160, v2, v102
	v_mfma_f32_16x16x32_bf16 v[110:113], v[6:9], v[78:81], v[110:113]
	v_mul_f32_e32 v161, v3, v103
	v_mul_f32_e32 v162, v4, v104
	v_mul_f32_e32 v163, v5, v105
	v_add_f32_e32 v159, v160, v161
	v_add_f32_e32 v159, v162, v159
	v_add_f32_e32 v159, v163, v159
	s_nop 1
	v_permlane16_swap_b32_e32 v156, v157
	v_mfma_f32_16x16x32_bf16 v[114:117], v[6:9], v[82:85], v[114:117]
	v_permlane16_swap_b32_e32 v158, v159
	v_add_f32_e32 v156, v156, v157
	v_add_f32_e32 v158, v158, v159
	s_nop 1
	v_permlane32_swap_b32_e32 v156, v158
	v_ashrrev_i32_e32 v164, 31, v156
	v_ashrrev_i32_e32 v165, 31, v158
	v_or_b32_e32 v164, 0x80000000, v164
	v_mfma_f32_16x16x32_bf16 v[118:121], v[6:9], v[86:89], v[118:121]
	v_or_b32_e32 v165, 0x80000000, v165
	v_xor_b32_e32 v164, v156, v164
	v_xor_b32_e32 v165, v158, v165
	v_and_b32_e32 v164, 0xffffff00, v164
	v_and_b32_e32 v165, 0xffffff00, v165
	v_cmp_ge_i32_e32 vcc, s5, v242
	s_nop 1
	v_cndmask_b32_e32 v222, 0, v164, vcc
	v_cmp_ge_i32_e32 vcc, s67, v242
	s_nop 1
	v_cndmask_b32_e32 v165, 0, v165, vcc
	global_store_dword v168, v165, s[8:9] offset:2560
.Lsc_h3:
	s_cmp_le_u32 s4, 3
	s_cbranch_scc1 .Lsc_drain3
	s_cmp_gt_u32 s4, 5
	s_cbranch_scc0 .Lsc_ni3
	v_lshl_add_u64 v[170:171], s[48:49], 0, v[0:1]
	s_add_i32 m0, s1, 0x8000
	s_nop 0
	global_load_lds_dwordx4 v[170:171], off
	v_lshl_add_u64 v[170:171], s[48:49], 0, v[18:19]
	s_add_i32 m0, s1, 0xa000
	s_nop 0
	global_load_lds_dwordx4 v[170:171], off
	v_lshl_add_u64 v[170:171], s[48:49], 0, v[20:21]
	s_add_i32 m0, s1, 0xc000
	s_nop 0
	global_load_lds_dwordx4 v[170:171], off
	v_lshl_add_u64 v[170:171], s[48:49], 0, v[22:23]
	s_add_i32 m0, s1, 0xe000
	s_nop 0
	global_load_lds_dwordx4 v[170:171], off
	s_add_u32 s48, s48, 0x8000
	s_addc_u32 s49, s49, 0
	s_waitcnt vmcnt(8)
	s_branch .Lsc_b3
.Lsc_ni3:
	s_cmp_gt_u32 s4, 4
	s_cbranch_scc0 .Lsc_w03
	s_waitcnt vmcnt(4)
	s_branch .Lsc_b3

.Lsc_b3:
	s_barrier
	ds_read_b128 v[26:29], v166 offset:32768
	ds_read_b128 v[30:33], v166 offset:34816
	ds_read_b128 v[34:37], v166 offset:36864
	ds_read_b128 v[38:41], v166 offset:38912
	ds_read_b128 v[42:45], v167 offset:32768
	ds_read_b128 v[46:49], v167 offset:34816
	ds_read_b128 v[50:53], v167 offset:36864
	ds_read_b128 v[54:57], v167 offset:38912
	ds_read_b128 v[58:61], v166 offset:40960
	ds_read_b128 v[62:65], v166 offset:43008
	ds_read_b128 v[66:69], v166 offset:45056
	ds_read_b128 v[70:73], v166 offset:47104
	ds_read_b128 v[74:77], v167 offset:40960
	ds_read_b128 v[78:81], v167 offset:43008
	ds_read_b128 v[82:85], v167 offset:45056
	ds_read_b128 v[86:89], v167 offset:47104
	s_sub_i32 s5, s57, 704
	s_add_i32 s67, s5, 1
	v_med3_f32 v106, v106, 0, v240
	v_med3_f32 v107, v107, 0, v240
	v_med3_f32 v108, v108, 0, v240
	v_med3_f32 v109, v109, 0, v240
	v_mul_f32_e32 v160, v2, v106
	v_mul_f32_e32 v161, v3, v107
	v_mul_f32_e32 v162, v4, v108
	v_mul_f32_e32 v163, v5, v109
	v_add_f32_e32 v156, v160, v161
	v_add_f32_e32 v156, v162, v156
	v_add_f32_e32 v156, v163, v156
	v_med3_f32 v110, v110, 0, v240
	v_med3_f32 v111, v111, 0, v240
	v_med3_f32 v112, v112, 0, v240
	v_med3_f32 v113, v113, 0, v240
	v_mul_f32_e32 v160, v2, v110
	v_mul_f32_e32 v161, v3, v111
	v_mul_f32_e32 v162, v4, v112
	v_mul_f32_e32 v163, v5, v113
	v_add_f32_e32 v157, v160, v161
	v_add_f32_e32 v157, v162, v157
	v_add_f32_e32 v157, v163, v157
	v_med3_f32 v114, v114, 0, v240
	v_med3_f32 v115, v115, 0, v240
	v_med3_f32 v116, v116, 0, v240
	v_med3_f32 v117, v117, 0, v240
	v_mul_f32_e32 v160, v2, v114
	v_mul_f32_e32 v161, v3, v115
	v_mul_f32_e32 v162, v4, v116
	v_mul_f32_e32 v163, v5, v117
	v_add_f32_e32 v158, v160, v161
	v_add_f32_e32 v158, v162, v158
	s_waitcnt lgkmcnt(8)
	v_mfma_f32_16x16x32_bf16 v[90:93], v[10:13], v[26:29], 0
	v_add_f32_e32 v158, v163, v158
	v_med3_f32 v118, v118, 0, v240
	v_med3_f32 v119, v119, 0, v240
	v_med3_f32 v120, v120, 0, v240
	v_mfma_f32_16x16x32_bf16 v[94:97], v[10:13], v[30:33], 0
	v_med3_f32 v121, v121, 0, v240
	v_mul_f32_e32 v160, v2, v118
	v_mul_f32_e32 v161, v3, v119
	v_mul_f32_e32 v162, v4, v120
	v_mfma_f32_16x16x32_bf16 v[98:101], v[10:13], v[34:37], 0
	v_mul_f32_e32 v163, v5, v121
	v_add_f32_e32 v159, v160, v161
	v_add_f32_e32 v159, v162, v159
	v_add_f32_e32 v159, v163, v159
	v_mfma_f32_16x16x32_bf16 v[102:105], v[10:13], v[38:41], 0
	s_nop 1
	v_permlane16_swap_b32_e32 v156, v157
	v_permlane16_swap_b32_e32 v158, v159
	v_add_f32_e32 v156, v156, v157
	v_mfma_f32_16x16x32_bf16 v[90:93], v[6:9], v[42:45], v[90:93]
	v_add_f32_e32 v158, v158, v159
	s_nop 1
	v_permlane32_swap_b32_e32 v156, v158
	v_ashrrev_i32_e32 v164, 31, v156
	v_mfma_f32_16x16x32_bf16 v[94:97], v[6:9], v[46:49], v[94:97]
	v_ashrrev_i32_e32 v165, 31, v158
	v_or_b32_e32 v164, 0x80000000, v164
	v_or_b32_e32 v165, 0x80000000, v165
	v_xor_b32_e32 v164, v156, v164
	v_mfma_f32_16x16x32_bf16 v[98:101], v[6:9], v[50:53], v[98:101]
	v_xor_b32_e32 v165, v158, v165
	v_and_b32_e32 v164, 0xffffff00, v164
	v_and_b32_e32 v165, 0xffffff00, v165
	v_cmp_ge_i32_e32 vcc, s5, v242
	v_mfma_f32_16x16x32_bf16 v[102:105], v[6:9], v[54:57], v[102:105]
	s_nop 1
	v_cndmask_b32_e32 v223, 0, v164, vcc
	v_cmp_ge_i32_e32 vcc, s67, v242
	s_nop 1
	v_cndmask_b32_e32 v165, 0, v165, vcc
	global_store_dword v168, v165, s[8:9] offset:2816
	ds_read_b128 v[26:29], v166 offset:49152
	ds_read_b128 v[30:33], v166 offset:51200
	ds_read_b128 v[34:37], v166 offset:53248
	ds_read_b128 v[38:41], v166 offset:55296
	ds_read_b128 v[42:45], v167 offset:49152
	ds_read_b128 v[46:49], v167 offset:51200
	ds_read_b128 v[50:53], v167 offset:53248
	ds_read_b128 v[54:57], v167 offset:55296
	s_waitcnt lgkmcnt(8)
	v_mfma_f32_16x16x32_bf16 v[106:109], v[10:13], v[58:61], 0
	s_sub_i32 s5, s57, 768
	s_add_i32 s67, s5, 1
	v_med3_f32 v90, v90, 0, v240
	v_med3_f32 v91, v91, 0, v240
	v_med3_f32 v92, v92, 0, v240
	v_med3_f32 v93, v93, 0, v240
	v_mul_f32_e32 v160, v2, v90
	v_mul_f32_e32 v161, v3, v91
	v_mfma_f32_16x16x32_bf16 v[110:113], v[10:13], v[62:65], 0
	v_mul_f32_e32 v162, v4, v92
	v_mul_f32_e32 v163, v5, v93
	v_add_f32_e32 v156, v160, v161
	v_add_f32_e32 v156, v162, v156
	v_add_f32_e32 v156, v163, v156
	v_med3_f32 v94, v94, 0, v240
	v_med3_f32 v95, v95, 0, v240
	v_med3_f32 v96, v96, 0, v240
	v_mfma_f32_16x16x32_bf16 v[114:117], v[10:13], v[66:69], 0
	v_med3_f32 v97, v97, 0, v240
	v_mul_f32_e32 v160, v2, v94
	v_mul_f32_e32 v161, v3, v95
	v_mul_f32_e32 v162, v4, v96
	v_mul_f32_e32 v163, v5, v97
	v_add_f32_e32 v157, v160, v161
	v_add_f32_e32 v157, v162, v157
	v_add_f32_e32 v157, v163, v157
	v_mfma_f32_16x16x32_bf16 v[118:121], v[10:13], v[70:73], 0
	v_med3_f32 v98, v98, 0, v240
	v_med3_f32 v99, v99, 0, v240
	v_med3_f32 v100, v100, 0, v240
	v_med3_f32 v101, v101, 0, v240
	v_mul_f32_e32 v160, v2, v98
	v_mul_f32_e32 v161, v3, v99
	v_mul_f32_e32 v162, v4, v100
	v_mul_f32_e32 v163, v5, v101
	v_mfma_f32_16x16x32_bf16 v[106:109], v[6:9], v[74:77], v[106:109]
	v_add_f32_e32 v158, v160, v161
	v_add_f32_e32 v158, v162, v158
	v_add_f32_e32 v158, v163, v158
	v_med3_f32 v102, v102, 0, v240
	v_med3_f32 v103, v103, 0, v240
	v_med3_f32 v104, v104, 0, v240
	v_med3_f32 v105, v105, 0, v240
	v_mul_f32_e32 v160, v2, v102
	v_mfma_f32_16x16x32_bf16 v[110:113], v[6:9], v[78:81], v[110:113]
	v_mul_f32_e32 v161, v3, v103
	v_mul_f32_e32 v162, v4, v104
	v_mul_f32_e32 v163, v5, v105
	v_add_f32_e32 v159, v160, v161
	v_add_f32_e32 v159, v162, v159
	v_add_f32_e32 v159, v163, v159
	s_nop 1
	v_permlane16_swap_b32_e32 v156, v157
	v_mfma_f32_16x16x32_bf16 v[114:117], v[6:9], v[82:85], v[114:117]
	v_permlane16_swap_b32_e32 v158, v159
	v_add_f32_e32 v156, v156, v157
	v_add_f32_e32 v158, v158, v159
	s_nop 1
	v_permlane32_swap_b32_e32 v156, v158
	v_ashrrev_i32_e32 v164, 31, v156
	v_ashrrev_i32_e32 v165, 31, v158
	v_or_b32_e32 v164, 0x80000000, v164
	v_mfma_f32_16x16x32_bf16 v[118:121], v[6:9], v[86:89], v[118:121]
	v_or_b32_e32 v165, 0x80000000, v165
	v_xor_b32_e32 v164, v156, v164
	v_xor_b32_e32 v165, v158, v165
	v_and_b32_e32 v164, 0xffffff00, v164
	v_and_b32_e32 v165, 0xffffff00, v165
	v_cmp_ge_i32_e32 vcc, s5, v242
	s_nop 1
	v_cndmask_b32_e32 v224, 0, v164, vcc
	v_cmp_ge_i32_e32 vcc, s67, v242
	s_nop 1
	v_cndmask_b32_e32 v165, 0, v165, vcc
	global_store_dword v168, v165, s[8:9] offset:3072
	ds_read_b128 v[58:61], v166 offset:57344
	ds_read_b128 v[62:65], v166 offset:59392
	ds_read_b128 v[66:69], v166 offset:61440
	ds_read_b128 v[70:73], v166 offset:63488
	ds_read_b128 v[74:77], v167 offset:57344
	ds_read_b128 v[78:81], v167 offset:59392
	ds_read_b128 v[82:85], v167 offset:61440
	ds_read_b128 v[86:89], v167 offset:63488
	s_waitcnt lgkmcnt(8)
	v_mfma_f32_16x16x32_bf16 v[90:93], v[10:13], v[26:29], 0
	s_sub_i32 s5, s57, 832
	s_add_i32 s67, s5, 1
	v_med3_f32 v106, v106, 0, v240
	v_med3_f32 v107, v107, 0, v240
	v_med3_f32 v108, v108, 0, v240
	v_med3_f32 v109, v109, 0, v240
	v_mul_f32_e32 v160, v2, v106
	v_mul_f32_e32 v161, v3, v107
	v_mfma_f32_16x16x32_bf16 v[94:97], v[10:13], v[30:33], 0
	v_mul_f32_e32 v162, v4, v108
	v_mul_f32_e32 v163, v5, v109
	v_add_f32_e32 v156, v160, v161
	v_add_f32_e32 v156, v162, v156
	v_add_f32_e32 v156, v163, v156
	v_med3_f32 v110, v110, 0, v240
	v_med3_f32 v111, v111, 0, v240
	v_med3_f32 v112, v112, 0, v240
	v_mfma_f32_16x16x32_bf16 v[98:101], v[10:13], v[34:37], 0
	v_med3_f32 v113, v113, 0, v240
	v_mul_f32_e32 v160, v2, v110
	v_mul_f32_e32 v161, v3, v111
	v_mul_f32_e32 v162, v4, v112
	v_mul_f32_e32 v163, v5, v113
	v_add_f32_e32 v157, v160, v161
	v_add_f32_e32 v157, v162, v157
	v_add_f32_e32 v157, v163, v157
	v_mfma_f32_16x16x32_bf16 v[102:105], v[10:13], v[38:41], 0
	v_med3_f32 v114, v114, 0, v240
	v_med3_f32 v115, v115, 0, v240
	v_med3_f32 v116, v116, 0, v240
	v_med3_f32 v117, v117, 0, v240
	v_mul_f32_e32 v160, v2, v114
	v_mul_f32_e32 v161, v3, v115
	v_mul_f32_e32 v162, v4, v116
	v_mul_f32_e32 v163, v5, v117
	v_mfma_f32_16x16x32_bf16 v[90:93], v[6:9], v[42:45], v[90:93]
	v_add_f32_e32 v158, v160, v161
	v_add_f32_e32 v158, v162, v158
	v_add_f32_e32 v158, v163, v158
	v_med3_f32 v118, v118, 0, v240
	v_med3_f32 v119, v119, 0, v240
	v_med3_f32 v120, v120, 0, v240
	v_med3_f32 v121, v121, 0, v240
	v_mul_f32_e32 v160, v2, v118
	v_mfma_f32_16x16x32_bf16 v[94:97], v[6:9], v[46:49], v[94:97]
	v_mul_f32_e32 v161, v3, v119
	v_mul_f32_e32 v162, v4, v120
	v_mul_f32_e32 v163, v5, v121
	v_add_f32_e32 v159, v160, v161
	v_add_f32_e32 v159, v162, v159
	v_add_f32_e32 v159, v163, v159
	s_nop 1
	v_permlane16_swap_b32_e32 v156, v157
	v_mfma_f32_16x16x32_bf16 v[98:101], v[6:9], v[50:53], v[98:101]
	v_permlane16_swap_b32_e32 v158, v159
	v_add_f32_e32 v156, v156, v157
	v_add_f32_e32 v158, v158, v159
	s_nop 1
	v_permlane32_swap_b32_e32 v156, v158
	v_ashrrev_i32_e32 v164, 31, v156
	v_ashrrev_i32_e32 v165, 31, v158
	v_or_b32_e32 v164, 0x80000000, v164
	v_mfma_f32_16x16x32_bf16 v[102:105], v[6:9], v[54:57], v[102:105]
	v_or_b32_e32 v165, 0x80000000, v165
	v_xor_b32_e32 v164, v156, v164
	v_xor_b32_e32 v165, v158, v165
	v_and_b32_e32 v164, 0xffffff00, v164
	v_and_b32_e32 v165, 0xffffff00, v165
	v_cmp_ge_i32_e32 vcc, s5, v242
	s_nop 1
	v_cndmask_b32_e32 v225, 0, v164, vcc
	v_cmp_ge_i32_e32 vcc, s67, v242
	s_nop 1
	v_cndmask_b32_e32 v165, 0, v165, vcc
	global_store_dword v168, v165, s[8:9] offset:3328
	s_waitcnt lgkmcnt(0)
	v_mfma_f32_16x16x32_bf16 v[106:109], v[10:13], v[58:61], 0
	s_sub_i32 s5, s57, 896
	s_add_i32 s67, s5, 1
	v_med3_f32 v90, v90, 0, v240
	v_med3_f32 v91, v91, 0, v240
	v_med3_f32 v92, v92, 0, v240
	v_med3_f32 v93, v93, 0, v240
	v_mul_f32_e32 v160, v2, v90
	v_mul_f32_e32 v161, v3, v91
	v_mfma_f32_16x16x32_bf16 v[110:113], v[10:13], v[62:65], 0
	v_mul_f32_e32 v162, v4, v92
	v_mul_f32_e32 v163, v5, v93
	v_add_f32_e32 v156, v160, v161
	v_add_f32_e32 v156, v162, v156
	v_add_f32_e32 v156, v163, v156
	v_med3_f32 v94, v94, 0, v240
	v_med3_f32 v95, v95, 0, v240
	v_med3_f32 v96, v96, 0, v240
	v_mfma_f32_16x16x32_bf16 v[114:117], v[10:13], v[66:69], 0
	v_med3_f32 v97, v97, 0, v240
	v_mul_f32_e32 v160, v2, v94
	v_mul_f32_e32 v161, v3, v95
	v_mul_f32_e32 v162, v4, v96
	v_mul_f32_e32 v163, v5, v97
	v_add_f32_e32 v157, v160, v161
	v_add_f32_e32 v157, v162, v157
	v_add_f32_e32 v157, v163, v157
	v_mfma_f32_16x16x32_bf16 v[118:121], v[10:13], v[70:73], 0
	v_med3_f32 v98, v98, 0, v240
	v_med3_f32 v99, v99, 0, v240
	v_med3_f32 v100, v100, 0, v240
	v_med3_f32 v101, v101, 0, v240
	v_mul_f32_e32 v160, v2, v98
	v_mul_f32_e32 v161, v3, v99
	v_mul_f32_e32 v162, v4, v100
	v_mul_f32_e32 v163, v5, v101
	v_mfma_f32_16x16x32_bf16 v[106:109], v[6:9], v[74:77], v[106:109]
	v_add_f32_e32 v158, v160, v161
	v_add_f32_e32 v158, v162, v158
	v_add_f32_e32 v158, v163, v158
	v_med3_f32 v102, v102, 0, v240
	v_med3_f32 v103, v103, 0, v240
	v_med3_f32 v104, v104, 0, v240
	v_med3_f32 v105, v105, 0, v240
	v_mul_f32_e32 v160, v2, v102
	v_mfma_f32_16x16x32_bf16 v[110:113], v[6:9], v[78:81], v[110:113]
	v_mul_f32_e32 v161, v3, v103
	v_mul_f32_e32 v162, v4, v104
	v_mul_f32_e32 v163, v5, v105
	v_add_f32_e32 v159, v160, v161
	v_add_f32_e32 v159, v162, v159
	v_add_f32_e32 v159, v163, v159
	s_nop 1
	v_permlane16_swap_b32_e32 v156, v157
	v_mfma_f32_16x16x32_bf16 v[114:117], v[6:9], v[82:85], v[114:117]
	v_permlane16_swap_b32_e32 v158, v159
	v_add_f32_e32 v156, v156, v157
	v_add_f32_e32 v158, v158, v159
	s_nop 1
	v_permlane32_swap_b32_e32 v156, v158
	v_ashrrev_i32_e32 v164, 31, v156
	v_ashrrev_i32_e32 v165, 31, v158
	v_or_b32_e32 v164, 0x80000000, v164
	v_mfma_f32_16x16x32_bf16 v[118:121], v[6:9], v[86:89], v[118:121]
	v_or_b32_e32 v165, 0x80000000, v165
	v_xor_b32_e32 v164, v156, v164
	v_xor_b32_e32 v165, v158, v165
	v_and_b32_e32 v164, 0xffffff00, v164
	v_and_b32_e32 v165, 0xffffff00, v165
	v_cmp_ge_i32_e32 vcc, s5, v242
	s_nop 1
	v_cndmask_b32_e32 v226, 0, v164, vcc
	v_cmp_ge_i32_e32 vcc, s67, v242
	s_nop 1
	v_cndmask_b32_e32 v165, 0, v165, vcc
	global_store_dword v168, v165, s[8:9] offset:3584
.Lsc_h4:
	s_cmp_le_u32 s4, 4
	s_cbranch_scc1 .Lsc_drain4
	s_cmp_gt_u32 s4, 6
	s_cbranch_scc0 .Lsc_ni4
	v_lshl_add_u64 v[170:171], s[48:49], 0, v[0:1]
	s_add_i32 m0, s1, 0x10000
	s_nop 0
	global_load_lds_dwordx4 v[170:171], off
	v_lshl_add_u64 v[170:171], s[48:49], 0, v[18:19]
	s_add_i32 m0, s1, 0x12000
	s_nop 0
	global_load_lds_dwordx4 v[170:171], off
	v_lshl_add_u64 v[170:171], s[48:49], 0, v[20:21]
	s_add_i32 m0, s1, 0x14000
	s_nop 0
	global_load_lds_dwordx4 v[170:171], off
	v_lshl_add_u64 v[170:171], s[48:49], 0, v[22:23]
	s_add_i32 m0, s1, 0x16000
	s_nop 0
	global_load_lds_dwordx4 v[170:171], off
	s_add_u32 s48, s48, 0x8000
	s_addc_u32 s49, s49, 0
	s_waitcnt vmcnt(8)
	s_branch .Lsc_b4
.Lsc_ni4:
	s_cmp_gt_u32 s4, 5
	s_cbranch_scc0 .Lsc_w04
	s_waitcnt vmcnt(4)
	s_branch .Lsc_b4

.Lsc_b4:
	s_barrier
	ds_read_b128 v[26:29], v124
	ds_read_b128 v[30:33], v124 offset:2048
	ds_read_b128 v[34:37], v124 offset:4096
	ds_read_b128 v[38:41], v124 offset:6144
	ds_read_b128 v[42:45], v125
	ds_read_b128 v[46:49], v125 offset:2048
	ds_read_b128 v[50:53], v125 offset:4096
	ds_read_b128 v[54:57], v125 offset:6144
	ds_read_b128 v[58:61], v124 offset:8192
	ds_read_b128 v[62:65], v124 offset:10240
	ds_read_b128 v[66:69], v124 offset:12288
	ds_read_b128 v[70:73], v124 offset:14336
	ds_read_b128 v[74:77], v125 offset:8192
	ds_read_b128 v[78:81], v125 offset:10240
	ds_read_b128 v[82:85], v125 offset:12288
	ds_read_b128 v[86:89], v125 offset:14336
	s_sub_i32 s5, s57, 960
	s_add_i32 s67, s5, 1
	v_med3_f32 v106, v106, 0, v240
	v_med3_f32 v107, v107, 0, v240
	v_med3_f32 v108, v108, 0, v240
	v_med3_f32 v109, v109, 0, v240
	v_mul_f32_e32 v160, v2, v106
	v_mul_f32_e32 v161, v3, v107
	v_mul_f32_e32 v162, v4, v108
	v_mul_f32_e32 v163, v5, v109
	v_add_f32_e32 v156, v160, v161
	v_add_f32_e32 v156, v162, v156
	v_add_f32_e32 v156, v163, v156
	v_med3_f32 v110, v110, 0, v240
	v_med3_f32 v111, v111, 0, v240
	v_med3_f32 v112, v112, 0, v240
	v_med3_f32 v113, v113, 0, v240
	v_mul_f32_e32 v160, v2, v110
	v_mul_f32_e32 v161, v3, v111
	v_mul_f32_e32 v162, v4, v112
	v_mul_f32_e32 v163, v5, v113
	v_add_f32_e32 v157, v160, v161
	v_add_f32_e32 v157, v162, v157
	v_add_f32_e32 v157, v163, v157
	v_med3_f32 v114, v114, 0, v240
	v_med3_f32 v115, v115, 0, v240
	v_med3_f32 v116, v116, 0, v240
	v_med3_f32 v117, v117, 0, v240
	v_mul_f32_e32 v160, v2, v114
	v_mul_f32_e32 v161, v3, v115
	v_mul_f32_e32 v162, v4, v116
	v_mul_f32_e32 v163, v5, v117
	v_add_f32_e32 v158, v160, v161
	v_add_f32_e32 v158, v162, v158
	s_waitcnt lgkmcnt(8)
	v_mfma_f32_16x16x32_bf16 v[90:93], v[10:13], v[26:29], 0
	v_add_f32_e32 v158, v163, v158
	v_med3_f32 v118, v118, 0, v240
	v_med3_f32 v119, v119, 0, v240
	v_med3_f32 v120, v120, 0, v240
	v_mfma_f32_16x16x32_bf16 v[94:97], v[10:13], v[30:33], 0
	v_med3_f32 v121, v121, 0, v240
	v_mul_f32_e32 v160, v2, v118
	v_mul_f32_e32 v161, v3, v119
	v_mul_f32_e32 v162, v4, v120
	v_mfma_f32_16x16x32_bf16 v[98:101], v[10:13], v[34:37], 0
	v_mul_f32_e32 v163, v5, v121
	v_add_f32_e32 v159, v160, v161
	v_add_f32_e32 v159, v162, v159
	v_add_f32_e32 v159, v163, v159
	v_mfma_f32_16x16x32_bf16 v[102:105], v[10:13], v[38:41], 0
	s_nop 1
	v_permlane16_swap_b32_e32 v156, v157
	v_permlane16_swap_b32_e32 v158, v159
	v_add_f32_e32 v156, v156, v157
	v_mfma_f32_16x16x32_bf16 v[90:93], v[6:9], v[42:45], v[90:93]
	v_add_f32_e32 v158, v158, v159
	s_nop 1
	v_permlane32_swap_b32_e32 v156, v158
	v_ashrrev_i32_e32 v164, 31, v156
	v_mfma_f32_16x16x32_bf16 v[94:97], v[6:9], v[46:49], v[94:97]
	v_ashrrev_i32_e32 v165, 31, v158
	v_or_b32_e32 v164, 0x80000000, v164
	v_or_b32_e32 v165, 0x80000000, v165
	v_xor_b32_e32 v164, v156, v164
	v_mfma_f32_16x16x32_bf16 v[98:101], v[6:9], v[50:53], v[98:101]
	v_xor_b32_e32 v165, v158, v165
	v_and_b32_e32 v164, 0xffffff00, v164
	v_and_b32_e32 v165, 0xffffff00, v165
	v_cmp_ge_i32_e32 vcc, s5, v242
	v_mfma_f32_16x16x32_bf16 v[102:105], v[6:9], v[54:57], v[102:105]
	s_nop 1
	v_cndmask_b32_e32 v227, 0, v164, vcc
	v_cmp_ge_i32_e32 vcc, s67, v242
	s_nop 1
	v_cndmask_b32_e32 v165, 0, v165, vcc
	global_store_dword v168, v165, s[8:9] offset:3840
	ds_read_b128 v[26:29], v124 offset:16384
	ds_read_b128 v[30:33], v124 offset:18432
	ds_read_b128 v[34:37], v124 offset:20480
	ds_read_b128 v[38:41], v124 offset:22528
	ds_read_b128 v[42:45], v125 offset:16384
	ds_read_b128 v[46:49], v125 offset:18432
	ds_read_b128 v[50:53], v125 offset:20480
	ds_read_b128 v[54:57], v125 offset:22528
	s_waitcnt lgkmcnt(8)
	v_mfma_f32_16x16x32_bf16 v[106:109], v[10:13], v[58:61], 0
	s_sub_i32 s5, s57, 1024
	s_add_i32 s67, s5, 1
	v_med3_f32 v90, v90, 0, v240
	v_med3_f32 v91, v91, 0, v240
	v_med3_f32 v92, v92, 0, v240
	v_med3_f32 v93, v93, 0, v240
	v_mul_f32_e32 v160, v2, v90
	v_mul_f32_e32 v161, v3, v91
	v_mfma_f32_16x16x32_bf16 v[110:113], v[10:13], v[62:65], 0
	v_mul_f32_e32 v162, v4, v92
	v_mul_f32_e32 v163, v5, v93
	v_add_f32_e32 v156, v160, v161
	v_add_f32_e32 v156, v162, v156
	v_add_f32_e32 v156, v163, v156
	v_med3_f32 v94, v94, 0, v240
	v_med3_f32 v95, v95, 0, v240
	v_med3_f32 v96, v96, 0, v240
	v_mfma_f32_16x16x32_bf16 v[114:117], v[10:13], v[66:69], 0
	v_med3_f32 v97, v97, 0, v240
	v_mul_f32_e32 v160, v2, v94
	v_mul_f32_e32 v161, v3, v95
	v_mul_f32_e32 v162, v4, v96
	v_mul_f32_e32 v163, v5, v97
	v_add_f32_e32 v157, v160, v161
	v_add_f32_e32 v157, v162, v157
	v_add_f32_e32 v157, v163, v157
	v_mfma_f32_16x16x32_bf16 v[118:121], v[10:13], v[70:73], 0
	v_med3_f32 v98, v98, 0, v240
	v_med3_f32 v99, v99, 0, v240
	v_med3_f32 v100, v100, 0, v240
	v_med3_f32 v101, v101, 0, v240
	v_mul_f32_e32 v160, v2, v98
	v_mul_f32_e32 v161, v3, v99
	v_mul_f32_e32 v162, v4, v100
	v_mul_f32_e32 v163, v5, v101
	v_mfma_f32_16x16x32_bf16 v[106:109], v[6:9], v[74:77], v[106:109]
	v_add_f32_e32 v158, v160, v161
	v_add_f32_e32 v158, v162, v158
	v_add_f32_e32 v158, v163, v158
	v_med3_f32 v102, v102, 0, v240
	v_med3_f32 v103, v103, 0, v240
	v_med3_f32 v104, v104, 0, v240
	v_med3_f32 v105, v105, 0, v240
	v_mul_f32_e32 v160, v2, v102
	v_mfma_f32_16x16x32_bf16 v[110:113], v[6:9], v[78:81], v[110:113]
	v_mul_f32_e32 v161, v3, v103
	v_mul_f32_e32 v162, v4, v104
	v_mul_f32_e32 v163, v5, v105
	v_add_f32_e32 v159, v160, v161
	v_add_f32_e32 v159, v162, v159
	v_add_f32_e32 v159, v163, v159
	s_nop 1
	v_permlane16_swap_b32_e32 v156, v157
	v_mfma_f32_16x16x32_bf16 v[114:117], v[6:9], v[82:85], v[114:117]
	v_permlane16_swap_b32_e32 v158, v159
	v_add_f32_e32 v156, v156, v157
	v_add_f32_e32 v158, v158, v159
	s_nop 1
	v_permlane32_swap_b32_e32 v156, v158
	v_ashrrev_i32_e32 v164, 31, v156
	v_ashrrev_i32_e32 v165, 31, v158
	v_or_b32_e32 v164, 0x80000000, v164
	v_mfma_f32_16x16x32_bf16 v[118:121], v[6:9], v[86:89], v[118:121]
	v_or_b32_e32 v165, 0x80000000, v165
	v_xor_b32_e32 v164, v156, v164
	v_xor_b32_e32 v165, v158, v165
	v_and_b32_e32 v164, 0xffffff00, v164
	v_and_b32_e32 v165, 0xffffff00, v165
	v_cmp_ge_i32_e32 vcc, s5, v242
	s_nop 1
	v_cndmask_b32_e32 v228, 0, v164, vcc
	v_cmp_ge_i32_e32 vcc, s67, v242
	s_nop 1
	v_cndmask_b32_e32 v165, 0, v165, vcc
	global_store_dword v168, v165, s[14:15]
	ds_read_b128 v[58:61], v124 offset:24576
	ds_read_b128 v[62:65], v124 offset:26624
	ds_read_b128 v[66:69], v124 offset:28672
	ds_read_b128 v[70:73], v124 offset:30720
	ds_read_b128 v[74:77], v125 offset:24576
	ds_read_b128 v[78:81], v125 offset:26624
	ds_read_b128 v[82:85], v125 offset:28672
	ds_read_b128 v[86:89], v125 offset:30720
	s_waitcnt lgkmcnt(8)
	v_mfma_f32_16x16x32_bf16 v[90:93], v[10:13], v[26:29], 0
	s_sub_i32 s5, s57, 1088
	s_add_i32 s67, s5, 1
	v_med3_f32 v106, v106, 0, v240
	v_med3_f32 v107, v107, 0, v240
	v_med3_f32 v108, v108, 0, v240
	v_med3_f32 v109, v109, 0, v240
	v_mul_f32_e32 v160, v2, v106
	v_mul_f32_e32 v161, v3, v107
	v_mfma_f32_16x16x32_bf16 v[94:97], v[10:13], v[30:33], 0
	v_mul_f32_e32 v162, v4, v108
	v_mul_f32_e32 v163, v5, v109
	v_add_f32_e32 v156, v160, v161
	v_add_f32_e32 v156, v162, v156
	v_add_f32_e32 v156, v163, v156
	v_med3_f32 v110, v110, 0, v240
	v_med3_f32 v111, v111, 0, v240
	v_med3_f32 v112, v112, 0, v240
	v_mfma_f32_16x16x32_bf16 v[98:101], v[10:13], v[34:37], 0
	v_med3_f32 v113, v113, 0, v240
	v_mul_f32_e32 v160, v2, v110
	v_mul_f32_e32 v161, v3, v111
	v_mul_f32_e32 v162, v4, v112
	v_mul_f32_e32 v163, v5, v113
	v_add_f32_e32 v157, v160, v161
	v_add_f32_e32 v157, v162, v157
	v_add_f32_e32 v157, v163, v157
	v_mfma_f32_16x16x32_bf16 v[102:105], v[10:13], v[38:41], 0
	v_med3_f32 v114, v114, 0, v240
	v_med3_f32 v115, v115, 0, v240
	v_med3_f32 v116, v116, 0, v240
	v_med3_f32 v117, v117, 0, v240
	v_mul_f32_e32 v160, v2, v114
	v_mul_f32_e32 v161, v3, v115
	v_mul_f32_e32 v162, v4, v116
	v_mul_f32_e32 v163, v5, v117
	v_mfma_f32_16x16x32_bf16 v[90:93], v[6:9], v[42:45], v[90:93]
	v_add_f32_e32 v158, v160, v161
	v_add_f32_e32 v158, v162, v158
	v_add_f32_e32 v158, v163, v158
	v_med3_f32 v118, v118, 0, v240
	v_med3_f32 v119, v119, 0, v240
	v_med3_f32 v120, v120, 0, v240
	v_med3_f32 v121, v121, 0, v240
	v_mul_f32_e32 v160, v2, v118
	v_mfma_f32_16x16x32_bf16 v[94:97], v[6:9], v[46:49], v[94:97]
	v_mul_f32_e32 v161, v3, v119
	v_mul_f32_e32 v162, v4, v120
	v_mul_f32_e32 v163, v5, v121
	v_add_f32_e32 v159, v160, v161
	v_add_f32_e32 v159, v162, v159
	v_add_f32_e32 v159, v163, v159
	s_nop 1
	v_permlane16_swap_b32_e32 v156, v157
	v_mfma_f32_16x16x32_bf16 v[98:101], v[6:9], v[50:53], v[98:101]
	v_permlane16_swap_b32_e32 v158, v159
	v_add_f32_e32 v156, v156, v157
	v_add_f32_e32 v158, v158, v159
	s_nop 1
	v_permlane32_swap_b32_e32 v156, v158
	v_ashrrev_i32_e32 v164, 31, v156
	v_ashrrev_i32_e32 v165, 31, v158
	v_or_b32_e32 v164, 0x80000000, v164
	v_mfma_f32_16x16x32_bf16 v[102:105], v[6:9], v[54:57], v[102:105]
	v_or_b32_e32 v165, 0x80000000, v165
	v_xor_b32_e32 v164, v156, v164
	v_xor_b32_e32 v165, v158, v165
	v_and_b32_e32 v164, 0xffffff00, v164
	v_and_b32_e32 v165, 0xffffff00, v165
	v_cmp_ge_i32_e32 vcc, s5, v242
	s_nop 1
	v_cndmask_b32_e32 v229, 0, v164, vcc
	v_cmp_ge_i32_e32 vcc, s67, v242
	s_nop 1
	v_cndmask_b32_e32 v165, 0, v165, vcc
	global_store_dword v168, v165, s[14:15] offset:256
	s_waitcnt lgkmcnt(0)
	v_mfma_f32_16x16x32_bf16 v[106:109], v[10:13], v[58:61], 0
	s_sub_i32 s5, s57, 1152
	s_add_i32 s67, s5, 1
	v_med3_f32 v90, v90, 0, v240
	v_med3_f32 v91, v91, 0, v240
	v_med3_f32 v92, v92, 0, v240
	v_med3_f32 v93, v93, 0, v240
	v_mul_f32_e32 v160, v2, v90
	v_mul_f32_e32 v161, v3, v91
	v_mfma_f32_16x16x32_bf16 v[110:113], v[10:13], v[62:65], 0
	v_mul_f32_e32 v162, v4, v92
	v_mul_f32_e32 v163, v5, v93
	v_add_f32_e32 v156, v160, v161
	v_add_f32_e32 v156, v162, v156
	v_add_f32_e32 v156, v163, v156
	v_med3_f32 v94, v94, 0, v240
	v_med3_f32 v95, v95, 0, v240
	v_med3_f32 v96, v96, 0, v240
	v_mfma_f32_16x16x32_bf16 v[114:117], v[10:13], v[66:69], 0
	v_med3_f32 v97, v97, 0, v240
	v_mul_f32_e32 v160, v2, v94
	v_mul_f32_e32 v161, v3, v95
	v_mul_f32_e32 v162, v4, v96
	v_mul_f32_e32 v163, v5, v97
	v_add_f32_e32 v157, v160, v161
	v_add_f32_e32 v157, v162, v157
	v_add_f32_e32 v157, v163, v157
	v_mfma_f32_16x16x32_bf16 v[118:121], v[10:13], v[70:73], 0
	v_med3_f32 v98, v98, 0, v240
	v_med3_f32 v99, v99, 0, v240
	v_med3_f32 v100, v100, 0, v240
	v_med3_f32 v101, v101, 0, v240
	v_mul_f32_e32 v160, v2, v98
	v_mul_f32_e32 v161, v3, v99
	v_mul_f32_e32 v162, v4, v100
	v_mul_f32_e32 v163, v5, v101
	v_mfma_f32_16x16x32_bf16 v[106:109], v[6:9], v[74:77], v[106:109]
	v_add_f32_e32 v158, v160, v161
	v_add_f32_e32 v158, v162, v158
	v_add_f32_e32 v158, v163, v158
	v_med3_f32 v102, v102, 0, v240
	v_med3_f32 v103, v103, 0, v240
	v_med3_f32 v104, v104, 0, v240
	v_med3_f32 v105, v105, 0, v240
	v_mul_f32_e32 v160, v2, v102
	v_mfma_f32_16x16x32_bf16 v[110:113], v[6:9], v[78:81], v[110:113]
	v_mul_f32_e32 v161, v3, v103
	v_mul_f32_e32 v162, v4, v104
	v_mul_f32_e32 v163, v5, v105
	v_add_f32_e32 v159, v160, v161
	v_add_f32_e32 v159, v162, v159
	v_add_f32_e32 v159, v163, v159
	s_nop 1
	v_permlane16_swap_b32_e32 v156, v157
	v_mfma_f32_16x16x32_bf16 v[114:117], v[6:9], v[82:85], v[114:117]
	v_permlane16_swap_b32_e32 v158, v159
	v_add_f32_e32 v156, v156, v157
	v_add_f32_e32 v158, v158, v159
	s_nop 1
	v_permlane32_swap_b32_e32 v156, v158
	v_ashrrev_i32_e32 v164, 31, v156
	v_ashrrev_i32_e32 v165, 31, v158
	v_or_b32_e32 v164, 0x80000000, v164
	v_mfma_f32_16x16x32_bf16 v[118:121], v[6:9], v[86:89], v[118:121]
	v_or_b32_e32 v165, 0x80000000, v165
	v_xor_b32_e32 v164, v156, v164
	v_xor_b32_e32 v165, v158, v165
	v_and_b32_e32 v164, 0xffffff00, v164
	v_and_b32_e32 v165, 0xffffff00, v165
	v_cmp_ge_i32_e32 vcc, s5, v242
	s_nop 1
	v_cndmask_b32_e32 v230, 0, v164, vcc
	v_cmp_ge_i32_e32 vcc, s67, v242
	s_nop 1
	v_cndmask_b32_e32 v165, 0, v165, vcc
	global_store_dword v168, v165, s[14:15] offset:512
.Lsc_h5:
	s_cmp_le_u32 s4, 5
	s_cbranch_scc1 .Lsc_drain5
	s_cmp_gt_u32 s4, 7
	s_cbranch_scc0 .Lsc_ni5
	v_lshl_add_u64 v[170:171], s[48:49], 0, v[0:1]
	s_add_i32 m0, s1, 0x18000
	s_nop 0
	global_load_lds_dwordx4 v[170:171], off
	v_lshl_add_u64 v[170:171], s[48:49], 0, v[18:19]
	s_add_i32 m0, s1, 0x1a000
	s_nop 0
	global_load_lds_dwordx4 v[170:171], off
	v_lshl_add_u64 v[170:171], s[48:49], 0, v[20:21]
	s_add_i32 m0, s1, 0x1c000
	s_nop 0
	global_load_lds_dwordx4 v[170:171], off
	v_lshl_add_u64 v[170:171], s[48:49], 0, v[22:23]
	s_add_i32 m0, s1, 0x1e000
	s_nop 0
	global_load_lds_dwordx4 v[170:171], off
	s_add_u32 s48, s48, 0x8000
	s_addc_u32 s49, s49, 0
	s_waitcnt vmcnt(8)
	s_branch .Lsc_b5
.Lsc_ni5:
	s_cmp_gt_u32 s4, 6
	s_cbranch_scc0 .Lsc_w05
	s_waitcnt vmcnt(4)
	s_branch .Lsc_b5

.Lsc_b5:
	s_barrier
	ds_read_b128 v[26:29], v124 offset:32768
	ds_read_b128 v[30:33], v124 offset:34816
	ds_read_b128 v[34:37], v124 offset:36864
	ds_read_b128 v[38:41], v124 offset:38912
	ds_read_b128 v[42:45], v125 offset:32768
	ds_read_b128 v[46:49], v125 offset:34816
	ds_read_b128 v[50:53], v125 offset:36864
	ds_read_b128 v[54:57], v125 offset:38912
	ds_read_b128 v[58:61], v124 offset:40960
	ds_read_b128 v[62:65], v124 offset:43008
	ds_read_b128 v[66:69], v124 offset:45056
	ds_read_b128 v[70:73], v124 offset:47104
	ds_read_b128 v[74:77], v125 offset:40960
	ds_read_b128 v[78:81], v125 offset:43008
	ds_read_b128 v[82:85], v125 offset:45056
	ds_read_b128 v[86:89], v125 offset:47104
	s_sub_i32 s5, s57, 1216
	s_add_i32 s67, s5, 1
	v_med3_f32 v106, v106, 0, v240
	v_med3_f32 v107, v107, 0, v240
	v_med3_f32 v108, v108, 0, v240
	v_med3_f32 v109, v109, 0, v240
	v_mul_f32_e32 v160, v2, v106
	v_mul_f32_e32 v161, v3, v107
	v_mul_f32_e32 v162, v4, v108
	v_mul_f32_e32 v163, v5, v109
	v_add_f32_e32 v156, v160, v161
	v_add_f32_e32 v156, v162, v156
	v_add_f32_e32 v156, v163, v156
	v_med3_f32 v110, v110, 0, v240
	v_med3_f32 v111, v111, 0, v240
	v_med3_f32 v112, v112, 0, v240
	v_med3_f32 v113, v113, 0, v240
	v_mul_f32_e32 v160, v2, v110
	v_mul_f32_e32 v161, v3, v111
	v_mul_f32_e32 v162, v4, v112
	v_mul_f32_e32 v163, v5, v113
	v_add_f32_e32 v157, v160, v161
	v_add_f32_e32 v157, v162, v157
	v_add_f32_e32 v157, v163, v157
	v_med3_f32 v114, v114, 0, v240
	v_med3_f32 v115, v115, 0, v240
	v_med3_f32 v116, v116, 0, v240
	v_med3_f32 v117, v117, 0, v240
	v_mul_f32_e32 v160, v2, v114
	v_mul_f32_e32 v161, v3, v115
	v_mul_f32_e32 v162, v4, v116
	v_mul_f32_e32 v163, v5, v117
	v_add_f32_e32 v158, v160, v161
	v_add_f32_e32 v158, v162, v158
	s_waitcnt lgkmcnt(8)
	v_mfma_f32_16x16x32_bf16 v[90:93], v[10:13], v[26:29], 0
	v_add_f32_e32 v158, v163, v158
	v_med3_f32 v118, v118, 0, v240
	v_med3_f32 v119, v119, 0, v240
	v_med3_f32 v120, v120, 0, v240
	v_mfma_f32_16x16x32_bf16 v[94:97], v[10:13], v[30:33], 0
	v_med3_f32 v121, v121, 0, v240
	v_mul_f32_e32 v160, v2, v118
	v_mul_f32_e32 v161, v3, v119
	v_mul_f32_e32 v162, v4, v120
	v_mfma_f32_16x16x32_bf16 v[98:101], v[10:13], v[34:37], 0
	v_mul_f32_e32 v163, v5, v121
	v_add_f32_e32 v159, v160, v161
	v_add_f32_e32 v159, v162, v159
	v_add_f32_e32 v159, v163, v159
	v_mfma_f32_16x16x32_bf16 v[102:105], v[10:13], v[38:41], 0
	s_nop 1
	v_permlane16_swap_b32_e32 v156, v157
	v_permlane16_swap_b32_e32 v158, v159
	v_add_f32_e32 v156, v156, v157
	v_mfma_f32_16x16x32_bf16 v[90:93], v[6:9], v[42:45], v[90:93]
	v_add_f32_e32 v158, v158, v159
	s_nop 1
	v_permlane32_swap_b32_e32 v156, v158
	v_ashrrev_i32_e32 v164, 31, v156
	v_mfma_f32_16x16x32_bf16 v[94:97], v[6:9], v[46:49], v[94:97]
	v_ashrrev_i32_e32 v165, 31, v158
	v_or_b32_e32 v164, 0x80000000, v164
	v_or_b32_e32 v165, 0x80000000, v165
	v_xor_b32_e32 v164, v156, v164
	v_mfma_f32_16x16x32_bf16 v[98:101], v[6:9], v[50:53], v[98:101]
	v_xor_b32_e32 v165, v158, v165
	v_and_b32_e32 v164, 0xffffff00, v164
	v_and_b32_e32 v165, 0xffffff00, v165
	v_cmp_ge_i32_e32 vcc, s5, v242
	v_mfma_f32_16x16x32_bf16 v[102:105], v[6:9], v[54:57], v[102:105]
	s_nop 1
	v_cndmask_b32_e32 v231, 0, v164, vcc
	v_cmp_ge_i32_e32 vcc, s67, v242
	s_nop 1
	v_cndmask_b32_e32 v165, 0, v165, vcc
	global_store_dword v168, v165, s[14:15] offset:768
	ds_read_b128 v[26:29], v124 offset:49152
	ds_read_b128 v[30:33], v124 offset:51200
	ds_read_b128 v[34:37], v124 offset:53248
	ds_read_b128 v[38:41], v124 offset:55296
	ds_read_b128 v[42:45], v125 offset:49152
	ds_read_b128 v[46:49], v125 offset:51200
	ds_read_b128 v[50:53], v125 offset:53248
	ds_read_b128 v[54:57], v125 offset:55296
	s_waitcnt lgkmcnt(8)
	v_mfma_f32_16x16x32_bf16 v[106:109], v[10:13], v[58:61], 0
	s_sub_i32 s5, s57, 1280
	s_add_i32 s67, s5, 1
	v_med3_f32 v90, v90, 0, v240
	v_med3_f32 v91, v91, 0, v240
	v_med3_f32 v92, v92, 0, v240
	v_med3_f32 v93, v93, 0, v240
	v_mul_f32_e32 v160, v2, v90
	v_mul_f32_e32 v161, v3, v91
	v_mfma_f32_16x16x32_bf16 v[110:113], v[10:13], v[62:65], 0
	v_mul_f32_e32 v162, v4, v92
	v_mul_f32_e32 v163, v5, v93
	v_add_f32_e32 v156, v160, v161
	v_add_f32_e32 v156, v162, v156
	v_add_f32_e32 v156, v163, v156
	v_med3_f32 v94, v94, 0, v240
	v_med3_f32 v95, v95, 0, v240
	v_med3_f32 v96, v96, 0, v240
	v_mfma_f32_16x16x32_bf16 v[114:117], v[10:13], v[66:69], 0
	v_med3_f32 v97, v97, 0, v240
	v_mul_f32_e32 v160, v2, v94
	v_mul_f32_e32 v161, v3, v95
	v_mul_f32_e32 v162, v4, v96
	v_mul_f32_e32 v163, v5, v97
	v_add_f32_e32 v157, v160, v161
	v_add_f32_e32 v157, v162, v157
	v_add_f32_e32 v157, v163, v157
	v_mfma_f32_16x16x32_bf16 v[118:121], v[10:13], v[70:73], 0
	v_med3_f32 v98, v98, 0, v240
	v_med3_f32 v99, v99, 0, v240
	v_med3_f32 v100, v100, 0, v240
	v_med3_f32 v101, v101, 0, v240
	v_mul_f32_e32 v160, v2, v98
	v_mul_f32_e32 v161, v3, v99
	v_mul_f32_e32 v162, v4, v100
	v_mul_f32_e32 v163, v5, v101
	v_mfma_f32_16x16x32_bf16 v[106:109], v[6:9], v[74:77], v[106:109]
	v_add_f32_e32 v158, v160, v161
	v_add_f32_e32 v158, v162, v158
	v_add_f32_e32 v158, v163, v158
	v_med3_f32 v102, v102, 0, v240
	v_med3_f32 v103, v103, 0, v240
	v_med3_f32 v104, v104, 0, v240
	v_med3_f32 v105, v105, 0, v240
	v_mul_f32_e32 v160, v2, v102
	v_mfma_f32_16x16x32_bf16 v[110:113], v[6:9], v[78:81], v[110:113]
	v_mul_f32_e32 v161, v3, v103
	v_mul_f32_e32 v162, v4, v104
	v_mul_f32_e32 v163, v5, v105
	v_add_f32_e32 v159, v160, v161
	v_add_f32_e32 v159, v162, v159
	v_add_f32_e32 v159, v163, v159
	s_nop 1
	v_permlane16_swap_b32_e32 v156, v157
	v_mfma_f32_16x16x32_bf16 v[114:117], v[6:9], v[82:85], v[114:117]
	v_permlane16_swap_b32_e32 v158, v159
	v_add_f32_e32 v156, v156, v157
	v_add_f32_e32 v158, v158, v159
	s_nop 1
	v_permlane32_swap_b32_e32 v156, v158
	v_ashrrev_i32_e32 v164, 31, v156
	v_ashrrev_i32_e32 v165, 31, v158
	v_or_b32_e32 v164, 0x80000000, v164
	v_mfma_f32_16x16x32_bf16 v[118:121], v[6:9], v[86:89], v[118:121]
	v_or_b32_e32 v165, 0x80000000, v165
	v_xor_b32_e32 v164, v156, v164
	v_xor_b32_e32 v165, v158, v165
	v_and_b32_e32 v164, 0xffffff00, v164
	v_and_b32_e32 v165, 0xffffff00, v165
	v_cmp_ge_i32_e32 vcc, s5, v242
	s_nop 1
	v_cndmask_b32_e32 v232, 0, v164, vcc
	v_cmp_ge_i32_e32 vcc, s67, v242
	s_nop 1
	v_cndmask_b32_e32 v165, 0, v165, vcc
	global_store_dword v168, v165, s[14:15] offset:1024
	ds_read_b128 v[58:61], v124 offset:57344
	ds_read_b128 v[62:65], v124 offset:59392
	ds_read_b128 v[66:69], v124 offset:61440
	ds_read_b128 v[70:73], v124 offset:63488
	ds_read_b128 v[74:77], v125 offset:57344
	ds_read_b128 v[78:81], v125 offset:59392
	ds_read_b128 v[82:85], v125 offset:61440
	ds_read_b128 v[86:89], v125 offset:63488
	s_waitcnt lgkmcnt(8)
	v_mfma_f32_16x16x32_bf16 v[90:93], v[10:13], v[26:29], 0
	s_sub_i32 s5, s57, 1344
	s_add_i32 s67, s5, 1
	v_med3_f32 v106, v106, 0, v240
	v_med3_f32 v107, v107, 0, v240
	v_med3_f32 v108, v108, 0, v240
	v_med3_f32 v109, v109, 0, v240
	v_mul_f32_e32 v160, v2, v106
	v_mul_f32_e32 v161, v3, v107
	v_mfma_f32_16x16x32_bf16 v[94:97], v[10:13], v[30:33], 0
	v_mul_f32_e32 v162, v4, v108
	v_mul_f32_e32 v163, v5, v109
	v_add_f32_e32 v156, v160, v161
	v_add_f32_e32 v156, v162, v156
	v_add_f32_e32 v156, v163, v156
	v_med3_f32 v110, v110, 0, v240
	v_med3_f32 v111, v111, 0, v240
	v_med3_f32 v112, v112, 0, v240
	v_mfma_f32_16x16x32_bf16 v[98:101], v[10:13], v[34:37], 0
	v_med3_f32 v113, v113, 0, v240
	v_mul_f32_e32 v160, v2, v110
	v_mul_f32_e32 v161, v3, v111
	v_mul_f32_e32 v162, v4, v112
	v_mul_f32_e32 v163, v5, v113
	v_add_f32_e32 v157, v160, v161
	v_add_f32_e32 v157, v162, v157
	v_add_f32_e32 v157, v163, v157
	v_mfma_f32_16x16x32_bf16 v[102:105], v[10:13], v[38:41], 0
	v_med3_f32 v114, v114, 0, v240
	v_med3_f32 v115, v115, 0, v240
	v_med3_f32 v116, v116, 0, v240
	v_med3_f32 v117, v117, 0, v240
	v_mul_f32_e32 v160, v2, v114
	v_mul_f32_e32 v161, v3, v115
	v_mul_f32_e32 v162, v4, v116
	v_mul_f32_e32 v163, v5, v117
	v_mfma_f32_16x16x32_bf16 v[90:93], v[6:9], v[42:45], v[90:93]
	v_add_f32_e32 v158, v160, v161
	v_add_f32_e32 v158, v162, v158
	v_add_f32_e32 v158, v163, v158
	v_med3_f32 v118, v118, 0, v240
	v_med3_f32 v119, v119, 0, v240
	v_med3_f32 v120, v120, 0, v240
	v_med3_f32 v121, v121, 0, v240
	v_mul_f32_e32 v160, v2, v118
	v_mfma_f32_16x16x32_bf16 v[94:97], v[6:9], v[46:49], v[94:97]
	v_mul_f32_e32 v161, v3, v119
	v_mul_f32_e32 v162, v4, v120
	v_mul_f32_e32 v163, v5, v121
	v_add_f32_e32 v159, v160, v161
	v_add_f32_e32 v159, v162, v159
	v_add_f32_e32 v159, v163, v159
	s_nop 1
	v_permlane16_swap_b32_e32 v156, v157
	v_mfma_f32_16x16x32_bf16 v[98:101], v[6:9], v[50:53], v[98:101]
	v_permlane16_swap_b32_e32 v158, v159
	v_add_f32_e32 v156, v156, v157
	v_add_f32_e32 v158, v158, v159
	s_nop 1
	v_permlane32_swap_b32_e32 v156, v158
	v_ashrrev_i32_e32 v164, 31, v156
	v_ashrrev_i32_e32 v165, 31, v158
	v_or_b32_e32 v164, 0x80000000, v164
	v_mfma_f32_16x16x32_bf16 v[102:105], v[6:9], v[54:57], v[102:105]
	v_or_b32_e32 v165, 0x80000000, v165
	v_xor_b32_e32 v164, v156, v164
	v_xor_b32_e32 v165, v158, v165
	v_and_b32_e32 v164, 0xffffff00, v164
	v_and_b32_e32 v165, 0xffffff00, v165
	v_cmp_ge_i32_e32 vcc, s5, v242
	s_nop 1
	v_cndmask_b32_e32 v233, 0, v164, vcc
	v_cmp_ge_i32_e32 vcc, s67, v242
	s_nop 1
	v_cndmask_b32_e32 v165, 0, v165, vcc
	global_store_dword v168, v165, s[14:15] offset:1280
	s_waitcnt lgkmcnt(0)
	v_mfma_f32_16x16x32_bf16 v[106:109], v[10:13], v[58:61], 0
	s_sub_i32 s5, s57, 1408
	s_add_i32 s67, s5, 1
	v_med3_f32 v90, v90, 0, v240
	v_med3_f32 v91, v91, 0, v240
	v_med3_f32 v92, v92, 0, v240
	v_med3_f32 v93, v93, 0, v240
	v_mul_f32_e32 v160, v2, v90
	v_mul_f32_e32 v161, v3, v91
	v_mfma_f32_16x16x32_bf16 v[110:113], v[10:13], v[62:65], 0
	v_mul_f32_e32 v162, v4, v92
	v_mul_f32_e32 v163, v5, v93
	v_add_f32_e32 v156, v160, v161
	v_add_f32_e32 v156, v162, v156
	v_add_f32_e32 v156, v163, v156
	v_med3_f32 v94, v94, 0, v240
	v_med3_f32 v95, v95, 0, v240
	v_med3_f32 v96, v96, 0, v240
	v_mfma_f32_16x16x32_bf16 v[114:117], v[10:13], v[66:69], 0
	v_med3_f32 v97, v97, 0, v240
	v_mul_f32_e32 v160, v2, v94
	v_mul_f32_e32 v161, v3, v95
	v_mul_f32_e32 v162, v4, v96
	v_mul_f32_e32 v163, v5, v97
	v_add_f32_e32 v157, v160, v161
	v_add_f32_e32 v157, v162, v157
	v_add_f32_e32 v157, v163, v157
	v_mfma_f32_16x16x32_bf16 v[118:121], v[10:13], v[70:73], 0
	v_med3_f32 v98, v98, 0, v240
	v_med3_f32 v99, v99, 0, v240
	v_med3_f32 v100, v100, 0, v240
	v_med3_f32 v101, v101, 0, v240
	v_mul_f32_e32 v160, v2, v98
	v_mul_f32_e32 v161, v3, v99
	v_mul_f32_e32 v162, v4, v100
	v_mul_f32_e32 v163, v5, v101
	v_mfma_f32_16x16x32_bf16 v[106:109], v[6:9], v[74:77], v[106:109]
	v_add_f32_e32 v158, v160, v161
	v_add_f32_e32 v158, v162, v158
	v_add_f32_e32 v158, v163, v158
	v_med3_f32 v102, v102, 0, v240
	v_med3_f32 v103, v103, 0, v240
	v_med3_f32 v104, v104, 0, v240
	v_med3_f32 v105, v105, 0, v240
	v_mul_f32_e32 v160, v2, v102
	v_mfma_f32_16x16x32_bf16 v[110:113], v[6:9], v[78:81], v[110:113]
	v_mul_f32_e32 v161, v3, v103
	v_mul_f32_e32 v162, v4, v104
	v_mul_f32_e32 v163, v5, v105
	v_add_f32_e32 v159, v160, v161
	v_add_f32_e32 v159, v162, v159
	v_add_f32_e32 v159, v163, v159
	s_nop 1
	v_permlane16_swap_b32_e32 v156, v157
	v_mfma_f32_16x16x32_bf16 v[114:117], v[6:9], v[82:85], v[114:117]
	v_permlane16_swap_b32_e32 v158, v159
	v_add_f32_e32 v156, v156, v157
	v_add_f32_e32 v158, v158, v159
	s_nop 1
	v_permlane32_swap_b32_e32 v156, v158
	v_ashrrev_i32_e32 v164, 31, v156
	v_ashrrev_i32_e32 v165, 31, v158
	v_or_b32_e32 v164, 0x80000000, v164
	v_mfma_f32_16x16x32_bf16 v[118:121], v[6:9], v[86:89], v[118:121]
	v_or_b32_e32 v165, 0x80000000, v165
	v_xor_b32_e32 v164, v156, v164
	v_xor_b32_e32 v165, v158, v165
	v_and_b32_e32 v164, 0xffffff00, v164
	v_and_b32_e32 v165, 0xffffff00, v165
	v_cmp_ge_i32_e32 vcc, s5, v242
	s_nop 1
	v_cndmask_b32_e32 v234, 0, v164, vcc
	v_cmp_ge_i32_e32 vcc, s67, v242
	s_nop 1
	v_cndmask_b32_e32 v165, 0, v165, vcc
	global_store_dword v168, v165, s[14:15] offset:1536
.Lsc_h6:
	s_cmp_le_u32 s4, 6
	s_cbranch_scc1 .Lsc_drain6
	s_cmp_gt_u32 s4, 8
	s_cbranch_scc0 .Lsc_ni6
	v_lshl_add_u64 v[170:171], s[48:49], 0, v[0:1]
	s_add_i32 m0, s1, 0x0
	s_nop 0
	global_load_lds_dwordx4 v[170:171], off
	v_lshl_add_u64 v[170:171], s[48:49], 0, v[18:19]
	s_add_i32 m0, s1, 0x2000
	s_nop 0
	global_load_lds_dwordx4 v[170:171], off
	v_lshl_add_u64 v[170:171], s[48:49], 0, v[20:21]
	s_add_i32 m0, s1, 0x4000
	s_nop 0
	global_load_lds_dwordx4 v[170:171], off
	v_lshl_add_u64 v[170:171], s[48:49], 0, v[22:23]
	s_add_i32 m0, s1, 0x6000
	s_nop 0
	global_load_lds_dwordx4 v[170:171], off
	s_add_u32 s48, s48, 0x8000
	s_addc_u32 s49, s49, 0
	s_waitcnt vmcnt(8)
	s_branch .Lsc_b6
.Lsc_ni6:
	s_cmp_gt_u32 s4, 7
	s_cbranch_scc0 .Lsc_w06
	s_waitcnt vmcnt(4)
	s_branch .Lsc_b6

.Lsc_b6:
	s_barrier
	ds_read_b128 v[26:29], v166
	ds_read_b128 v[30:33], v166 offset:2048
	ds_read_b128 v[34:37], v166 offset:4096
	ds_read_b128 v[38:41], v166 offset:6144
	ds_read_b128 v[42:45], v167
	ds_read_b128 v[46:49], v167 offset:2048
	ds_read_b128 v[50:53], v167 offset:4096
	ds_read_b128 v[54:57], v167 offset:6144
	ds_read_b128 v[58:61], v166 offset:8192
	ds_read_b128 v[62:65], v166 offset:10240
	ds_read_b128 v[66:69], v166 offset:12288
	ds_read_b128 v[70:73], v166 offset:14336
	ds_read_b128 v[74:77], v167 offset:8192
	ds_read_b128 v[78:81], v167 offset:10240
	ds_read_b128 v[82:85], v167 offset:12288
	ds_read_b128 v[86:89], v167 offset:14336
	s_sub_i32 s5, s57, 1472
	s_add_i32 s67, s5, 1
	v_med3_f32 v106, v106, 0, v240
	v_med3_f32 v107, v107, 0, v240
	v_med3_f32 v108, v108, 0, v240
	v_med3_f32 v109, v109, 0, v240
	v_mul_f32_e32 v160, v2, v106
	v_mul_f32_e32 v161, v3, v107
	v_mul_f32_e32 v162, v4, v108
	v_mul_f32_e32 v163, v5, v109
	v_add_f32_e32 v156, v160, v161
	v_add_f32_e32 v156, v162, v156
	v_add_f32_e32 v156, v163, v156
	v_med3_f32 v110, v110, 0, v240
	v_med3_f32 v111, v111, 0, v240
	v_med3_f32 v112, v112, 0, v240
	v_med3_f32 v113, v113, 0, v240
	v_mul_f32_e32 v160, v2, v110
	v_mul_f32_e32 v161, v3, v111
	v_mul_f32_e32 v162, v4, v112
	v_mul_f32_e32 v163, v5, v113
	v_add_f32_e32 v157, v160, v161
	v_add_f32_e32 v157, v162, v157
	v_add_f32_e32 v157, v163, v157
	v_med3_f32 v114, v114, 0, v240
	v_med3_f32 v115, v115, 0, v240
	v_med3_f32 v116, v116, 0, v240
	v_med3_f32 v117, v117, 0, v240
	v_mul_f32_e32 v160, v2, v114
	v_mul_f32_e32 v161, v3, v115
	v_mul_f32_e32 v162, v4, v116
	v_mul_f32_e32 v163, v5, v117
	v_add_f32_e32 v158, v160, v161
	v_add_f32_e32 v158, v162, v158
	s_waitcnt lgkmcnt(8)
	v_mfma_f32_16x16x32_bf16 v[90:93], v[10:13], v[26:29], 0
	v_add_f32_e32 v158, v163, v158
	v_med3_f32 v118, v118, 0, v240
	v_med3_f32 v119, v119, 0, v240
	v_med3_f32 v120, v120, 0, v240
	v_mfma_f32_16x16x32_bf16 v[94:97], v[10:13], v[30:33], 0
	v_med3_f32 v121, v121, 0, v240
	v_mul_f32_e32 v160, v2, v118
	v_mul_f32_e32 v161, v3, v119
	v_mul_f32_e32 v162, v4, v120
	v_mfma_f32_16x16x32_bf16 v[98:101], v[10:13], v[34:37], 0
	v_mul_f32_e32 v163, v5, v121
	v_add_f32_e32 v159, v160, v161
	v_add_f32_e32 v159, v162, v159
	v_add_f32_e32 v159, v163, v159
	v_mfma_f32_16x16x32_bf16 v[102:105], v[10:13], v[38:41], 0
	s_nop 1
	v_permlane16_swap_b32_e32 v156, v157
	v_permlane16_swap_b32_e32 v158, v159
	v_add_f32_e32 v156, v156, v157
	v_mfma_f32_16x16x32_bf16 v[90:93], v[6:9], v[42:45], v[90:93]
	v_add_f32_e32 v158, v158, v159
	s_nop 1
	v_permlane32_swap_b32_e32 v156, v158
	v_ashrrev_i32_e32 v164, 31, v156
	v_mfma_f32_16x16x32_bf16 v[94:97], v[6:9], v[46:49], v[94:97]
	v_ashrrev_i32_e32 v165, 31, v158
	v_or_b32_e32 v164, 0x80000000, v164
	v_or_b32_e32 v165, 0x80000000, v165
	v_xor_b32_e32 v164, v156, v164
	v_mfma_f32_16x16x32_bf16 v[98:101], v[6:9], v[50:53], v[98:101]
	v_xor_b32_e32 v165, v158, v165
	v_and_b32_e32 v164, 0xffffff00, v164
	v_and_b32_e32 v165, 0xffffff00, v165
	v_cmp_ge_i32_e32 vcc, s5, v242
	v_mfma_f32_16x16x32_bf16 v[102:105], v[6:9], v[54:57], v[102:105]
	s_nop 1
	v_cndmask_b32_e32 v235, 0, v164, vcc
	v_cmp_ge_i32_e32 vcc, s67, v242
	s_nop 1
	v_cndmask_b32_e32 v165, 0, v165, vcc
	global_store_dword v168, v165, s[14:15] offset:1792
	ds_read_b128 v[26:29], v166 offset:16384
	ds_read_b128 v[30:33], v166 offset:18432
	ds_read_b128 v[34:37], v166 offset:20480
	ds_read_b128 v[38:41], v166 offset:22528
	ds_read_b128 v[42:45], v167 offset:16384
	ds_read_b128 v[46:49], v167 offset:18432
	ds_read_b128 v[50:53], v167 offset:20480
	ds_read_b128 v[54:57], v167 offset:22528
	s_waitcnt lgkmcnt(8)
	v_mfma_f32_16x16x32_bf16 v[106:109], v[10:13], v[58:61], 0
	s_sub_i32 s5, s57, 1536
	s_add_i32 s67, s5, 1
	v_med3_f32 v90, v90, 0, v240
	v_med3_f32 v91, v91, 0, v240
	v_med3_f32 v92, v92, 0, v240
	v_med3_f32 v93, v93, 0, v240
	v_mul_f32_e32 v160, v2, v90
	v_mul_f32_e32 v161, v3, v91
	v_mfma_f32_16x16x32_bf16 v[110:113], v[10:13], v[62:65], 0
	v_mul_f32_e32 v162, v4, v92
	v_mul_f32_e32 v163, v5, v93
	v_add_f32_e32 v156, v160, v161
	v_add_f32_e32 v156, v162, v156
	v_add_f32_e32 v156, v163, v156
	v_med3_f32 v94, v94, 0, v240
	v_med3_f32 v95, v95, 0, v240
	v_med3_f32 v96, v96, 0, v240
	v_mfma_f32_16x16x32_bf16 v[114:117], v[10:13], v[66:69], 0
	v_med3_f32 v97, v97, 0, v240
	v_mul_f32_e32 v160, v2, v94
	v_mul_f32_e32 v161, v3, v95
	v_mul_f32_e32 v162, v4, v96
	v_mul_f32_e32 v163, v5, v97
	v_add_f32_e32 v157, v160, v161
	v_add_f32_e32 v157, v162, v157
	v_add_f32_e32 v157, v163, v157
	v_mfma_f32_16x16x32_bf16 v[118:121], v[10:13], v[70:73], 0
	v_med3_f32 v98, v98, 0, v240
	v_med3_f32 v99, v99, 0, v240
	v_med3_f32 v100, v100, 0, v240
	v_med3_f32 v101, v101, 0, v240
	v_mul_f32_e32 v160, v2, v98
	v_mul_f32_e32 v161, v3, v99
	v_mul_f32_e32 v162, v4, v100
	v_mul_f32_e32 v163, v5, v101
	v_mfma_f32_16x16x32_bf16 v[106:109], v[6:9], v[74:77], v[106:109]
	v_add_f32_e32 v158, v160, v161
	v_add_f32_e32 v158, v162, v158
	v_add_f32_e32 v158, v163, v158
	v_med3_f32 v102, v102, 0, v240
	v_med3_f32 v103, v103, 0, v240
	v_med3_f32 v104, v104, 0, v240
	v_med3_f32 v105, v105, 0, v240
	v_mul_f32_e32 v160, v2, v102
	v_mfma_f32_16x16x32_bf16 v[110:113], v[6:9], v[78:81], v[110:113]
	v_mul_f32_e32 v161, v3, v103
	v_mul_f32_e32 v162, v4, v104
	v_mul_f32_e32 v163, v5, v105
	v_add_f32_e32 v159, v160, v161
	v_add_f32_e32 v159, v162, v159
	v_add_f32_e32 v159, v163, v159
	s_nop 1
	v_permlane16_swap_b32_e32 v156, v157
	v_mfma_f32_16x16x32_bf16 v[114:117], v[6:9], v[82:85], v[114:117]
	v_permlane16_swap_b32_e32 v158, v159
	v_add_f32_e32 v156, v156, v157
	v_add_f32_e32 v158, v158, v159
	s_nop 1
	v_permlane32_swap_b32_e32 v156, v158
	v_ashrrev_i32_e32 v164, 31, v156
	v_ashrrev_i32_e32 v165, 31, v158
	v_or_b32_e32 v164, 0x80000000, v164
	v_mfma_f32_16x16x32_bf16 v[118:121], v[6:9], v[86:89], v[118:121]
	v_or_b32_e32 v165, 0x80000000, v165
	v_xor_b32_e32 v164, v156, v164
	v_xor_b32_e32 v165, v158, v165
	v_and_b32_e32 v164, 0xffffff00, v164
	v_and_b32_e32 v165, 0xffffff00, v165
	v_cmp_ge_i32_e32 vcc, s5, v242
	s_nop 1
	v_cndmask_b32_e32 v236, 0, v164, vcc
	v_cmp_ge_i32_e32 vcc, s67, v242
	s_nop 1
	v_cndmask_b32_e32 v165, 0, v165, vcc
	global_store_dword v168, v165, s[14:15] offset:2048
	ds_read_b128 v[58:61], v166 offset:24576
	ds_read_b128 v[62:65], v166 offset:26624
	ds_read_b128 v[66:69], v166 offset:28672
	ds_read_b128 v[70:73], v166 offset:30720
	ds_read_b128 v[74:77], v167 offset:24576
	ds_read_b128 v[78:81], v167 offset:26624
	ds_read_b128 v[82:85], v167 offset:28672
	ds_read_b128 v[86:89], v167 offset:30720
	s_waitcnt lgkmcnt(8)
	v_mfma_f32_16x16x32_bf16 v[90:93], v[10:13], v[26:29], 0
	s_sub_i32 s5, s57, 1600
	s_add_i32 s67, s5, 1
	v_med3_f32 v106, v106, 0, v240
	v_med3_f32 v107, v107, 0, v240
	v_med3_f32 v108, v108, 0, v240
	v_med3_f32 v109, v109, 0, v240
	v_mul_f32_e32 v160, v2, v106
	v_mul_f32_e32 v161, v3, v107
	v_mfma_f32_16x16x32_bf16 v[94:97], v[10:13], v[30:33], 0
	v_mul_f32_e32 v162, v4, v108
	v_mul_f32_e32 v163, v5, v109
	v_add_f32_e32 v156, v160, v161
	v_add_f32_e32 v156, v162, v156
	v_add_f32_e32 v156, v163, v156
	v_med3_f32 v110, v110, 0, v240
	v_med3_f32 v111, v111, 0, v240
	v_med3_f32 v112, v112, 0, v240
	v_mfma_f32_16x16x32_bf16 v[98:101], v[10:13], v[34:37], 0
	v_med3_f32 v113, v113, 0, v240
	v_mul_f32_e32 v160, v2, v110
	v_mul_f32_e32 v161, v3, v111
	v_mul_f32_e32 v162, v4, v112
	v_mul_f32_e32 v163, v5, v113
	v_add_f32_e32 v157, v160, v161
	v_add_f32_e32 v157, v162, v157
	v_add_f32_e32 v157, v163, v157
	v_mfma_f32_16x16x32_bf16 v[102:105], v[10:13], v[38:41], 0
	v_med3_f32 v114, v114, 0, v240
	v_med3_f32 v115, v115, 0, v240
	v_med3_f32 v116, v116, 0, v240
	v_med3_f32 v117, v117, 0, v240
	v_mul_f32_e32 v160, v2, v114
	v_mul_f32_e32 v161, v3, v115
	v_mul_f32_e32 v162, v4, v116
	v_mul_f32_e32 v163, v5, v117
	v_mfma_f32_16x16x32_bf16 v[90:93], v[6:9], v[42:45], v[90:93]
	v_add_f32_e32 v158, v160, v161
	v_add_f32_e32 v158, v162, v158
	v_add_f32_e32 v158, v163, v158
	v_med3_f32 v118, v118, 0, v240
	v_med3_f32 v119, v119, 0, v240
	v_med3_f32 v120, v120, 0, v240
	v_med3_f32 v121, v121, 0, v240
	v_mul_f32_e32 v160, v2, v118
	v_mfma_f32_16x16x32_bf16 v[94:97], v[6:9], v[46:49], v[94:97]
	v_mul_f32_e32 v161, v3, v119
	v_mul_f32_e32 v162, v4, v120
	v_mul_f32_e32 v163, v5, v121
	v_add_f32_e32 v159, v160, v161
	v_add_f32_e32 v159, v162, v159
	v_add_f32_e32 v159, v163, v159
	s_nop 1
	v_permlane16_swap_b32_e32 v156, v157
	v_mfma_f32_16x16x32_bf16 v[98:101], v[6:9], v[50:53], v[98:101]
	v_permlane16_swap_b32_e32 v158, v159
	v_add_f32_e32 v156, v156, v157
	v_add_f32_e32 v158, v158, v159
	s_nop 1
	v_permlane32_swap_b32_e32 v156, v158
	v_ashrrev_i32_e32 v164, 31, v156
	v_ashrrev_i32_e32 v165, 31, v158
	v_or_b32_e32 v164, 0x80000000, v164
	v_mfma_f32_16x16x32_bf16 v[102:105], v[6:9], v[54:57], v[102:105]
	v_or_b32_e32 v165, 0x80000000, v165
	v_xor_b32_e32 v164, v156, v164
	v_xor_b32_e32 v165, v158, v165
	v_and_b32_e32 v164, 0xffffff00, v164
	v_and_b32_e32 v165, 0xffffff00, v165
	v_cmp_ge_i32_e32 vcc, s5, v242
	s_nop 1
	v_cndmask_b32_e32 v237, 0, v164, vcc
	v_cmp_ge_i32_e32 vcc, s67, v242
	s_nop 1
	v_cndmask_b32_e32 v165, 0, v165, vcc
	global_store_dword v168, v165, s[14:15] offset:2304
	s_waitcnt lgkmcnt(0)
	v_mfma_f32_16x16x32_bf16 v[106:109], v[10:13], v[58:61], 0
	s_sub_i32 s5, s57, 1664
	s_add_i32 s67, s5, 1
	v_med3_f32 v90, v90, 0, v240
	v_med3_f32 v91, v91, 0, v240
	v_med3_f32 v92, v92, 0, v240
	v_med3_f32 v93, v93, 0, v240
	v_mul_f32_e32 v160, v2, v90
	v_mul_f32_e32 v161, v3, v91
	v_mfma_f32_16x16x32_bf16 v[110:113], v[10:13], v[62:65], 0
	v_mul_f32_e32 v162, v4, v92
	v_mul_f32_e32 v163, v5, v93
	v_add_f32_e32 v156, v160, v161
	v_add_f32_e32 v156, v162, v156
	v_add_f32_e32 v156, v163, v156
	v_med3_f32 v94, v94, 0, v240
	v_med3_f32 v95, v95, 0, v240
	v_med3_f32 v96, v96, 0, v240
	v_mfma_f32_16x16x32_bf16 v[114:117], v[10:13], v[66:69], 0
	v_med3_f32 v97, v97, 0, v240
	v_mul_f32_e32 v160, v2, v94
	v_mul_f32_e32 v161, v3, v95
	v_mul_f32_e32 v162, v4, v96
	v_mul_f32_e32 v163, v5, v97
	v_add_f32_e32 v157, v160, v161
	v_add_f32_e32 v157, v162, v157
	v_add_f32_e32 v157, v163, v157
	v_mfma_f32_16x16x32_bf16 v[118:121], v[10:13], v[70:73], 0
	v_med3_f32 v98, v98, 0, v240
	v_med3_f32 v99, v99, 0, v240
	v_med3_f32 v100, v100, 0, v240
	v_med3_f32 v101, v101, 0, v240
	v_mul_f32_e32 v160, v2, v98
	v_mul_f32_e32 v161, v3, v99
	v_mul_f32_e32 v162, v4, v100
	v_mul_f32_e32 v163, v5, v101
	v_mfma_f32_16x16x32_bf16 v[106:109], v[6:9], v[74:77], v[106:109]
	v_add_f32_e32 v158, v160, v161
	v_add_f32_e32 v158, v162, v158
	v_add_f32_e32 v158, v163, v158
	v_med3_f32 v102, v102, 0, v240
	v_med3_f32 v103, v103, 0, v240
	v_med3_f32 v104, v104, 0, v240
	v_med3_f32 v105, v105, 0, v240
	v_mul_f32_e32 v160, v2, v102
	v_mfma_f32_16x16x32_bf16 v[110:113], v[6:9], v[78:81], v[110:113]
	v_mul_f32_e32 v161, v3, v103
	v_mul_f32_e32 v162, v4, v104
	v_mul_f32_e32 v163, v5, v105
	v_add_f32_e32 v159, v160, v161
	v_add_f32_e32 v159, v162, v159
	v_add_f32_e32 v159, v163, v159
	s_nop 1
	v_permlane16_swap_b32_e32 v156, v157
	v_mfma_f32_16x16x32_bf16 v[114:117], v[6:9], v[82:85], v[114:117]
	v_permlane16_swap_b32_e32 v158, v159
	v_add_f32_e32 v156, v156, v157
	v_add_f32_e32 v158, v158, v159
	s_nop 1
	v_permlane32_swap_b32_e32 v156, v158
	v_ashrrev_i32_e32 v164, 31, v156
	v_ashrrev_i32_e32 v165, 31, v158
	v_or_b32_e32 v164, 0x80000000, v164
	v_mfma_f32_16x16x32_bf16 v[118:121], v[6:9], v[86:89], v[118:121]
	v_or_b32_e32 v165, 0x80000000, v165
	v_xor_b32_e32 v164, v156, v164
	v_xor_b32_e32 v165, v158, v165
	v_and_b32_e32 v164, 0xffffff00, v164
	v_and_b32_e32 v165, 0xffffff00, v165
	v_cmp_ge_i32_e32 vcc, s5, v242
	s_nop 1
	v_cndmask_b32_e32 v244, 0, v164, vcc
	v_cmp_ge_i32_e32 vcc, s67, v242
	s_nop 1
	v_cndmask_b32_e32 v165, 0, v165, vcc
	global_store_dword v168, v165, s[14:15] offset:2560
.Lsc_h7:
	s_cmp_le_u32 s4, 7
	s_cbranch_scc1 .Lsc_drain7
	s_cmp_gt_u32 s4, 9
	s_cbranch_scc0 .Lsc_ni7
	v_lshl_add_u64 v[170:171], s[48:49], 0, v[0:1]
	s_add_i32 m0, s1, 0x8000
	s_nop 0
	global_load_lds_dwordx4 v[170:171], off
	v_lshl_add_u64 v[170:171], s[48:49], 0, v[18:19]
	s_add_i32 m0, s1, 0xa000
	s_nop 0
	global_load_lds_dwordx4 v[170:171], off
	v_lshl_add_u64 v[170:171], s[48:49], 0, v[20:21]
	s_add_i32 m0, s1, 0xc000
	s_nop 0
	global_load_lds_dwordx4 v[170:171], off
	v_lshl_add_u64 v[170:171], s[48:49], 0, v[22:23]
	s_add_i32 m0, s1, 0xe000
	s_nop 0
	global_load_lds_dwordx4 v[170:171], off
	s_add_u32 s48, s48, 0x8000
	s_addc_u32 s49, s49, 0
	s_waitcnt vmcnt(8)
	s_branch .Lsc_b7
.Lsc_ni7:
	s_cmp_gt_u32 s4, 8
	s_cbranch_scc0 .Lsc_w07
	s_waitcnt vmcnt(4)
	s_branch .Lsc_b7

.Lsc_b7:
	s_barrier
	ds_read_b128 v[26:29], v166 offset:32768
	ds_read_b128 v[30:33], v166 offset:34816
	ds_read_b128 v[34:37], v166 offset:36864
	ds_read_b128 v[38:41], v166 offset:38912
	ds_read_b128 v[42:45], v167 offset:32768
	ds_read_b128 v[46:49], v167 offset:34816
	ds_read_b128 v[50:53], v167 offset:36864
	ds_read_b128 v[54:57], v167 offset:38912
	ds_read_b128 v[58:61], v166 offset:40960
	ds_read_b128 v[62:65], v166 offset:43008
	ds_read_b128 v[66:69], v166 offset:45056
	ds_read_b128 v[70:73], v166 offset:47104
	ds_read_b128 v[74:77], v167 offset:40960
	ds_read_b128 v[78:81], v167 offset:43008
	ds_read_b128 v[82:85], v167 offset:45056
	ds_read_b128 v[86:89], v167 offset:47104
	s_sub_i32 s5, s57, 1728
	s_add_i32 s67, s5, 1
	v_med3_f32 v106, v106, 0, v240
	v_med3_f32 v107, v107, 0, v240
	v_med3_f32 v108, v108, 0, v240
	v_med3_f32 v109, v109, 0, v240
	v_mul_f32_e32 v160, v2, v106
	v_mul_f32_e32 v161, v3, v107
	v_mul_f32_e32 v162, v4, v108
	v_mul_f32_e32 v163, v5, v109
	v_add_f32_e32 v156, v160, v161
	v_add_f32_e32 v156, v162, v156
	v_add_f32_e32 v156, v163, v156
	v_med3_f32 v110, v110, 0, v240
	v_med3_f32 v111, v111, 0, v240
	v_med3_f32 v112, v112, 0, v240
	v_med3_f32 v113, v113, 0, v240
	v_mul_f32_e32 v160, v2, v110
	v_mul_f32_e32 v161, v3, v111
	v_mul_f32_e32 v162, v4, v112
	v_mul_f32_e32 v163, v5, v113
	v_add_f32_e32 v157, v160, v161
	v_add_f32_e32 v157, v162, v157
	v_add_f32_e32 v157, v163, v157
	v_med3_f32 v114, v114, 0, v240
	v_med3_f32 v115, v115, 0, v240
	v_med3_f32 v116, v116, 0, v240
	v_med3_f32 v117, v117, 0, v240
	v_mul_f32_e32 v160, v2, v114
	v_mul_f32_e32 v161, v3, v115
	v_mul_f32_e32 v162, v4, v116
	v_mul_f32_e32 v163, v5, v117
	v_add_f32_e32 v158, v160, v161
	v_add_f32_e32 v158, v162, v158
	s_waitcnt lgkmcnt(8)
	v_mfma_f32_16x16x32_bf16 v[90:93], v[10:13], v[26:29], 0
	v_add_f32_e32 v158, v163, v158
	v_med3_f32 v118, v118, 0, v240
	v_med3_f32 v119, v119, 0, v240
	v_med3_f32 v120, v120, 0, v240
	v_mfma_f32_16x16x32_bf16 v[94:97], v[10:13], v[30:33], 0
	v_med3_f32 v121, v121, 0, v240
	v_mul_f32_e32 v160, v2, v118
	v_mul_f32_e32 v161, v3, v119
	v_mul_f32_e32 v162, v4, v120
	v_mfma_f32_16x16x32_bf16 v[98:101], v[10:13], v[34:37], 0
	v_mul_f32_e32 v163, v5, v121
	v_add_f32_e32 v159, v160, v161
	v_add_f32_e32 v159, v162, v159
	v_add_f32_e32 v159, v163, v159
	v_mfma_f32_16x16x32_bf16 v[102:105], v[10:13], v[38:41], 0
	s_nop 1
	v_permlane16_swap_b32_e32 v156, v157
	v_permlane16_swap_b32_e32 v158, v159
	v_add_f32_e32 v156, v156, v157
	v_mfma_f32_16x16x32_bf16 v[90:93], v[6:9], v[42:45], v[90:93]
	v_add_f32_e32 v158, v158, v159
	s_nop 1
	v_permlane32_swap_b32_e32 v156, v158
	v_ashrrev_i32_e32 v164, 31, v156
	v_mfma_f32_16x16x32_bf16 v[94:97], v[6:9], v[46:49], v[94:97]
	v_ashrrev_i32_e32 v165, 31, v158
	v_or_b32_e32 v164, 0x80000000, v164
	v_or_b32_e32 v165, 0x80000000, v165
	v_xor_b32_e32 v164, v156, v164
	v_mfma_f32_16x16x32_bf16 v[98:101], v[6:9], v[50:53], v[98:101]
	v_xor_b32_e32 v165, v158, v165
	v_and_b32_e32 v164, 0xffffff00, v164
	v_and_b32_e32 v165, 0xffffff00, v165
	v_cmp_ge_i32_e32 vcc, s5, v242
	v_mfma_f32_16x16x32_bf16 v[102:105], v[6:9], v[54:57], v[102:105]
	s_nop 1
	v_cndmask_b32_e32 v245, 0, v164, vcc
	v_cmp_ge_i32_e32 vcc, s67, v242
	s_nop 1
	v_cndmask_b32_e32 v165, 0, v165, vcc
	global_store_dword v168, v165, s[14:15] offset:2816
	ds_read_b128 v[26:29], v166 offset:49152
	ds_read_b128 v[30:33], v166 offset:51200
	ds_read_b128 v[34:37], v166 offset:53248
	ds_read_b128 v[38:41], v166 offset:55296
	ds_read_b128 v[42:45], v167 offset:49152
	ds_read_b128 v[46:49], v167 offset:51200
	ds_read_b128 v[50:53], v167 offset:53248
	ds_read_b128 v[54:57], v167 offset:55296
	s_waitcnt lgkmcnt(8)
	v_mfma_f32_16x16x32_bf16 v[106:109], v[10:13], v[58:61], 0
	s_sub_i32 s5, s57, 1792
	s_add_i32 s67, s5, 1
	v_med3_f32 v90, v90, 0, v240
	v_med3_f32 v91, v91, 0, v240
	v_med3_f32 v92, v92, 0, v240
	v_med3_f32 v93, v93, 0, v240
	v_mul_f32_e32 v160, v2, v90
	v_mul_f32_e32 v161, v3, v91
	v_mfma_f32_16x16x32_bf16 v[110:113], v[10:13], v[62:65], 0
	v_mul_f32_e32 v162, v4, v92
	v_mul_f32_e32 v163, v5, v93
	v_add_f32_e32 v156, v160, v161
	v_add_f32_e32 v156, v162, v156
	v_add_f32_e32 v156, v163, v156
	v_med3_f32 v94, v94, 0, v240
	v_med3_f32 v95, v95, 0, v240
	v_med3_f32 v96, v96, 0, v240
	v_mfma_f32_16x16x32_bf16 v[114:117], v[10:13], v[66:69], 0
	v_med3_f32 v97, v97, 0, v240
	v_mul_f32_e32 v160, v2, v94
	v_mul_f32_e32 v161, v3, v95
	v_mul_f32_e32 v162, v4, v96
	v_mul_f32_e32 v163, v5, v97
	v_add_f32_e32 v157, v160, v161
	v_add_f32_e32 v157, v162, v157
	v_add_f32_e32 v157, v163, v157
	v_mfma_f32_16x16x32_bf16 v[118:121], v[10:13], v[70:73], 0
	v_med3_f32 v98, v98, 0, v240
	v_med3_f32 v99, v99, 0, v240
	v_med3_f32 v100, v100, 0, v240
	v_med3_f32 v101, v101, 0, v240
	v_mul_f32_e32 v160, v2, v98
	v_mul_f32_e32 v161, v3, v99
	v_mul_f32_e32 v162, v4, v100
	v_mul_f32_e32 v163, v5, v101
	v_mfma_f32_16x16x32_bf16 v[106:109], v[6:9], v[74:77], v[106:109]
	v_add_f32_e32 v158, v160, v161
	v_add_f32_e32 v158, v162, v158
	v_add_f32_e32 v158, v163, v158
	v_med3_f32 v102, v102, 0, v240
	v_med3_f32 v103, v103, 0, v240
	v_med3_f32 v104, v104, 0, v240
	v_med3_f32 v105, v105, 0, v240
	v_mul_f32_e32 v160, v2, v102
	v_mfma_f32_16x16x32_bf16 v[110:113], v[6:9], v[78:81], v[110:113]
	v_mul_f32_e32 v161, v3, v103
	v_mul_f32_e32 v162, v4, v104
	v_mul_f32_e32 v163, v5, v105
	v_add_f32_e32 v159, v160, v161
	v_add_f32_e32 v159, v162, v159
	v_add_f32_e32 v159, v163, v159
	s_nop 1
	v_permlane16_swap_b32_e32 v156, v157
	v_mfma_f32_16x16x32_bf16 v[114:117], v[6:9], v[82:85], v[114:117]
	v_permlane16_swap_b32_e32 v158, v159
	v_add_f32_e32 v156, v156, v157
	v_add_f32_e32 v158, v158, v159
	s_nop 1
	v_permlane32_swap_b32_e32 v156, v158
	v_ashrrev_i32_e32 v164, 31, v156
	v_ashrrev_i32_e32 v165, 31, v158
	v_or_b32_e32 v164, 0x80000000, v164
	v_mfma_f32_16x16x32_bf16 v[118:121], v[6:9], v[86:89], v[118:121]
	v_or_b32_e32 v165, 0x80000000, v165
	v_xor_b32_e32 v164, v156, v164
	v_xor_b32_e32 v165, v158, v165
	v_and_b32_e32 v164, 0xffffff00, v164
	v_and_b32_e32 v165, 0xffffff00, v165
	v_cmp_ge_i32_e32 vcc, s5, v242
	s_nop 1
	v_cndmask_b32_e32 v246, 0, v164, vcc
	v_cmp_ge_i32_e32 vcc, s67, v242
	s_nop 1
	v_cndmask_b32_e32 v165, 0, v165, vcc
	global_store_dword v168, v165, s[14:15] offset:3072
	ds_read_b128 v[58:61], v166 offset:57344
	ds_read_b128 v[62:65], v166 offset:59392
	ds_read_b128 v[66:69], v166 offset:61440
	ds_read_b128 v[70:73], v166 offset:63488
	ds_read_b128 v[74:77], v167 offset:57344
	ds_read_b128 v[78:81], v167 offset:59392
	ds_read_b128 v[82:85], v167 offset:61440
	ds_read_b128 v[86:89], v167 offset:63488
	s_waitcnt lgkmcnt(8)
	v_mfma_f32_16x16x32_bf16 v[90:93], v[10:13], v[26:29], 0
	s_sub_i32 s5, s57, 1856
	s_add_i32 s67, s5, 1
	v_med3_f32 v106, v106, 0, v240
	v_med3_f32 v107, v107, 0, v240
	v_med3_f32 v108, v108, 0, v240
	v_med3_f32 v109, v109, 0, v240
	v_mul_f32_e32 v160, v2, v106
	v_mul_f32_e32 v161, v3, v107
	v_mfma_f32_16x16x32_bf16 v[94:97], v[10:13], v[30:33], 0
	v_mul_f32_e32 v162, v4, v108
	v_mul_f32_e32 v163, v5, v109
	v_add_f32_e32 v156, v160, v161
	v_add_f32_e32 v156, v162, v156
	v_add_f32_e32 v156, v163, v156
	v_med3_f32 v110, v110, 0, v240
	v_med3_f32 v111, v111, 0, v240
	v_med3_f32 v112, v112, 0, v240
	v_mfma_f32_16x16x32_bf16 v[98:101], v[10:13], v[34:37], 0
	v_med3_f32 v113, v113, 0, v240
	v_mul_f32_e32 v160, v2, v110
	v_mul_f32_e32 v161, v3, v111
	v_mul_f32_e32 v162, v4, v112
	v_mul_f32_e32 v163, v5, v113
	v_add_f32_e32 v157, v160, v161
	v_add_f32_e32 v157, v162, v157
	v_add_f32_e32 v157, v163, v157
	v_mfma_f32_16x16x32_bf16 v[102:105], v[10:13], v[38:41], 0
	v_med3_f32 v114, v114, 0, v240
	v_med3_f32 v115, v115, 0, v240
	v_med3_f32 v116, v116, 0, v240
	v_med3_f32 v117, v117, 0, v240
	v_mul_f32_e32 v160, v2, v114
	v_mul_f32_e32 v161, v3, v115
	v_mul_f32_e32 v162, v4, v116
	v_mul_f32_e32 v163, v5, v117
	v_mfma_f32_16x16x32_bf16 v[90:93], v[6:9], v[42:45], v[90:93]
	v_add_f32_e32 v158, v160, v161
	v_add_f32_e32 v158, v162, v158
	v_add_f32_e32 v158, v163, v158
	v_med3_f32 v118, v118, 0, v240
	v_med3_f32 v119, v119, 0, v240
	v_med3_f32 v120, v120, 0, v240
	v_med3_f32 v121, v121, 0, v240
	v_mul_f32_e32 v160, v2, v118
	v_mfma_f32_16x16x32_bf16 v[94:97], v[6:9], v[46:49], v[94:97]
	v_mul_f32_e32 v161, v3, v119
	v_mul_f32_e32 v162, v4, v120
	v_mul_f32_e32 v163, v5, v121
	v_add_f32_e32 v159, v160, v161
	v_add_f32_e32 v159, v162, v159
	v_add_f32_e32 v159, v163, v159
	s_nop 1
	v_permlane16_swap_b32_e32 v156, v157
	v_mfma_f32_16x16x32_bf16 v[98:101], v[6:9], v[50:53], v[98:101]
	v_permlane16_swap_b32_e32 v158, v159
	v_add_f32_e32 v156, v156, v157
	v_add_f32_e32 v158, v158, v159
	s_nop 1
	v_permlane32_swap_b32_e32 v156, v158
	v_ashrrev_i32_e32 v164, 31, v156
	v_ashrrev_i32_e32 v165, 31, v158
	v_or_b32_e32 v164, 0x80000000, v164
	v_mfma_f32_16x16x32_bf16 v[102:105], v[6:9], v[54:57], v[102:105]
	v_or_b32_e32 v165, 0x80000000, v165
	v_xor_b32_e32 v164, v156, v164
	v_xor_b32_e32 v165, v158, v165
	v_and_b32_e32 v164, 0xffffff00, v164
	v_and_b32_e32 v165, 0xffffff00, v165
	v_cmp_ge_i32_e32 vcc, s5, v242
	s_nop 1
	v_cndmask_b32_e32 v247, 0, v164, vcc
	v_cmp_ge_i32_e32 vcc, s67, v242
	s_nop 1
	v_cndmask_b32_e32 v165, 0, v165, vcc
	global_store_dword v168, v165, s[14:15] offset:3328
	s_waitcnt lgkmcnt(0)
	v_mfma_f32_16x16x32_bf16 v[106:109], v[10:13], v[58:61], 0
	s_sub_i32 s5, s57, 1920
	s_add_i32 s67, s5, 1
	v_med3_f32 v90, v90, 0, v240
	v_med3_f32 v91, v91, 0, v240
	v_med3_f32 v92, v92, 0, v240
	v_med3_f32 v93, v93, 0, v240
	v_mul_f32_e32 v160, v2, v90
	v_mul_f32_e32 v161, v3, v91
	v_mfma_f32_16x16x32_bf16 v[110:113], v[10:13], v[62:65], 0
	v_mul_f32_e32 v162, v4, v92
	v_mul_f32_e32 v163, v5, v93
	v_add_f32_e32 v156, v160, v161
	v_add_f32_e32 v156, v162, v156
	v_add_f32_e32 v156, v163, v156
	v_med3_f32 v94, v94, 0, v240
	v_med3_f32 v95, v95, 0, v240
	v_med3_f32 v96, v96, 0, v240
	v_mfma_f32_16x16x32_bf16 v[114:117], v[10:13], v[66:69], 0
	v_med3_f32 v97, v97, 0, v240
	v_mul_f32_e32 v160, v2, v94
	v_mul_f32_e32 v161, v3, v95
	v_mul_f32_e32 v162, v4, v96
	v_mul_f32_e32 v163, v5, v97
	v_add_f32_e32 v157, v160, v161
	v_add_f32_e32 v157, v162, v157
	v_add_f32_e32 v157, v163, v157
	v_mfma_f32_16x16x32_bf16 v[118:121], v[10:13], v[70:73], 0
	v_med3_f32 v98, v98, 0, v240
	v_med3_f32 v99, v99, 0, v240
	v_med3_f32 v100, v100, 0, v240
	v_med3_f32 v101, v101, 0, v240
	v_mul_f32_e32 v160, v2, v98
	v_mul_f32_e32 v161, v3, v99
	v_mul_f32_e32 v162, v4, v100
	v_mul_f32_e32 v163, v5, v101
	v_mfma_f32_16x16x32_bf16 v[106:109], v[6:9], v[74:77], v[106:109]
	v_add_f32_e32 v158, v160, v161
	v_add_f32_e32 v158, v162, v158
	v_add_f32_e32 v158, v163, v158
	v_med3_f32 v102, v102, 0, v240
	v_med3_f32 v103, v103, 0, v240
	v_med3_f32 v104, v104, 0, v240
	v_med3_f32 v105, v105, 0, v240
	v_mul_f32_e32 v160, v2, v102
	v_mfma_f32_16x16x32_bf16 v[110:113], v[6:9], v[78:81], v[110:113]
	v_mul_f32_e32 v161, v3, v103
	v_mul_f32_e32 v162, v4, v104
	v_mul_f32_e32 v163, v5, v105
	v_add_f32_e32 v159, v160, v161
	v_add_f32_e32 v159, v162, v159
	v_add_f32_e32 v159, v163, v159
	s_nop 1
	v_permlane16_swap_b32_e32 v156, v157
	v_mfma_f32_16x16x32_bf16 v[114:117], v[6:9], v[82:85], v[114:117]
	v_permlane16_swap_b32_e32 v158, v159
	v_add_f32_e32 v156, v156, v157
	v_add_f32_e32 v158, v158, v159
	s_nop 1
	v_permlane32_swap_b32_e32 v156, v158
	v_ashrrev_i32_e32 v164, 31, v156
	v_ashrrev_i32_e32 v165, 31, v158
	v_or_b32_e32 v164, 0x80000000, v164
	v_mfma_f32_16x16x32_bf16 v[118:121], v[6:9], v[86:89], v[118:121]
	v_or_b32_e32 v165, 0x80000000, v165
	v_xor_b32_e32 v164, v156, v164
	v_xor_b32_e32 v165, v158, v165
	v_and_b32_e32 v164, 0xffffff00, v164
	v_and_b32_e32 v165, 0xffffff00, v165
	v_cmp_ge_i32_e32 vcc, s5, v242
	s_nop 1
	v_cndmask_b32_e32 v248, 0, v164, vcc
	v_cmp_ge_i32_e32 vcc, s67, v242
	s_nop 1
	v_cndmask_b32_e32 v165, 0, v165, vcc
	global_store_dword v168, v165, s[14:15] offset:3584
.Lsc_h8:
	s_cmp_le_u32 s4, 8
	s_cbranch_scc1 .Lsc_drain8
	s_cmp_gt_u32 s4, 10
	s_cbranch_scc0 .Lsc_ni8
	v_lshl_add_u64 v[170:171], s[48:49], 0, v[0:1]
	s_add_i32 m0, s1, 0x10000
	s_nop 0
	global_load_lds_dwordx4 v[170:171], off
	v_lshl_add_u64 v[170:171], s[48:49], 0, v[18:19]
	s_add_i32 m0, s1, 0x12000
	s_nop 0
	global_load_lds_dwordx4 v[170:171], off
	v_lshl_add_u64 v[170:171], s[48:49], 0, v[20:21]
	s_add_i32 m0, s1, 0x14000
	s_nop 0
	global_load_lds_dwordx4 v[170:171], off
	v_lshl_add_u64 v[170:171], s[48:49], 0, v[22:23]
	s_add_i32 m0, s1, 0x16000
	s_nop 0
	global_load_lds_dwordx4 v[170:171], off
	s_add_u32 s48, s48, 0x8000
	s_addc_u32 s49, s49, 0
	s_waitcnt vmcnt(8)
	s_branch .Lsc_b8
.Lsc_ni8:
	s_cmp_gt_u32 s4, 9
	s_cbranch_scc0 .Lsc_w08
	s_waitcnt vmcnt(4)
	s_branch .Lsc_b8

.Lsc_b8:
	s_barrier
	ds_read_b128 v[26:29], v124
	ds_read_b128 v[30:33], v124 offset:2048
	ds_read_b128 v[34:37], v124 offset:4096
	ds_read_b128 v[38:41], v124 offset:6144
	ds_read_b128 v[42:45], v125
	ds_read_b128 v[46:49], v125 offset:2048
	ds_read_b128 v[50:53], v125 offset:4096
	ds_read_b128 v[54:57], v125 offset:6144
	ds_read_b128 v[58:61], v124 offset:8192
	ds_read_b128 v[62:65], v124 offset:10240
	ds_read_b128 v[66:69], v124 offset:12288
	ds_read_b128 v[70:73], v124 offset:14336
	ds_read_b128 v[74:77], v125 offset:8192
	ds_read_b128 v[78:81], v125 offset:10240
	ds_read_b128 v[82:85], v125 offset:12288
	ds_read_b128 v[86:89], v125 offset:14336
	s_sub_i32 s5, s57, 1984
	s_add_i32 s67, s5, 1
	v_med3_f32 v106, v106, 0, v240
	v_med3_f32 v107, v107, 0, v240
	v_med3_f32 v108, v108, 0, v240
	v_med3_f32 v109, v109, 0, v240
	v_mul_f32_e32 v160, v2, v106
	v_mul_f32_e32 v161, v3, v107
	v_mul_f32_e32 v162, v4, v108
	v_mul_f32_e32 v163, v5, v109
	v_add_f32_e32 v156, v160, v161
	v_add_f32_e32 v156, v162, v156
	v_add_f32_e32 v156, v163, v156
	v_med3_f32 v110, v110, 0, v240
	v_med3_f32 v111, v111, 0, v240
	v_med3_f32 v112, v112, 0, v240
	v_med3_f32 v113, v113, 0, v240
	v_mul_f32_e32 v160, v2, v110
	v_mul_f32_e32 v161, v3, v111
	v_mul_f32_e32 v162, v4, v112
	v_mul_f32_e32 v163, v5, v113
	v_add_f32_e32 v157, v160, v161
	v_add_f32_e32 v157, v162, v157
	v_add_f32_e32 v157, v163, v157
	v_med3_f32 v114, v114, 0, v240
	v_med3_f32 v115, v115, 0, v240
	v_med3_f32 v116, v116, 0, v240
	v_med3_f32 v117, v117, 0, v240
	v_mul_f32_e32 v160, v2, v114
	v_mul_f32_e32 v161, v3, v115
	v_mul_f32_e32 v162, v4, v116
	v_mul_f32_e32 v163, v5, v117
	v_add_f32_e32 v158, v160, v161
	v_add_f32_e32 v158, v162, v158
	s_waitcnt lgkmcnt(8)
	v_mfma_f32_16x16x32_bf16 v[90:93], v[10:13], v[26:29], 0
	v_add_f32_e32 v158, v163, v158
	v_med3_f32 v118, v118, 0, v240
	v_med3_f32 v119, v119, 0, v240
	v_med3_f32 v120, v120, 0, v240
	v_mfma_f32_16x16x32_bf16 v[94:97], v[10:13], v[30:33], 0
	v_med3_f32 v121, v121, 0, v240
	v_mul_f32_e32 v160, v2, v118
	v_mul_f32_e32 v161, v3, v119
	v_mul_f32_e32 v162, v4, v120
	v_mfma_f32_16x16x32_bf16 v[98:101], v[10:13], v[34:37], 0
	v_mul_f32_e32 v163, v5, v121
	v_add_f32_e32 v159, v160, v161
	v_add_f32_e32 v159, v162, v159
	v_add_f32_e32 v159, v163, v159
	v_mfma_f32_16x16x32_bf16 v[102:105], v[10:13], v[38:41], 0
	s_nop 1
	v_permlane16_swap_b32_e32 v156, v157
	v_permlane16_swap_b32_e32 v158, v159
	v_add_f32_e32 v156, v156, v157
	v_mfma_f32_16x16x32_bf16 v[90:93], v[6:9], v[42:45], v[90:93]
	v_add_f32_e32 v158, v158, v159
	s_nop 1
	v_permlane32_swap_b32_e32 v156, v158
	v_ashrrev_i32_e32 v164, 31, v156
	v_mfma_f32_16x16x32_bf16 v[94:97], v[6:9], v[46:49], v[94:97]
	v_ashrrev_i32_e32 v165, 31, v158
	v_or_b32_e32 v164, 0x80000000, v164
	v_or_b32_e32 v165, 0x80000000, v165
	v_xor_b32_e32 v164, v156, v164
	v_mfma_f32_16x16x32_bf16 v[98:101], v[6:9], v[50:53], v[98:101]
	v_xor_b32_e32 v165, v158, v165
	v_and_b32_e32 v164, 0xffffff00, v164
	v_and_b32_e32 v165, 0xffffff00, v165
	v_cmp_ge_i32_e32 vcc, s5, v242
	v_mfma_f32_16x16x32_bf16 v[102:105], v[6:9], v[54:57], v[102:105]
	s_nop 1
	v_cndmask_b32_e32 v249, 0, v164, vcc
	v_cmp_ge_i32_e32 vcc, s67, v242
	s_nop 1
	v_cndmask_b32_e32 v165, 0, v165, vcc
	global_store_dword v168, v165, s[14:15] offset:3840
	ds_read_b128 v[26:29], v124 offset:16384
	ds_read_b128 v[30:33], v124 offset:18432
	ds_read_b128 v[34:37], v124 offset:20480
	ds_read_b128 v[38:41], v124 offset:22528
	ds_read_b128 v[42:45], v125 offset:16384
	ds_read_b128 v[46:49], v125 offset:18432
	ds_read_b128 v[50:53], v125 offset:20480
	ds_read_b128 v[54:57], v125 offset:22528
	s_waitcnt lgkmcnt(8)
	v_mfma_f32_16x16x32_bf16 v[106:109], v[10:13], v[58:61], 0
	s_sub_i32 s5, s57, 2048
	s_add_i32 s67, s5, 1
	v_med3_f32 v90, v90, 0, v240
	v_med3_f32 v91, v91, 0, v240
	v_med3_f32 v92, v92, 0, v240
	v_med3_f32 v93, v93, 0, v240
	v_mul_f32_e32 v160, v2, v90
	v_mul_f32_e32 v161, v3, v91
	v_mfma_f32_16x16x32_bf16 v[110:113], v[10:13], v[62:65], 0
	v_mul_f32_e32 v162, v4, v92
	v_mul_f32_e32 v163, v5, v93
	v_add_f32_e32 v156, v160, v161
	v_add_f32_e32 v156, v162, v156
	v_add_f32_e32 v156, v163, v156
	v_med3_f32 v94, v94, 0, v240
	v_med3_f32 v95, v95, 0, v240
	v_med3_f32 v96, v96, 0, v240
	v_mfma_f32_16x16x32_bf16 v[114:117], v[10:13], v[66:69], 0
	v_med3_f32 v97, v97, 0, v240
	v_mul_f32_e32 v160, v2, v94
	v_mul_f32_e32 v161, v3, v95
	v_mul_f32_e32 v162, v4, v96
	v_mul_f32_e32 v163, v5, v97
	v_add_f32_e32 v157, v160, v161
	v_add_f32_e32 v157, v162, v157
	v_add_f32_e32 v157, v163, v157
	v_mfma_f32_16x16x32_bf16 v[118:121], v[10:13], v[70:73], 0
	v_med3_f32 v98, v98, 0, v240
	v_med3_f32 v99, v99, 0, v240
	v_med3_f32 v100, v100, 0, v240
	v_med3_f32 v101, v101, 0, v240
	v_mul_f32_e32 v160, v2, v98
	v_mul_f32_e32 v161, v3, v99
	v_mul_f32_e32 v162, v4, v100
	v_mul_f32_e32 v163, v5, v101
	v_mfma_f32_16x16x32_bf16 v[106:109], v[6:9], v[74:77], v[106:109]
	v_add_f32_e32 v158, v160, v161
	v_add_f32_e32 v158, v162, v158
	v_add_f32_e32 v158, v163, v158
	v_med3_f32 v102, v102, 0, v240
	v_med3_f32 v103, v103, 0, v240
	v_med3_f32 v104, v104, 0, v240
	v_med3_f32 v105, v105, 0, v240
	v_mul_f32_e32 v160, v2, v102
	v_mfma_f32_16x16x32_bf16 v[110:113], v[6:9], v[78:81], v[110:113]
	v_mul_f32_e32 v161, v3, v103
	v_mul_f32_e32 v162, v4, v104
	v_mul_f32_e32 v163, v5, v105
	v_add_f32_e32 v159, v160, v161
	v_add_f32_e32 v159, v162, v159
	v_add_f32_e32 v159, v163, v159
	s_nop 1
	v_permlane16_swap_b32_e32 v156, v157
	v_mfma_f32_16x16x32_bf16 v[114:117], v[6:9], v[82:85], v[114:117]
	v_permlane16_swap_b32_e32 v158, v159
	v_add_f32_e32 v156, v156, v157
	v_add_f32_e32 v158, v158, v159
	s_nop 1
	v_permlane32_swap_b32_e32 v156, v158
	v_ashrrev_i32_e32 v164, 31, v156
	v_ashrrev_i32_e32 v165, 31, v158
	v_or_b32_e32 v164, 0x80000000, v164
	v_mfma_f32_16x16x32_bf16 v[118:121], v[6:9], v[86:89], v[118:121]
	v_or_b32_e32 v165, 0x80000000, v165
	v_xor_b32_e32 v164, v156, v164
	v_xor_b32_e32 v165, v158, v165
	v_and_b32_e32 v164, 0xffffff00, v164
	v_and_b32_e32 v165, 0xffffff00, v165
	v_cmp_ge_i32_e32 vcc, s5, v242
	s_nop 1
	v_cndmask_b32_e32 v250, 0, v164, vcc
	v_cmp_ge_i32_e32 vcc, s67, v242
	s_nop 1
	v_cndmask_b32_e32 v165, 0, v165, vcc
	global_store_dword v168, v165, s[46:47]
	ds_read_b128 v[58:61], v124 offset:24576
	ds_read_b128 v[62:65], v124 offset:26624
	ds_read_b128 v[66:69], v124 offset:28672
	ds_read_b128 v[70:73], v124 offset:30720
	ds_read_b128 v[74:77], v125 offset:24576
	ds_read_b128 v[78:81], v125 offset:26624
	ds_read_b128 v[82:85], v125 offset:28672
	ds_read_b128 v[86:89], v125 offset:30720
	s_waitcnt lgkmcnt(8)
	v_mfma_f32_16x16x32_bf16 v[90:93], v[10:13], v[26:29], 0
	s_sub_i32 s5, s57, 2112
	s_add_i32 s67, s5, 1
	v_med3_f32 v106, v106, 0, v240
	v_med3_f32 v107, v107, 0, v240
	v_med3_f32 v108, v108, 0, v240
	v_med3_f32 v109, v109, 0, v240
	v_mul_f32_e32 v160, v2, v106
	v_mul_f32_e32 v161, v3, v107
	v_mfma_f32_16x16x32_bf16 v[94:97], v[10:13], v[30:33], 0
	v_mul_f32_e32 v162, v4, v108
	v_mul_f32_e32 v163, v5, v109
	v_add_f32_e32 v156, v160, v161
	v_add_f32_e32 v156, v162, v156
	v_add_f32_e32 v156, v163, v156
	v_med3_f32 v110, v110, 0, v240
	v_med3_f32 v111, v111, 0, v240
	v_med3_f32 v112, v112, 0, v240
	v_mfma_f32_16x16x32_bf16 v[98:101], v[10:13], v[34:37], 0
	v_med3_f32 v113, v113, 0, v240
	v_mul_f32_e32 v160, v2, v110
	v_mul_f32_e32 v161, v3, v111
	v_mul_f32_e32 v162, v4, v112
	v_mul_f32_e32 v163, v5, v113
	v_add_f32_e32 v157, v160, v161
	v_add_f32_e32 v157, v162, v157
	v_add_f32_e32 v157, v163, v157
	v_mfma_f32_16x16x32_bf16 v[102:105], v[10:13], v[38:41], 0
	v_med3_f32 v114, v114, 0, v240
	v_med3_f32 v115, v115, 0, v240
	v_med3_f32 v116, v116, 0, v240
	v_med3_f32 v117, v117, 0, v240
	v_mul_f32_e32 v160, v2, v114
	v_mul_f32_e32 v161, v3, v115
	v_mul_f32_e32 v162, v4, v116
	v_mul_f32_e32 v163, v5, v117
	v_mfma_f32_16x16x32_bf16 v[90:93], v[6:9], v[42:45], v[90:93]
	v_add_f32_e32 v158, v160, v161
	v_add_f32_e32 v158, v162, v158
	v_add_f32_e32 v158, v163, v158
	v_med3_f32 v118, v118, 0, v240
	v_med3_f32 v119, v119, 0, v240
	v_med3_f32 v120, v120, 0, v240
	v_med3_f32 v121, v121, 0, v240
	v_mul_f32_e32 v160, v2, v118
	v_mfma_f32_16x16x32_bf16 v[94:97], v[6:9], v[46:49], v[94:97]
	v_mul_f32_e32 v161, v3, v119
	v_mul_f32_e32 v162, v4, v120
	v_mul_f32_e32 v163, v5, v121
	v_add_f32_e32 v159, v160, v161
	v_add_f32_e32 v159, v162, v159
	v_add_f32_e32 v159, v163, v159
	s_nop 1
	v_permlane16_swap_b32_e32 v156, v157
	v_mfma_f32_16x16x32_bf16 v[98:101], v[6:9], v[50:53], v[98:101]
	v_permlane16_swap_b32_e32 v158, v159
	v_add_f32_e32 v156, v156, v157
	v_add_f32_e32 v158, v158, v159
	s_nop 1
	v_permlane32_swap_b32_e32 v156, v158
	v_ashrrev_i32_e32 v164, 31, v156
	v_ashrrev_i32_e32 v165, 31, v158
	v_or_b32_e32 v164, 0x80000000, v164
	v_mfma_f32_16x16x32_bf16 v[102:105], v[6:9], v[54:57], v[102:105]
	v_or_b32_e32 v165, 0x80000000, v165
	v_xor_b32_e32 v164, v156, v164
	v_xor_b32_e32 v165, v158, v165
	v_and_b32_e32 v164, 0xffffff00, v164
	v_and_b32_e32 v165, 0xffffff00, v165
	v_cmp_ge_i32_e32 vcc, s5, v242
	s_nop 1
	v_cndmask_b32_e32 v251, 0, v164, vcc
	v_cmp_ge_i32_e32 vcc, s67, v242
	s_nop 1
	v_cndmask_b32_e32 v165, 0, v165, vcc
	global_store_dword v168, v165, s[46:47] offset:256
	s_waitcnt lgkmcnt(0)
	v_mfma_f32_16x16x32_bf16 v[106:109], v[10:13], v[58:61], 0
	s_sub_i32 s5, s57, 2176
	s_add_i32 s67, s5, 1
	v_med3_f32 v90, v90, 0, v240
	v_med3_f32 v91, v91, 0, v240
	v_med3_f32 v92, v92, 0, v240
	v_med3_f32 v93, v93, 0, v240
	v_mul_f32_e32 v160, v2, v90
	v_mul_f32_e32 v161, v3, v91
	v_mfma_f32_16x16x32_bf16 v[110:113], v[10:13], v[62:65], 0
	v_mul_f32_e32 v162, v4, v92
	v_mul_f32_e32 v163, v5, v93
	v_add_f32_e32 v156, v160, v161
	v_add_f32_e32 v156, v162, v156
	v_add_f32_e32 v156, v163, v156
	v_med3_f32 v94, v94, 0, v240
	v_med3_f32 v95, v95, 0, v240
	v_med3_f32 v96, v96, 0, v240
	v_mfma_f32_16x16x32_bf16 v[114:117], v[10:13], v[66:69], 0
	v_med3_f32 v97, v97, 0, v240
	v_mul_f32_e32 v160, v2, v94
	v_mul_f32_e32 v161, v3, v95
	v_mul_f32_e32 v162, v4, v96
	v_mul_f32_e32 v163, v5, v97
	v_add_f32_e32 v157, v160, v161
	v_add_f32_e32 v157, v162, v157
	v_add_f32_e32 v157, v163, v157
	v_mfma_f32_16x16x32_bf16 v[118:121], v[10:13], v[70:73], 0
	v_med3_f32 v98, v98, 0, v240
	v_med3_f32 v99, v99, 0, v240
	v_med3_f32 v100, v100, 0, v240
	v_med3_f32 v101, v101, 0, v240
	v_mul_f32_e32 v160, v2, v98
	v_mul_f32_e32 v161, v3, v99
	v_mul_f32_e32 v162, v4, v100
	v_mul_f32_e32 v163, v5, v101
	v_mfma_f32_16x16x32_bf16 v[106:109], v[6:9], v[74:77], v[106:109]
	v_add_f32_e32 v158, v160, v161
	v_add_f32_e32 v158, v162, v158
	v_add_f32_e32 v158, v163, v158
	v_med3_f32 v102, v102, 0, v240
	v_med3_f32 v103, v103, 0, v240
	v_med3_f32 v104, v104, 0, v240
	v_med3_f32 v105, v105, 0, v240
	v_mul_f32_e32 v160, v2, v102
	v_mfma_f32_16x16x32_bf16 v[110:113], v[6:9], v[78:81], v[110:113]
	v_mul_f32_e32 v161, v3, v103
	v_mul_f32_e32 v162, v4, v104
	v_mul_f32_e32 v163, v5, v105
	v_add_f32_e32 v159, v160, v161
	v_add_f32_e32 v159, v162, v159
	v_add_f32_e32 v159, v163, v159
	s_nop 1
	v_permlane16_swap_b32_e32 v156, v157
	v_mfma_f32_16x16x32_bf16 v[114:117], v[6:9], v[82:85], v[114:117]
	v_permlane16_swap_b32_e32 v158, v159
	v_add_f32_e32 v156, v156, v157
	v_add_f32_e32 v158, v158, v159
	s_nop 1
	v_permlane32_swap_b32_e32 v156, v158
	v_ashrrev_i32_e32 v164, 31, v156
	v_ashrrev_i32_e32 v165, 31, v158
	v_or_b32_e32 v164, 0x80000000, v164
	v_mfma_f32_16x16x32_bf16 v[118:121], v[6:9], v[86:89], v[118:121]
	v_or_b32_e32 v165, 0x80000000, v165
	v_xor_b32_e32 v164, v156, v164
	v_xor_b32_e32 v165, v158, v165
	v_and_b32_e32 v164, 0xffffff00, v164
	v_and_b32_e32 v165, 0xffffff00, v165
	v_cmp_ge_i32_e32 vcc, s5, v242
	s_nop 1
	v_cndmask_b32_e32 v252, 0, v164, vcc
	v_cmp_ge_i32_e32 vcc, s67, v242
	s_nop 1
	v_cndmask_b32_e32 v165, 0, v165, vcc
	global_store_dword v168, v165, s[46:47] offset:512
.Lsc_h9:
	s_cmp_le_u32 s4, 9
	s_cbranch_scc1 .Lsc_drain9
	s_cmp_gt_u32 s4, 11
	s_cbranch_scc0 .Lsc_ni9
	v_lshl_add_u64 v[170:171], s[48:49], 0, v[0:1]
	s_add_i32 m0, s1, 0x18000
	s_nop 0
	global_load_lds_dwordx4 v[170:171], off
	v_lshl_add_u64 v[170:171], s[48:49], 0, v[18:19]
	s_add_i32 m0, s1, 0x1a000
	s_nop 0
	global_load_lds_dwordx4 v[170:171], off
	v_lshl_add_u64 v[170:171], s[48:49], 0, v[20:21]
	s_add_i32 m0, s1, 0x1c000
	s_nop 0
	global_load_lds_dwordx4 v[170:171], off
	v_lshl_add_u64 v[170:171], s[48:49], 0, v[22:23]
	s_add_i32 m0, s1, 0x1e000
	s_nop 0
	global_load_lds_dwordx4 v[170:171], off
	s_add_u32 s48, s48, 0x8000
	s_addc_u32 s49, s49, 0
	s_waitcnt vmcnt(8)
	s_branch .Lsc_b9
.Lsc_ni9:
	s_cmp_gt_u32 s4, 10
	s_cbranch_scc0 .Lsc_w09
	s_waitcnt vmcnt(4)
	s_branch .Lsc_b9

.Lsc_b9:
	s_barrier
	ds_read_b128 v[26:29], v124 offset:32768
	ds_read_b128 v[30:33], v124 offset:34816
	ds_read_b128 v[34:37], v124 offset:36864
	ds_read_b128 v[38:41], v124 offset:38912
	ds_read_b128 v[42:45], v125 offset:32768
	ds_read_b128 v[46:49], v125 offset:34816
	ds_read_b128 v[50:53], v125 offset:36864
	ds_read_b128 v[54:57], v125 offset:38912
	ds_read_b128 v[58:61], v124 offset:40960
	ds_read_b128 v[62:65], v124 offset:43008
	ds_read_b128 v[66:69], v124 offset:45056
	ds_read_b128 v[70:73], v124 offset:47104
	ds_read_b128 v[74:77], v125 offset:40960
	ds_read_b128 v[78:81], v125 offset:43008
	ds_read_b128 v[82:85], v125 offset:45056
	ds_read_b128 v[86:89], v125 offset:47104
	s_sub_i32 s5, s57, 2240
	s_add_i32 s67, s5, 1
	v_med3_f32 v106, v106, 0, v240
	v_med3_f32 v107, v107, 0, v240
	v_med3_f32 v108, v108, 0, v240
	v_med3_f32 v109, v109, 0, v240
	v_mul_f32_e32 v160, v2, v106
	v_mul_f32_e32 v161, v3, v107
	v_mul_f32_e32 v162, v4, v108
	v_mul_f32_e32 v163, v5, v109
	v_add_f32_e32 v156, v160, v161
	v_add_f32_e32 v156, v162, v156
	v_add_f32_e32 v156, v163, v156
	v_med3_f32 v110, v110, 0, v240
	v_med3_f32 v111, v111, 0, v240
	v_med3_f32 v112, v112, 0, v240
	v_med3_f32 v113, v113, 0, v240
	v_mul_f32_e32 v160, v2, v110
	v_mul_f32_e32 v161, v3, v111
	v_mul_f32_e32 v162, v4, v112
	v_mul_f32_e32 v163, v5, v113
	v_add_f32_e32 v157, v160, v161
	v_add_f32_e32 v157, v162, v157
	v_add_f32_e32 v157, v163, v157
	v_med3_f32 v114, v114, 0, v240
	v_med3_f32 v115, v115, 0, v240
	v_med3_f32 v116, v116, 0, v240
	v_med3_f32 v117, v117, 0, v240
	v_mul_f32_e32 v160, v2, v114
	v_mul_f32_e32 v161, v3, v115
	v_mul_f32_e32 v162, v4, v116
	v_mul_f32_e32 v163, v5, v117
	v_add_f32_e32 v158, v160, v161
	v_add_f32_e32 v158, v162, v158
	s_waitcnt lgkmcnt(8)
	v_mfma_f32_16x16x32_bf16 v[90:93], v[10:13], v[26:29], 0
	v_add_f32_e32 v158, v163, v158
	v_med3_f32 v118, v118, 0, v240
	v_med3_f32 v119, v119, 0, v240
	v_med3_f32 v120, v120, 0, v240
	v_mfma_f32_16x16x32_bf16 v[94:97], v[10:13], v[30:33], 0
	v_med3_f32 v121, v121, 0, v240
	v_mul_f32_e32 v160, v2, v118
	v_mul_f32_e32 v161, v3, v119
	v_mul_f32_e32 v162, v4, v120
	v_mfma_f32_16x16x32_bf16 v[98:101], v[10:13], v[34:37], 0
	v_mul_f32_e32 v163, v5, v121
	v_add_f32_e32 v159, v160, v161
	v_add_f32_e32 v159, v162, v159
	v_add_f32_e32 v159, v163, v159
	v_mfma_f32_16x16x32_bf16 v[102:105], v[10:13], v[38:41], 0
	s_nop 1
	v_permlane16_swap_b32_e32 v156, v157
	v_permlane16_swap_b32_e32 v158, v159
	v_add_f32_e32 v156, v156, v157
	v_mfma_f32_16x16x32_bf16 v[90:93], v[6:9], v[42:45], v[90:93]
	v_add_f32_e32 v158, v158, v159
	s_nop 1
	v_permlane32_swap_b32_e32 v156, v158
	v_ashrrev_i32_e32 v164, 31, v156
	v_mfma_f32_16x16x32_bf16 v[94:97], v[6:9], v[46:49], v[94:97]
	v_ashrrev_i32_e32 v165, 31, v158
	v_or_b32_e32 v164, 0x80000000, v164
	v_or_b32_e32 v165, 0x80000000, v165
	v_xor_b32_e32 v164, v156, v164
	v_mfma_f32_16x16x32_bf16 v[98:101], v[6:9], v[50:53], v[98:101]
	v_xor_b32_e32 v165, v158, v165
	v_and_b32_e32 v164, 0xffffff00, v164
	v_and_b32_e32 v165, 0xffffff00, v165
	v_cmp_ge_i32_e32 vcc, s5, v242
	v_mfma_f32_16x16x32_bf16 v[102:105], v[6:9], v[54:57], v[102:105]
	s_nop 1
	v_cndmask_b32_e32 v253, 0, v164, vcc
	v_cmp_ge_i32_e32 vcc, s67, v242
	s_nop 1
	v_cndmask_b32_e32 v165, 0, v165, vcc
	global_store_dword v168, v165, s[46:47] offset:768
	ds_read_b128 v[26:29], v124 offset:49152
	ds_read_b128 v[30:33], v124 offset:51200
	ds_read_b128 v[34:37], v124 offset:53248
	ds_read_b128 v[38:41], v124 offset:55296
	ds_read_b128 v[42:45], v125 offset:49152
	ds_read_b128 v[46:49], v125 offset:51200
	ds_read_b128 v[50:53], v125 offset:53248
	ds_read_b128 v[54:57], v125 offset:55296
	s_waitcnt lgkmcnt(8)
	v_mfma_f32_16x16x32_bf16 v[106:109], v[10:13], v[58:61], 0
	s_sub_i32 s5, s57, 2304
	s_add_i32 s67, s5, 1
	v_med3_f32 v90, v90, 0, v240
	v_med3_f32 v91, v91, 0, v240
	v_med3_f32 v92, v92, 0, v240
	v_med3_f32 v93, v93, 0, v240
	v_mul_f32_e32 v160, v2, v90
	v_mul_f32_e32 v161, v3, v91
	v_mfma_f32_16x16x32_bf16 v[110:113], v[10:13], v[62:65], 0
	v_mul_f32_e32 v162, v4, v92
	v_mul_f32_e32 v163, v5, v93
	v_add_f32_e32 v156, v160, v161
	v_add_f32_e32 v156, v162, v156
	v_add_f32_e32 v156, v163, v156
	v_med3_f32 v94, v94, 0, v240
	v_med3_f32 v95, v95, 0, v240
	v_med3_f32 v96, v96, 0, v240
	v_mfma_f32_16x16x32_bf16 v[114:117], v[10:13], v[66:69], 0
	v_med3_f32 v97, v97, 0, v240
	v_mul_f32_e32 v160, v2, v94
	v_mul_f32_e32 v161, v3, v95
	v_mul_f32_e32 v162, v4, v96
	v_mul_f32_e32 v163, v5, v97
	v_add_f32_e32 v157, v160, v161
	v_add_f32_e32 v157, v162, v157
	v_add_f32_e32 v157, v163, v157
	v_mfma_f32_16x16x32_bf16 v[118:121], v[10:13], v[70:73], 0
	v_med3_f32 v98, v98, 0, v240
	v_med3_f32 v99, v99, 0, v240
	v_med3_f32 v100, v100, 0, v240
	v_med3_f32 v101, v101, 0, v240
	v_mul_f32_e32 v160, v2, v98
	v_mul_f32_e32 v161, v3, v99
	v_mul_f32_e32 v162, v4, v100
	v_mul_f32_e32 v163, v5, v101
	v_mfma_f32_16x16x32_bf16 v[106:109], v[6:9], v[74:77], v[106:109]
	v_add_f32_e32 v158, v160, v161
	v_add_f32_e32 v158, v162, v158
	v_add_f32_e32 v158, v163, v158
	v_med3_f32 v102, v102, 0, v240
	v_med3_f32 v103, v103, 0, v240
	v_med3_f32 v104, v104, 0, v240
	v_med3_f32 v105, v105, 0, v240
	v_mul_f32_e32 v160, v2, v102
	v_mfma_f32_16x16x32_bf16 v[110:113], v[6:9], v[78:81], v[110:113]
	v_mul_f32_e32 v161, v3, v103
	v_mul_f32_e32 v162, v4, v104
	v_mul_f32_e32 v163, v5, v105
	v_add_f32_e32 v159, v160, v161
	v_add_f32_e32 v159, v162, v159
	v_add_f32_e32 v159, v163, v159
	s_nop 1
	v_permlane16_swap_b32_e32 v156, v157
	v_mfma_f32_16x16x32_bf16 v[114:117], v[6:9], v[82:85], v[114:117]
	v_permlane16_swap_b32_e32 v158, v159
	v_add_f32_e32 v156, v156, v157
	v_add_f32_e32 v158, v158, v159
	s_nop 1
	v_permlane32_swap_b32_e32 v156, v158
	v_ashrrev_i32_e32 v164, 31, v156
	v_ashrrev_i32_e32 v165, 31, v158
	v_or_b32_e32 v164, 0x80000000, v164
	v_mfma_f32_16x16x32_bf16 v[118:121], v[6:9], v[86:89], v[118:121]
	v_or_b32_e32 v165, 0x80000000, v165
	v_xor_b32_e32 v164, v156, v164
	v_xor_b32_e32 v165, v158, v165
	v_and_b32_e32 v164, 0xffffff00, v164
	v_and_b32_e32 v165, 0xffffff00, v165
	v_cmp_ge_i32_e32 vcc, s5, v242
	s_nop 1
	v_cndmask_b32_e32 v196, 0, v164, vcc
	v_cmp_ge_i32_e32 vcc, s67, v242
	s_nop 1
	v_cndmask_b32_e32 v165, 0, v165, vcc
	global_store_dword v168, v165, s[46:47] offset:1024
	ds_read_b128 v[58:61], v124 offset:57344
	ds_read_b128 v[62:65], v124 offset:59392
	ds_read_b128 v[66:69], v124 offset:61440
	ds_read_b128 v[70:73], v124 offset:63488
	ds_read_b128 v[74:77], v125 offset:57344
	ds_read_b128 v[78:81], v125 offset:59392
	ds_read_b128 v[82:85], v125 offset:61440
	ds_read_b128 v[86:89], v125 offset:63488
	s_waitcnt lgkmcnt(8)
	v_mfma_f32_16x16x32_bf16 v[90:93], v[10:13], v[26:29], 0
	s_sub_i32 s5, s57, 2368
	s_add_i32 s67, s5, 1
	v_med3_f32 v106, v106, 0, v240
	v_med3_f32 v107, v107, 0, v240
	v_med3_f32 v108, v108, 0, v240
	v_med3_f32 v109, v109, 0, v240
	v_mul_f32_e32 v160, v2, v106
	v_mul_f32_e32 v161, v3, v107
	v_mfma_f32_16x16x32_bf16 v[94:97], v[10:13], v[30:33], 0
	v_mul_f32_e32 v162, v4, v108
	v_mul_f32_e32 v163, v5, v109
	v_add_f32_e32 v156, v160, v161
	v_add_f32_e32 v156, v162, v156
	v_add_f32_e32 v156, v163, v156
	v_med3_f32 v110, v110, 0, v240
	v_med3_f32 v111, v111, 0, v240
	v_med3_f32 v112, v112, 0, v240
	v_mfma_f32_16x16x32_bf16 v[98:101], v[10:13], v[34:37], 0
	v_med3_f32 v113, v113, 0, v240
	v_mul_f32_e32 v160, v2, v110
	v_mul_f32_e32 v161, v3, v111
	v_mul_f32_e32 v162, v4, v112
	v_mul_f32_e32 v163, v5, v113
	v_add_f32_e32 v157, v160, v161
	v_add_f32_e32 v157, v162, v157
	v_add_f32_e32 v157, v163, v157
	v_mfma_f32_16x16x32_bf16 v[102:105], v[10:13], v[38:41], 0
	v_med3_f32 v114, v114, 0, v240
	v_med3_f32 v115, v115, 0, v240
	v_med3_f32 v116, v116, 0, v240
	v_med3_f32 v117, v117, 0, v240
	v_mul_f32_e32 v160, v2, v114
	v_mul_f32_e32 v161, v3, v115
	v_mul_f32_e32 v162, v4, v116
	v_mul_f32_e32 v163, v5, v117
	v_mfma_f32_16x16x32_bf16 v[90:93], v[6:9], v[42:45], v[90:93]
	v_add_f32_e32 v158, v160, v161
	v_add_f32_e32 v158, v162, v158
	v_add_f32_e32 v158, v163, v158
	v_med3_f32 v118, v118, 0, v240
	v_med3_f32 v119, v119, 0, v240
	v_med3_f32 v120, v120, 0, v240
	v_med3_f32 v121, v121, 0, v240
	v_mul_f32_e32 v160, v2, v118
	v_mfma_f32_16x16x32_bf16 v[94:97], v[6:9], v[46:49], v[94:97]
	v_mul_f32_e32 v161, v3, v119
	v_mul_f32_e32 v162, v4, v120
	v_mul_f32_e32 v163, v5, v121
	v_add_f32_e32 v159, v160, v161
	v_add_f32_e32 v159, v162, v159
	v_add_f32_e32 v159, v163, v159
	s_nop 1
	v_permlane16_swap_b32_e32 v156, v157
	v_mfma_f32_16x16x32_bf16 v[98:101], v[6:9], v[50:53], v[98:101]
	v_permlane16_swap_b32_e32 v158, v159
	v_add_f32_e32 v156, v156, v157
	v_add_f32_e32 v158, v158, v159
	s_nop 1
	v_permlane32_swap_b32_e32 v156, v158
	v_ashrrev_i32_e32 v164, 31, v156
	v_ashrrev_i32_e32 v165, 31, v158
	v_or_b32_e32 v164, 0x80000000, v164
	v_mfma_f32_16x16x32_bf16 v[102:105], v[6:9], v[54:57], v[102:105]
	v_or_b32_e32 v165, 0x80000000, v165
	v_xor_b32_e32 v164, v156, v164
	v_xor_b32_e32 v165, v158, v165
	v_and_b32_e32 v164, 0xffffff00, v164
	v_and_b32_e32 v165, 0xffffff00, v165
	v_cmp_ge_i32_e32 vcc, s5, v242
	s_nop 1
	v_cndmask_b32_e32 v197, 0, v164, vcc
	v_cmp_ge_i32_e32 vcc, s67, v242
	s_nop 1
	v_cndmask_b32_e32 v165, 0, v165, vcc
	global_store_dword v168, v165, s[46:47] offset:1280
	s_waitcnt lgkmcnt(0)
	v_mfma_f32_16x16x32_bf16 v[106:109], v[10:13], v[58:61], 0
	s_sub_i32 s5, s57, 2432
	s_add_i32 s67, s5, 1
	v_med3_f32 v90, v90, 0, v240
	v_med3_f32 v91, v91, 0, v240
	v_med3_f32 v92, v92, 0, v240
	v_med3_f32 v93, v93, 0, v240
	v_mul_f32_e32 v160, v2, v90
	v_mul_f32_e32 v161, v3, v91
	v_mfma_f32_16x16x32_bf16 v[110:113], v[10:13], v[62:65], 0
	v_mul_f32_e32 v162, v4, v92
	v_mul_f32_e32 v163, v5, v93
	v_add_f32_e32 v156, v160, v161
	v_add_f32_e32 v156, v162, v156
	v_add_f32_e32 v156, v163, v156
	v_med3_f32 v94, v94, 0, v240
	v_med3_f32 v95, v95, 0, v240
	v_med3_f32 v96, v96, 0, v240
	v_mfma_f32_16x16x32_bf16 v[114:117], v[10:13], v[66:69], 0
	v_med3_f32 v97, v97, 0, v240
	v_mul_f32_e32 v160, v2, v94
	v_mul_f32_e32 v161, v3, v95
	v_mul_f32_e32 v162, v4, v96
	v_mul_f32_e32 v163, v5, v97
	v_add_f32_e32 v157, v160, v161
	v_add_f32_e32 v157, v162, v157
	v_add_f32_e32 v157, v163, v157
	v_mfma_f32_16x16x32_bf16 v[118:121], v[10:13], v[70:73], 0
	v_med3_f32 v98, v98, 0, v240
	v_med3_f32 v99, v99, 0, v240
	v_med3_f32 v100, v100, 0, v240
	v_med3_f32 v101, v101, 0, v240
	v_mul_f32_e32 v160, v2, v98
	v_mul_f32_e32 v161, v3, v99
	v_mul_f32_e32 v162, v4, v100
	v_mul_f32_e32 v163, v5, v101
	v_mfma_f32_16x16x32_bf16 v[106:109], v[6:9], v[74:77], v[106:109]
	v_add_f32_e32 v158, v160, v161
	v_add_f32_e32 v158, v162, v158
	v_add_f32_e32 v158, v163, v158
	v_med3_f32 v102, v102, 0, v240
	v_med3_f32 v103, v103, 0, v240
	v_med3_f32 v104, v104, 0, v240
	v_med3_f32 v105, v105, 0, v240
	v_mul_f32_e32 v160, v2, v102
	v_mfma_f32_16x16x32_bf16 v[110:113], v[6:9], v[78:81], v[110:113]
	v_mul_f32_e32 v161, v3, v103
	v_mul_f32_e32 v162, v4, v104
	v_mul_f32_e32 v163, v5, v105
	v_add_f32_e32 v159, v160, v161
	v_add_f32_e32 v159, v162, v159
	v_add_f32_e32 v159, v163, v159
	s_nop 1
	v_permlane16_swap_b32_e32 v156, v157
	v_mfma_f32_16x16x32_bf16 v[114:117], v[6:9], v[82:85], v[114:117]
	v_permlane16_swap_b32_e32 v158, v159
	v_add_f32_e32 v156, v156, v157
	v_add_f32_e32 v158, v158, v159
	s_nop 1
	v_permlane32_swap_b32_e32 v156, v158
	v_ashrrev_i32_e32 v164, 31, v156
	v_ashrrev_i32_e32 v165, 31, v158
	v_or_b32_e32 v164, 0x80000000, v164
	v_mfma_f32_16x16x32_bf16 v[118:121], v[6:9], v[86:89], v[118:121]
	v_or_b32_e32 v165, 0x80000000, v165
	v_xor_b32_e32 v164, v156, v164
	v_xor_b32_e32 v165, v158, v165
	v_and_b32_e32 v164, 0xffffff00, v164
	v_and_b32_e32 v165, 0xffffff00, v165
	v_cmp_ge_i32_e32 vcc, s5, v242
	s_nop 1
	v_cndmask_b32_e32 v198, 0, v164, vcc
	v_cmp_ge_i32_e32 vcc, s67, v242
	s_nop 1
	v_cndmask_b32_e32 v165, 0, v165, vcc
	global_store_dword v168, v165, s[46:47] offset:1536
.Lsc_h10:
	s_cmp_le_u32 s4, 10
	s_cbranch_scc1 .Lsc_drain10
	s_cmp_gt_u32 s4, 12
	s_cbranch_scc0 .Lsc_ni10
	v_lshl_add_u64 v[170:171], s[48:49], 0, v[0:1]
	s_add_i32 m0, s1, 0x0
	s_nop 0
	global_load_lds_dwordx4 v[170:171], off
	v_lshl_add_u64 v[170:171], s[48:49], 0, v[18:19]
	s_add_i32 m0, s1, 0x2000
	s_nop 0
	global_load_lds_dwordx4 v[170:171], off
	v_lshl_add_u64 v[170:171], s[48:49], 0, v[20:21]
	s_add_i32 m0, s1, 0x4000
	s_nop 0
	global_load_lds_dwordx4 v[170:171], off
	v_lshl_add_u64 v[170:171], s[48:49], 0, v[22:23]
	s_add_i32 m0, s1, 0x6000
	s_nop 0
	global_load_lds_dwordx4 v[170:171], off
	s_add_u32 s48, s48, 0x8000
	s_addc_u32 s49, s49, 0
	s_waitcnt vmcnt(8)
	s_branch .Lsc_b10
.Lsc_ni10:
	s_cmp_gt_u32 s4, 11
	s_cbranch_scc0 .Lsc_w010
	s_waitcnt vmcnt(4)
	s_branch .Lsc_b10

.Lsc_b10:
	s_barrier
	ds_read_b128 v[26:29], v166
	ds_read_b128 v[30:33], v166 offset:2048
	ds_read_b128 v[34:37], v166 offset:4096
	ds_read_b128 v[38:41], v166 offset:6144
	ds_read_b128 v[42:45], v167
	ds_read_b128 v[46:49], v167 offset:2048
	ds_read_b128 v[50:53], v167 offset:4096
	ds_read_b128 v[54:57], v167 offset:6144
	ds_read_b128 v[58:61], v166 offset:8192
	ds_read_b128 v[62:65], v166 offset:10240
	ds_read_b128 v[66:69], v166 offset:12288
	ds_read_b128 v[70:73], v166 offset:14336
	ds_read_b128 v[74:77], v167 offset:8192
	ds_read_b128 v[78:81], v167 offset:10240
	ds_read_b128 v[82:85], v167 offset:12288
	ds_read_b128 v[86:89], v167 offset:14336
	s_sub_i32 s5, s57, 2496
	s_add_i32 s67, s5, 1
	v_med3_f32 v106, v106, 0, v240
	v_med3_f32 v107, v107, 0, v240
	v_med3_f32 v108, v108, 0, v240
	v_med3_f32 v109, v109, 0, v240
	v_mul_f32_e32 v160, v2, v106
	v_mul_f32_e32 v161, v3, v107
	v_mul_f32_e32 v162, v4, v108
	v_mul_f32_e32 v163, v5, v109
	v_add_f32_e32 v156, v160, v161
	v_add_f32_e32 v156, v162, v156
	v_add_f32_e32 v156, v163, v156
	v_med3_f32 v110, v110, 0, v240
	v_med3_f32 v111, v111, 0, v240
	v_med3_f32 v112, v112, 0, v240
	v_med3_f32 v113, v113, 0, v240
	v_mul_f32_e32 v160, v2, v110
	v_mul_f32_e32 v161, v3, v111
	v_mul_f32_e32 v162, v4, v112
	v_mul_f32_e32 v163, v5, v113
	v_add_f32_e32 v157, v160, v161
	v_add_f32_e32 v157, v162, v157
	v_add_f32_e32 v157, v163, v157
	v_med3_f32 v114, v114, 0, v240
	v_med3_f32 v115, v115, 0, v240
	v_med3_f32 v116, v116, 0, v240
	v_med3_f32 v117, v117, 0, v240
	v_mul_f32_e32 v160, v2, v114
	v_mul_f32_e32 v161, v3, v115
	v_mul_f32_e32 v162, v4, v116
	v_mul_f32_e32 v163, v5, v117
	v_add_f32_e32 v158, v160, v161
	v_add_f32_e32 v158, v162, v158
	s_waitcnt lgkmcnt(8)
	v_mfma_f32_16x16x32_bf16 v[90:93], v[10:13], v[26:29], 0
	v_add_f32_e32 v158, v163, v158
	v_med3_f32 v118, v118, 0, v240
	v_med3_f32 v119, v119, 0, v240
	v_med3_f32 v120, v120, 0, v240
	v_mfma_f32_16x16x32_bf16 v[94:97], v[10:13], v[30:33], 0
	v_med3_f32 v121, v121, 0, v240
	v_mul_f32_e32 v160, v2, v118
	v_mul_f32_e32 v161, v3, v119
	v_mul_f32_e32 v162, v4, v120
	v_mfma_f32_16x16x32_bf16 v[98:101], v[10:13], v[34:37], 0
	v_mul_f32_e32 v163, v5, v121
	v_add_f32_e32 v159, v160, v161
	v_add_f32_e32 v159, v162, v159
	v_add_f32_e32 v159, v163, v159
	v_mfma_f32_16x16x32_bf16 v[102:105], v[10:13], v[38:41], 0
	s_nop 1
	v_permlane16_swap_b32_e32 v156, v157
	v_permlane16_swap_b32_e32 v158, v159
	v_add_f32_e32 v156, v156, v157
	v_mfma_f32_16x16x32_bf16 v[90:93], v[6:9], v[42:45], v[90:93]
	v_add_f32_e32 v158, v158, v159
	s_nop 1
	v_permlane32_swap_b32_e32 v156, v158
	v_ashrrev_i32_e32 v164, 31, v156
	v_mfma_f32_16x16x32_bf16 v[94:97], v[6:9], v[46:49], v[94:97]
	v_ashrrev_i32_e32 v165, 31, v158
	v_or_b32_e32 v164, 0x80000000, v164
	v_or_b32_e32 v165, 0x80000000, v165
	v_xor_b32_e32 v164, v156, v164
	v_mfma_f32_16x16x32_bf16 v[98:101], v[6:9], v[50:53], v[98:101]
	v_xor_b32_e32 v165, v158, v165
	v_and_b32_e32 v164, 0xffffff00, v164
	v_and_b32_e32 v165, 0xffffff00, v165
	v_cmp_ge_i32_e32 vcc, s5, v242
	v_mfma_f32_16x16x32_bf16 v[102:105], v[6:9], v[54:57], v[102:105]
	s_nop 1
	v_cndmask_b32_e32 v199, 0, v164, vcc
	v_cmp_ge_i32_e32 vcc, s67, v242
	s_nop 1
	v_cndmask_b32_e32 v165, 0, v165, vcc
	global_store_dword v168, v165, s[46:47] offset:1792
	ds_read_b128 v[26:29], v166 offset:16384
	ds_read_b128 v[30:33], v166 offset:18432
	ds_read_b128 v[34:37], v166 offset:20480
	ds_read_b128 v[38:41], v166 offset:22528
	ds_read_b128 v[42:45], v167 offset:16384
	ds_read_b128 v[46:49], v167 offset:18432
	ds_read_b128 v[50:53], v167 offset:20480
	ds_read_b128 v[54:57], v167 offset:22528
	s_waitcnt lgkmcnt(8)
	v_mfma_f32_16x16x32_bf16 v[106:109], v[10:13], v[58:61], 0
	s_sub_i32 s5, s57, 2560
	s_add_i32 s67, s5, 1
	v_med3_f32 v90, v90, 0, v240
	v_med3_f32 v91, v91, 0, v240
	v_med3_f32 v92, v92, 0, v240
	v_med3_f32 v93, v93, 0, v240
	v_mul_f32_e32 v160, v2, v90
	v_mul_f32_e32 v161, v3, v91
	v_mfma_f32_16x16x32_bf16 v[110:113], v[10:13], v[62:65], 0
	v_mul_f32_e32 v162, v4, v92
	v_mul_f32_e32 v163, v5, v93
	v_add_f32_e32 v156, v160, v161
	v_add_f32_e32 v156, v162, v156
	v_add_f32_e32 v156, v163, v156
	v_med3_f32 v94, v94, 0, v240
	v_med3_f32 v95, v95, 0, v240
	v_med3_f32 v96, v96, 0, v240
	v_mfma_f32_16x16x32_bf16 v[114:117], v[10:13], v[66:69], 0
	v_med3_f32 v97, v97, 0, v240
	v_mul_f32_e32 v160, v2, v94
	v_mul_f32_e32 v161, v3, v95
	v_mul_f32_e32 v162, v4, v96
	v_mul_f32_e32 v163, v5, v97
	v_add_f32_e32 v157, v160, v161
	v_add_f32_e32 v157, v162, v157
	v_add_f32_e32 v157, v163, v157
	v_mfma_f32_16x16x32_bf16 v[118:121], v[10:13], v[70:73], 0
	v_med3_f32 v98, v98, 0, v240
	v_med3_f32 v99, v99, 0, v240
	v_med3_f32 v100, v100, 0, v240
	v_med3_f32 v101, v101, 0, v240
	v_mul_f32_e32 v160, v2, v98
	v_mul_f32_e32 v161, v3, v99
	v_mul_f32_e32 v162, v4, v100
	v_mul_f32_e32 v163, v5, v101
	v_mfma_f32_16x16x32_bf16 v[106:109], v[6:9], v[74:77], v[106:109]
	v_add_f32_e32 v158, v160, v161
	v_add_f32_e32 v158, v162, v158
	v_add_f32_e32 v158, v163, v158
	v_med3_f32 v102, v102, 0, v240
	v_med3_f32 v103, v103, 0, v240
	v_med3_f32 v104, v104, 0, v240
	v_med3_f32 v105, v105, 0, v240
	v_mul_f32_e32 v160, v2, v102
	v_mfma_f32_16x16x32_bf16 v[110:113], v[6:9], v[78:81], v[110:113]
	v_mul_f32_e32 v161, v3, v103
	v_mul_f32_e32 v162, v4, v104
	v_mul_f32_e32 v163, v5, v105
	v_add_f32_e32 v159, v160, v161
	v_add_f32_e32 v159, v162, v159
	v_add_f32_e32 v159, v163, v159
	s_nop 1
	v_permlane16_swap_b32_e32 v156, v157
	v_mfma_f32_16x16x32_bf16 v[114:117], v[6:9], v[82:85], v[114:117]
	v_permlane16_swap_b32_e32 v158, v159
	v_add_f32_e32 v156, v156, v157
	v_add_f32_e32 v158, v158, v159
	s_nop 1
	v_permlane32_swap_b32_e32 v156, v158
	v_ashrrev_i32_e32 v164, 31, v156
	v_ashrrev_i32_e32 v165, 31, v158
	v_or_b32_e32 v164, 0x80000000, v164
	v_mfma_f32_16x16x32_bf16 v[118:121], v[6:9], v[86:89], v[118:121]
	v_or_b32_e32 v165, 0x80000000, v165
	v_xor_b32_e32 v164, v156, v164
	v_xor_b32_e32 v165, v158, v165
	v_and_b32_e32 v164, 0xffffff00, v164
	v_and_b32_e32 v165, 0xffffff00, v165
	v_cmp_ge_i32_e32 vcc, s5, v242
	s_nop 1
	v_cndmask_b32_e32 v201, 0, v164, vcc
	v_cmp_ge_i32_e32 vcc, s67, v242
	s_nop 1
	v_cndmask_b32_e32 v165, 0, v165, vcc
	global_store_dword v168, v165, s[46:47] offset:2048
	ds_read_b128 v[58:61], v166 offset:24576
	ds_read_b128 v[62:65], v166 offset:26624
	ds_read_b128 v[66:69], v166 offset:28672
	ds_read_b128 v[70:73], v166 offset:30720
	ds_read_b128 v[74:77], v167 offset:24576
	ds_read_b128 v[78:81], v167 offset:26624
	ds_read_b128 v[82:85], v167 offset:28672
	ds_read_b128 v[86:89], v167 offset:30720
	s_waitcnt lgkmcnt(8)
	v_mfma_f32_16x16x32_bf16 v[90:93], v[10:13], v[26:29], 0
	s_sub_i32 s5, s57, 2624
	s_add_i32 s67, s5, 1
	v_med3_f32 v106, v106, 0, v240
	v_med3_f32 v107, v107, 0, v240
	v_med3_f32 v108, v108, 0, v240
	v_med3_f32 v109, v109, 0, v240
	v_mul_f32_e32 v160, v2, v106
	v_mul_f32_e32 v161, v3, v107
	v_mfma_f32_16x16x32_bf16 v[94:97], v[10:13], v[30:33], 0
	v_mul_f32_e32 v162, v4, v108
	v_mul_f32_e32 v163, v5, v109
	v_add_f32_e32 v156, v160, v161
	v_add_f32_e32 v156, v162, v156
	v_add_f32_e32 v156, v163, v156
	v_med3_f32 v110, v110, 0, v240
	v_med3_f32 v111, v111, 0, v240
	v_med3_f32 v112, v112, 0, v240
	v_mfma_f32_16x16x32_bf16 v[98:101], v[10:13], v[34:37], 0
	v_med3_f32 v113, v113, 0, v240
	v_mul_f32_e32 v160, v2, v110
	v_mul_f32_e32 v161, v3, v111
	v_mul_f32_e32 v162, v4, v112
	v_mul_f32_e32 v163, v5, v113
	v_add_f32_e32 v157, v160, v161
	v_add_f32_e32 v157, v162, v157
	v_add_f32_e32 v157, v163, v157
	v_mfma_f32_16x16x32_bf16 v[102:105], v[10:13], v[38:41], 0
	v_med3_f32 v114, v114, 0, v240
	v_med3_f32 v115, v115, 0, v240
	v_med3_f32 v116, v116, 0, v240
	v_med3_f32 v117, v117, 0, v240
	v_mul_f32_e32 v160, v2, v114
	v_mul_f32_e32 v161, v3, v115
	v_mul_f32_e32 v162, v4, v116
	v_mul_f32_e32 v163, v5, v117
	v_mfma_f32_16x16x32_bf16 v[90:93], v[6:9], v[42:45], v[90:93]
	v_add_f32_e32 v158, v160, v161
	v_add_f32_e32 v158, v162, v158
	v_add_f32_e32 v158, v163, v158
	v_med3_f32 v118, v118, 0, v240
	v_med3_f32 v119, v119, 0, v240
	v_med3_f32 v120, v120, 0, v240
	v_med3_f32 v121, v121, 0, v240
	v_mul_f32_e32 v160, v2, v118
	v_mfma_f32_16x16x32_bf16 v[94:97], v[6:9], v[46:49], v[94:97]
	v_mul_f32_e32 v161, v3, v119
	v_mul_f32_e32 v162, v4, v120
	v_mul_f32_e32 v163, v5, v121
	v_add_f32_e32 v159, v160, v161
	v_add_f32_e32 v159, v162, v159
	v_add_f32_e32 v159, v163, v159
	s_nop 1
	v_permlane16_swap_b32_e32 v156, v157
	v_mfma_f32_16x16x32_bf16 v[98:101], v[6:9], v[50:53], v[98:101]
	v_permlane16_swap_b32_e32 v158, v159
	v_add_f32_e32 v156, v156, v157
	v_add_f32_e32 v158, v158, v159
	s_nop 1
	v_permlane32_swap_b32_e32 v156, v158
	v_ashrrev_i32_e32 v164, 31, v156
	v_ashrrev_i32_e32 v165, 31, v158
	v_or_b32_e32 v164, 0x80000000, v164
	v_mfma_f32_16x16x32_bf16 v[102:105], v[6:9], v[54:57], v[102:105]
	v_or_b32_e32 v165, 0x80000000, v165
	v_xor_b32_e32 v164, v156, v164
	v_xor_b32_e32 v165, v158, v165
	v_and_b32_e32 v164, 0xffffff00, v164
	v_and_b32_e32 v165, 0xffffff00, v165
	v_cmp_ge_i32_e32 vcc, s5, v242
	s_nop 1
	v_cndmask_b32_e32 v200, 0, v164, vcc
	v_cmp_ge_i32_e32 vcc, s67, v242
	s_nop 1
	v_cndmask_b32_e32 v165, 0, v165, vcc
	global_store_dword v168, v165, s[46:47] offset:2304
	s_waitcnt lgkmcnt(0)
	v_mfma_f32_16x16x32_bf16 v[106:109], v[10:13], v[58:61], 0
	s_sub_i32 s5, s57, 2688
	s_add_i32 s67, s5, 1
	v_med3_f32 v90, v90, 0, v240
	v_med3_f32 v91, v91, 0, v240
	v_med3_f32 v92, v92, 0, v240
	v_med3_f32 v93, v93, 0, v240
	v_mul_f32_e32 v160, v2, v90
	v_mul_f32_e32 v161, v3, v91
	v_mfma_f32_16x16x32_bf16 v[110:113], v[10:13], v[62:65], 0
	v_mul_f32_e32 v162, v4, v92
	v_mul_f32_e32 v163, v5, v93
	v_add_f32_e32 v156, v160, v161
	v_add_f32_e32 v156, v162, v156
	v_add_f32_e32 v156, v163, v156
	v_med3_f32 v94, v94, 0, v240
	v_med3_f32 v95, v95, 0, v240
	v_med3_f32 v96, v96, 0, v240
	v_mfma_f32_16x16x32_bf16 v[114:117], v[10:13], v[66:69], 0
	v_med3_f32 v97, v97, 0, v240
	v_mul_f32_e32 v160, v2, v94
	v_mul_f32_e32 v161, v3, v95
	v_mul_f32_e32 v162, v4, v96
	v_mul_f32_e32 v163, v5, v97
	v_add_f32_e32 v157, v160, v161
	v_add_f32_e32 v157, v162, v157
	v_add_f32_e32 v157, v163, v157
	v_mfma_f32_16x16x32_bf16 v[118:121], v[10:13], v[70:73], 0
	v_med3_f32 v98, v98, 0, v240
	v_med3_f32 v99, v99, 0, v240
	v_med3_f32 v100, v100, 0, v240
	v_med3_f32 v101, v101, 0, v240
	v_mul_f32_e32 v160, v2, v98
	v_mul_f32_e32 v161, v3, v99
	v_mul_f32_e32 v162, v4, v100
	v_mul_f32_e32 v163, v5, v101
	v_mfma_f32_16x16x32_bf16 v[106:109], v[6:9], v[74:77], v[106:109]
	v_add_f32_e32 v158, v160, v161
	v_add_f32_e32 v158, v162, v158
	v_add_f32_e32 v158, v163, v158
	v_med3_f32 v102, v102, 0, v240
	v_med3_f32 v103, v103, 0, v240
	v_med3_f32 v104, v104, 0, v240
	v_med3_f32 v105, v105, 0, v240
	v_mul_f32_e32 v160, v2, v102
	v_mfma_f32_16x16x32_bf16 v[110:113], v[6:9], v[78:81], v[110:113]
	v_mul_f32_e32 v161, v3, v103
	v_mul_f32_e32 v162, v4, v104
	v_mul_f32_e32 v163, v5, v105
	v_add_f32_e32 v159, v160, v161
	v_add_f32_e32 v159, v162, v159
	v_add_f32_e32 v159, v163, v159
	s_nop 1
	v_permlane16_swap_b32_e32 v156, v157
	v_mfma_f32_16x16x32_bf16 v[114:117], v[6:9], v[82:85], v[114:117]
	v_permlane16_swap_b32_e32 v158, v159
	v_add_f32_e32 v156, v156, v157
	v_add_f32_e32 v158, v158, v159
	s_nop 1
	v_permlane32_swap_b32_e32 v156, v158
	v_ashrrev_i32_e32 v164, 31, v156
	v_ashrrev_i32_e32 v165, 31, v158
	v_or_b32_e32 v164, 0x80000000, v164
	v_mfma_f32_16x16x32_bf16 v[118:121], v[6:9], v[86:89], v[118:121]
	v_or_b32_e32 v165, 0x80000000, v165
	v_xor_b32_e32 v164, v156, v164
	v_xor_b32_e32 v165, v158, v165
	v_and_b32_e32 v164, 0xffffff00, v164
	v_and_b32_e32 v165, 0xffffff00, v165
	v_cmp_ge_i32_e32 vcc, s5, v242
	s_nop 1
	v_cndmask_b32_e32 v238, 0, v164, vcc
	v_cmp_ge_i32_e32 vcc, s67, v242
	s_nop 1
	v_cndmask_b32_e32 v165, 0, v165, vcc
	global_store_dword v168, v165, s[46:47] offset:2560
.Lsc_h11:
	s_cmp_le_u32 s4, 11
	s_cbranch_scc1 .Lsc_drain11
	s_cmp_gt_u32 s4, 13
	s_cbranch_scc0 .Lsc_ni11
	v_lshl_add_u64 v[170:171], s[48:49], 0, v[0:1]
	s_add_i32 m0, s1, 0x8000
	s_nop 0
	global_load_lds_dwordx4 v[170:171], off
	v_lshl_add_u64 v[170:171], s[48:49], 0, v[18:19]
	s_add_i32 m0, s1, 0xa000
	s_nop 0
	global_load_lds_dwordx4 v[170:171], off
	v_lshl_add_u64 v[170:171], s[48:49], 0, v[20:21]
	s_add_i32 m0, s1, 0xc000
	s_nop 0
	global_load_lds_dwordx4 v[170:171], off
	v_lshl_add_u64 v[170:171], s[48:49], 0, v[22:23]
	s_add_i32 m0, s1, 0xe000
	s_nop 0
	global_load_lds_dwordx4 v[170:171], off
	s_add_u32 s48, s48, 0x8000
	s_addc_u32 s49, s49, 0
	s_waitcnt vmcnt(8)
	s_branch .Lsc_b11
.Lsc_ni11:
	s_cmp_gt_u32 s4, 12
	s_cbranch_scc0 .Lsc_w011
	s_waitcnt vmcnt(4)
	s_branch .Lsc_b11

.Lsc_b11:
	s_barrier
	ds_read_b128 v[26:29], v166 offset:32768
	ds_read_b128 v[30:33], v166 offset:34816
	ds_read_b128 v[34:37], v166 offset:36864
	ds_read_b128 v[38:41], v166 offset:38912
	ds_read_b128 v[42:45], v167 offset:32768
	ds_read_b128 v[46:49], v167 offset:34816
	ds_read_b128 v[50:53], v167 offset:36864
	ds_read_b128 v[54:57], v167 offset:38912
	ds_read_b128 v[58:61], v166 offset:40960
	ds_read_b128 v[62:65], v166 offset:43008
	ds_read_b128 v[66:69], v166 offset:45056
	ds_read_b128 v[70:73], v166 offset:47104
	ds_read_b128 v[74:77], v167 offset:40960
	ds_read_b128 v[78:81], v167 offset:43008
	ds_read_b128 v[82:85], v167 offset:45056
	ds_read_b128 v[86:89], v167 offset:47104
	s_sub_i32 s5, s57, 2752
	s_add_i32 s67, s5, 1
	v_med3_f32 v106, v106, 0, v240
	v_med3_f32 v107, v107, 0, v240
	v_med3_f32 v108, v108, 0, v240
	v_med3_f32 v109, v109, 0, v240
	v_mul_f32_e32 v160, v2, v106
	v_mul_f32_e32 v161, v3, v107
	v_mul_f32_e32 v162, v4, v108
	v_mul_f32_e32 v163, v5, v109
	v_add_f32_e32 v156, v160, v161
	v_add_f32_e32 v156, v162, v156
	v_add_f32_e32 v156, v163, v156
	v_med3_f32 v110, v110, 0, v240
	v_med3_f32 v111, v111, 0, v240
	v_med3_f32 v112, v112, 0, v240
	v_med3_f32 v113, v113, 0, v240
	v_mul_f32_e32 v160, v2, v110
	v_mul_f32_e32 v161, v3, v111
	v_mul_f32_e32 v162, v4, v112
	v_mul_f32_e32 v163, v5, v113
	v_add_f32_e32 v157, v160, v161
	v_add_f32_e32 v157, v162, v157
	v_add_f32_e32 v157, v163, v157
	v_med3_f32 v114, v114, 0, v240
	v_med3_f32 v115, v115, 0, v240
	v_med3_f32 v116, v116, 0, v240
	v_med3_f32 v117, v117, 0, v240
	v_mul_f32_e32 v160, v2, v114
	v_mul_f32_e32 v161, v3, v115
	v_mul_f32_e32 v162, v4, v116
	v_mul_f32_e32 v163, v5, v117
	v_add_f32_e32 v158, v160, v161
	v_add_f32_e32 v158, v162, v158
	s_waitcnt lgkmcnt(8)
	v_mfma_f32_16x16x32_bf16 v[90:93], v[10:13], v[26:29], 0
	v_add_f32_e32 v158, v163, v158
	v_med3_f32 v118, v118, 0, v240
	v_med3_f32 v119, v119, 0, v240
	v_med3_f32 v120, v120, 0, v240
	v_mfma_f32_16x16x32_bf16 v[94:97], v[10:13], v[30:33], 0
	v_med3_f32 v121, v121, 0, v240
	v_mul_f32_e32 v160, v2, v118
	v_mul_f32_e32 v161, v3, v119
	v_mul_f32_e32 v162, v4, v120
	v_mfma_f32_16x16x32_bf16 v[98:101], v[10:13], v[34:37], 0
	v_mul_f32_e32 v163, v5, v121
	v_add_f32_e32 v159, v160, v161
	v_add_f32_e32 v159, v162, v159
	v_add_f32_e32 v159, v163, v159
	v_mfma_f32_16x16x32_bf16 v[102:105], v[10:13], v[38:41], 0
	s_nop 1
	v_permlane16_swap_b32_e32 v156, v157
	v_permlane16_swap_b32_e32 v158, v159
	v_add_f32_e32 v156, v156, v157
	v_mfma_f32_16x16x32_bf16 v[90:93], v[6:9], v[42:45], v[90:93]
	v_add_f32_e32 v158, v158, v159
	s_nop 1
	v_permlane32_swap_b32_e32 v156, v158
	v_ashrrev_i32_e32 v164, 31, v156
	v_mfma_f32_16x16x32_bf16 v[94:97], v[6:9], v[46:49], v[94:97]
	v_ashrrev_i32_e32 v165, 31, v158
	v_or_b32_e32 v164, 0x80000000, v164
	v_or_b32_e32 v165, 0x80000000, v165
	v_xor_b32_e32 v164, v156, v164
	v_mfma_f32_16x16x32_bf16 v[98:101], v[6:9], v[50:53], v[98:101]
	v_xor_b32_e32 v165, v158, v165
	v_and_b32_e32 v164, 0xffffff00, v164
	v_and_b32_e32 v165, 0xffffff00, v165
	v_cmp_ge_i32_e32 vcc, s5, v242
	v_mfma_f32_16x16x32_bf16 v[102:105], v[6:9], v[54:57], v[102:105]
	s_nop 1
	v_cndmask_b32_e32 v131, 0, v164, vcc
	v_cmp_ge_i32_e32 vcc, s67, v242
	s_nop 1
	v_cndmask_b32_e32 v165, 0, v165, vcc
	global_store_dword v168, v165, s[46:47] offset:2816
	ds_read_b128 v[26:29], v166 offset:49152
	ds_read_b128 v[30:33], v166 offset:51200
	ds_read_b128 v[34:37], v166 offset:53248
	ds_read_b128 v[38:41], v166 offset:55296
	ds_read_b128 v[42:45], v167 offset:49152
	ds_read_b128 v[46:49], v167 offset:51200
	ds_read_b128 v[50:53], v167 offset:53248
	ds_read_b128 v[54:57], v167 offset:55296
	s_waitcnt lgkmcnt(8)
	v_mfma_f32_16x16x32_bf16 v[106:109], v[10:13], v[58:61], 0
	s_sub_i32 s5, s57, 2816
	s_add_i32 s67, s5, 1
	v_med3_f32 v90, v90, 0, v240
	v_med3_f32 v91, v91, 0, v240
	v_med3_f32 v92, v92, 0, v240
	v_med3_f32 v93, v93, 0, v240
	v_mul_f32_e32 v160, v2, v90
	v_mul_f32_e32 v161, v3, v91
	v_mfma_f32_16x16x32_bf16 v[110:113], v[10:13], v[62:65], 0
	v_mul_f32_e32 v162, v4, v92
	v_mul_f32_e32 v163, v5, v93
	v_add_f32_e32 v156, v160, v161
	v_add_f32_e32 v156, v162, v156
	v_add_f32_e32 v156, v163, v156
	v_med3_f32 v94, v94, 0, v240
	v_med3_f32 v95, v95, 0, v240
	v_med3_f32 v96, v96, 0, v240
	v_mfma_f32_16x16x32_bf16 v[114:117], v[10:13], v[66:69], 0
	v_med3_f32 v97, v97, 0, v240
	v_mul_f32_e32 v160, v2, v94
	v_mul_f32_e32 v161, v3, v95
	v_mul_f32_e32 v162, v4, v96
	v_mul_f32_e32 v163, v5, v97
	v_add_f32_e32 v157, v160, v161
	v_add_f32_e32 v157, v162, v157
	v_add_f32_e32 v157, v163, v157
	v_mfma_f32_16x16x32_bf16 v[118:121], v[10:13], v[70:73], 0
	v_med3_f32 v98, v98, 0, v240
	v_med3_f32 v99, v99, 0, v240
	v_med3_f32 v100, v100, 0, v240
	v_med3_f32 v101, v101, 0, v240
	v_mul_f32_e32 v160, v2, v98
	v_mul_f32_e32 v161, v3, v99
	v_mul_f32_e32 v162, v4, v100
	v_mul_f32_e32 v163, v5, v101
	v_mfma_f32_16x16x32_bf16 v[106:109], v[6:9], v[74:77], v[106:109]
	v_add_f32_e32 v158, v160, v161
	v_add_f32_e32 v158, v162, v158
	v_add_f32_e32 v158, v163, v158
	v_med3_f32 v102, v102, 0, v240
	v_med3_f32 v103, v103, 0, v240
	v_med3_f32 v104, v104, 0, v240
	v_med3_f32 v105, v105, 0, v240
	v_mul_f32_e32 v160, v2, v102
	v_mfma_f32_16x16x32_bf16 v[110:113], v[6:9], v[78:81], v[110:113]
	v_mul_f32_e32 v161, v3, v103
	v_mul_f32_e32 v162, v4, v104
	v_mul_f32_e32 v163, v5, v105
	v_add_f32_e32 v159, v160, v161
	v_add_f32_e32 v159, v162, v159
	v_add_f32_e32 v159, v163, v159
	s_nop 1
	v_permlane16_swap_b32_e32 v156, v157
	v_mfma_f32_16x16x32_bf16 v[114:117], v[6:9], v[82:85], v[114:117]
	v_permlane16_swap_b32_e32 v158, v159
	v_add_f32_e32 v156, v156, v157
	v_add_f32_e32 v158, v158, v159
	s_nop 1
	v_permlane32_swap_b32_e32 v156, v158
	v_ashrrev_i32_e32 v164, 31, v156
	v_ashrrev_i32_e32 v165, 31, v158
	v_or_b32_e32 v164, 0x80000000, v164
	v_mfma_f32_16x16x32_bf16 v[118:121], v[6:9], v[86:89], v[118:121]
	v_or_b32_e32 v165, 0x80000000, v165
	v_xor_b32_e32 v164, v156, v164
	v_xor_b32_e32 v165, v158, v165
	v_and_b32_e32 v164, 0xffffff00, v164
	v_and_b32_e32 v165, 0xffffff00, v165
	v_cmp_ge_i32_e32 vcc, s5, v242
	s_nop 1
	v_cndmask_b32_e32 v132, 0, v164, vcc
	v_cmp_ge_i32_e32 vcc, s67, v242
	s_nop 1
	v_cndmask_b32_e32 v165, 0, v165, vcc
	global_store_dword v168, v165, s[46:47] offset:3072
	ds_read_b128 v[58:61], v166 offset:57344
	ds_read_b128 v[62:65], v166 offset:59392
	ds_read_b128 v[66:69], v166 offset:61440
	ds_read_b128 v[70:73], v166 offset:63488
	ds_read_b128 v[74:77], v167 offset:57344
	ds_read_b128 v[78:81], v167 offset:59392
	ds_read_b128 v[82:85], v167 offset:61440
	ds_read_b128 v[86:89], v167 offset:63488
	s_waitcnt lgkmcnt(8)
	v_mfma_f32_16x16x32_bf16 v[90:93], v[10:13], v[26:29], 0
	s_sub_i32 s5, s57, 2880
	s_add_i32 s67, s5, 1
	v_med3_f32 v106, v106, 0, v240
	v_med3_f32 v107, v107, 0, v240
	v_med3_f32 v108, v108, 0, v240
	v_med3_f32 v109, v109, 0, v240
	v_mul_f32_e32 v160, v2, v106
	v_mul_f32_e32 v161, v3, v107
	v_mfma_f32_16x16x32_bf16 v[94:97], v[10:13], v[30:33], 0
	v_mul_f32_e32 v162, v4, v108
	v_mul_f32_e32 v163, v5, v109
	v_add_f32_e32 v156, v160, v161
	v_add_f32_e32 v156, v162, v156
	v_add_f32_e32 v156, v163, v156
	v_med3_f32 v110, v110, 0, v240
	v_med3_f32 v111, v111, 0, v240
	v_med3_f32 v112, v112, 0, v240
	v_mfma_f32_16x16x32_bf16 v[98:101], v[10:13], v[34:37], 0
	v_med3_f32 v113, v113, 0, v240
	v_mul_f32_e32 v160, v2, v110
	v_mul_f32_e32 v161, v3, v111
	v_mul_f32_e32 v162, v4, v112
	v_mul_f32_e32 v163, v5, v113
	v_add_f32_e32 v157, v160, v161
	v_add_f32_e32 v157, v162, v157
	v_add_f32_e32 v157, v163, v157
	v_mfma_f32_16x16x32_bf16 v[102:105], v[10:13], v[38:41], 0
	v_med3_f32 v114, v114, 0, v240
	v_med3_f32 v115, v115, 0, v240
	v_med3_f32 v116, v116, 0, v240
	v_med3_f32 v117, v117, 0, v240
	v_mul_f32_e32 v160, v2, v114
	v_mul_f32_e32 v161, v3, v115
	v_mul_f32_e32 v162, v4, v116
	v_mul_f32_e32 v163, v5, v117
	v_mfma_f32_16x16x32_bf16 v[90:93], v[6:9], v[42:45], v[90:93]
	v_add_f32_e32 v158, v160, v161
	v_add_f32_e32 v158, v162, v158
	v_add_f32_e32 v158, v163, v158
	v_med3_f32 v118, v118, 0, v240
	v_med3_f32 v119, v119, 0, v240
	v_med3_f32 v120, v120, 0, v240
	v_med3_f32 v121, v121, 0, v240
	v_mul_f32_e32 v160, v2, v118
	v_mfma_f32_16x16x32_bf16 v[94:97], v[6:9], v[46:49], v[94:97]
	v_mul_f32_e32 v161, v3, v119
	v_mul_f32_e32 v162, v4, v120
	v_mul_f32_e32 v163, v5, v121
	v_add_f32_e32 v159, v160, v161
	v_add_f32_e32 v159, v162, v159
	v_add_f32_e32 v159, v163, v159
	s_nop 1
	v_permlane16_swap_b32_e32 v156, v157
	v_mfma_f32_16x16x32_bf16 v[98:101], v[6:9], v[50:53], v[98:101]
	v_permlane16_swap_b32_e32 v158, v159
	v_add_f32_e32 v156, v156, v157
	v_add_f32_e32 v158, v158, v159
	s_nop 1
	v_permlane32_swap_b32_e32 v156, v158
	v_ashrrev_i32_e32 v164, 31, v156
	v_ashrrev_i32_e32 v165, 31, v158
	v_or_b32_e32 v164, 0x80000000, v164
	v_mfma_f32_16x16x32_bf16 v[102:105], v[6:9], v[54:57], v[102:105]
	v_or_b32_e32 v165, 0x80000000, v165
	v_xor_b32_e32 v164, v156, v164
	v_xor_b32_e32 v165, v158, v165
	v_and_b32_e32 v164, 0xffffff00, v164
	v_and_b32_e32 v165, 0xffffff00, v165
	v_cmp_ge_i32_e32 vcc, s5, v242
	s_nop 1
	v_cndmask_b32_e32 v133, 0, v164, vcc
	v_cmp_ge_i32_e32 vcc, s67, v242
	s_nop 1
	v_cndmask_b32_e32 v165, 0, v165, vcc
	global_store_dword v168, v165, s[46:47] offset:3328
	s_waitcnt lgkmcnt(0)
	v_mfma_f32_16x16x32_bf16 v[106:109], v[10:13], v[58:61], 0
	s_sub_i32 s5, s57, 2944
	s_add_i32 s67, s5, 1
	v_med3_f32 v90, v90, 0, v240
	v_med3_f32 v91, v91, 0, v240
	v_med3_f32 v92, v92, 0, v240
	v_med3_f32 v93, v93, 0, v240
	v_mul_f32_e32 v160, v2, v90
	v_mul_f32_e32 v161, v3, v91
	v_mfma_f32_16x16x32_bf16 v[110:113], v[10:13], v[62:65], 0
	v_mul_f32_e32 v162, v4, v92
	v_mul_f32_e32 v163, v5, v93
	v_add_f32_e32 v156, v160, v161
	v_add_f32_e32 v156, v162, v156
	v_add_f32_e32 v156, v163, v156
	v_med3_f32 v94, v94, 0, v240
	v_med3_f32 v95, v95, 0, v240
	v_med3_f32 v96, v96, 0, v240
	v_mfma_f32_16x16x32_bf16 v[114:117], v[10:13], v[66:69], 0
	v_med3_f32 v97, v97, 0, v240
	v_mul_f32_e32 v160, v2, v94
	v_mul_f32_e32 v161, v3, v95
	v_mul_f32_e32 v162, v4, v96
	v_mul_f32_e32 v163, v5, v97
	v_add_f32_e32 v157, v160, v161
	v_add_f32_e32 v157, v162, v157
	v_add_f32_e32 v157, v163, v157
	v_mfma_f32_16x16x32_bf16 v[118:121], v[10:13], v[70:73], 0
	v_med3_f32 v98, v98, 0, v240
	v_med3_f32 v99, v99, 0, v240
	v_med3_f32 v100, v100, 0, v240
	v_med3_f32 v101, v101, 0, v240
	v_mul_f32_e32 v160, v2, v98
	v_mul_f32_e32 v161, v3, v99
	v_mul_f32_e32 v162, v4, v100
	v_mul_f32_e32 v163, v5, v101
	v_mfma_f32_16x16x32_bf16 v[106:109], v[6:9], v[74:77], v[106:109]
	v_add_f32_e32 v158, v160, v161
	v_add_f32_e32 v158, v162, v158
	v_add_f32_e32 v158, v163, v158
	v_med3_f32 v102, v102, 0, v240
	v_med3_f32 v103, v103, 0, v240
	v_med3_f32 v104, v104, 0, v240
	v_med3_f32 v105, v105, 0, v240
	v_mul_f32_e32 v160, v2, v102
	v_mfma_f32_16x16x32_bf16 v[110:113], v[6:9], v[78:81], v[110:113]
	v_mul_f32_e32 v161, v3, v103
	v_mul_f32_e32 v162, v4, v104
	v_mul_f32_e32 v163, v5, v105
	v_add_f32_e32 v159, v160, v161
	v_add_f32_e32 v159, v162, v159
	v_add_f32_e32 v159, v163, v159
	s_nop 1
	v_permlane16_swap_b32_e32 v156, v157
	v_mfma_f32_16x16x32_bf16 v[114:117], v[6:9], v[82:85], v[114:117]
	v_permlane16_swap_b32_e32 v158, v159
	v_add_f32_e32 v156, v156, v157
	v_add_f32_e32 v158, v158, v159
	s_nop 1
	v_permlane32_swap_b32_e32 v156, v158
	v_ashrrev_i32_e32 v164, 31, v156
	v_ashrrev_i32_e32 v165, 31, v158
	v_or_b32_e32 v164, 0x80000000, v164
	v_mfma_f32_16x16x32_bf16 v[118:121], v[6:9], v[86:89], v[118:121]
	v_or_b32_e32 v165, 0x80000000, v165
	v_xor_b32_e32 v164, v156, v164
	v_xor_b32_e32 v165, v158, v165
	v_and_b32_e32 v164, 0xffffff00, v164
	v_and_b32_e32 v165, 0xffffff00, v165
	v_cmp_ge_i32_e32 vcc, s5, v242
	s_nop 1
	v_cndmask_b32_e32 v134, 0, v164, vcc
	v_cmp_ge_i32_e32 vcc, s67, v242
	s_nop 1
	v_cndmask_b32_e32 v165, 0, v165, vcc
	global_store_dword v168, v165, s[46:47] offset:3584
.Lsc_h12:
	s_cmp_le_u32 s4, 12
	s_cbranch_scc1 .Lsc_drain12
	s_cmp_gt_u32 s4, 14
	s_cbranch_scc0 .Lsc_ni12
	v_lshl_add_u64 v[170:171], s[48:49], 0, v[0:1]
	s_add_i32 m0, s1, 0x10000
	s_nop 0
	global_load_lds_dwordx4 v[170:171], off
	v_lshl_add_u64 v[170:171], s[48:49], 0, v[18:19]
	s_add_i32 m0, s1, 0x12000
	s_nop 0
	global_load_lds_dwordx4 v[170:171], off
	v_lshl_add_u64 v[170:171], s[48:49], 0, v[20:21]
	s_add_i32 m0, s1, 0x14000
	s_nop 0
	global_load_lds_dwordx4 v[170:171], off
	v_lshl_add_u64 v[170:171], s[48:49], 0, v[22:23]
	s_add_i32 m0, s1, 0x16000
	s_nop 0
	global_load_lds_dwordx4 v[170:171], off
	s_add_u32 s48, s48, 0x8000
	s_addc_u32 s49, s49, 0
	s_waitcnt vmcnt(8)
	s_branch .Lsc_b12
.Lsc_ni12:
	s_cmp_gt_u32 s4, 13
	s_cbranch_scc0 .Lsc_w012
	s_waitcnt vmcnt(4)
	s_branch .Lsc_b12

.Lsc_b12:
	s_barrier
	ds_read_b128 v[26:29], v124
	ds_read_b128 v[30:33], v124 offset:2048
	ds_read_b128 v[34:37], v124 offset:4096
	ds_read_b128 v[38:41], v124 offset:6144
	ds_read_b128 v[42:45], v125
	ds_read_b128 v[46:49], v125 offset:2048
	ds_read_b128 v[50:53], v125 offset:4096
	ds_read_b128 v[54:57], v125 offset:6144
	ds_read_b128 v[58:61], v124 offset:8192
	ds_read_b128 v[62:65], v124 offset:10240
	ds_read_b128 v[66:69], v124 offset:12288
	ds_read_b128 v[70:73], v124 offset:14336
	ds_read_b128 v[74:77], v125 offset:8192
	ds_read_b128 v[78:81], v125 offset:10240
	ds_read_b128 v[82:85], v125 offset:12288
	ds_read_b128 v[86:89], v125 offset:14336
	s_sub_i32 s5, s57, 3008
	s_add_i32 s67, s5, 1
	v_med3_f32 v106, v106, 0, v240
	v_med3_f32 v107, v107, 0, v240
	v_med3_f32 v108, v108, 0, v240
	v_med3_f32 v109, v109, 0, v240
	v_mul_f32_e32 v160, v2, v106
	v_mul_f32_e32 v161, v3, v107
	v_mul_f32_e32 v162, v4, v108
	v_mul_f32_e32 v163, v5, v109
	v_add_f32_e32 v156, v160, v161
	v_add_f32_e32 v156, v162, v156
	v_add_f32_e32 v156, v163, v156
	v_med3_f32 v110, v110, 0, v240
	v_med3_f32 v111, v111, 0, v240
	v_med3_f32 v112, v112, 0, v240
	v_med3_f32 v113, v113, 0, v240
	v_mul_f32_e32 v160, v2, v110
	v_mul_f32_e32 v161, v3, v111
	v_mul_f32_e32 v162, v4, v112
	v_mul_f32_e32 v163, v5, v113
	v_add_f32_e32 v157, v160, v161
	v_add_f32_e32 v157, v162, v157
	v_add_f32_e32 v157, v163, v157
	v_med3_f32 v114, v114, 0, v240
	v_med3_f32 v115, v115, 0, v240
	v_med3_f32 v116, v116, 0, v240
	v_med3_f32 v117, v117, 0, v240
	v_mul_f32_e32 v160, v2, v114
	v_mul_f32_e32 v161, v3, v115
	v_mul_f32_e32 v162, v4, v116
	v_mul_f32_e32 v163, v5, v117
	v_add_f32_e32 v158, v160, v161
	v_add_f32_e32 v158, v162, v158
	s_waitcnt lgkmcnt(8)
	v_mfma_f32_16x16x32_bf16 v[90:93], v[10:13], v[26:29], 0
	v_add_f32_e32 v158, v163, v158
	v_med3_f32 v118, v118, 0, v240
	v_med3_f32 v119, v119, 0, v240
	v_med3_f32 v120, v120, 0, v240
	v_mfma_f32_16x16x32_bf16 v[94:97], v[10:13], v[30:33], 0
	v_med3_f32 v121, v121, 0, v240
	v_mul_f32_e32 v160, v2, v118
	v_mul_f32_e32 v161, v3, v119
	v_mul_f32_e32 v162, v4, v120
	v_mfma_f32_16x16x32_bf16 v[98:101], v[10:13], v[34:37], 0
	v_mul_f32_e32 v163, v5, v121
	v_add_f32_e32 v159, v160, v161
	v_add_f32_e32 v159, v162, v159
	v_add_f32_e32 v159, v163, v159
	v_mfma_f32_16x16x32_bf16 v[102:105], v[10:13], v[38:41], 0
	s_nop 1
	v_permlane16_swap_b32_e32 v156, v157
	v_permlane16_swap_b32_e32 v158, v159
	v_add_f32_e32 v156, v156, v157
	v_mfma_f32_16x16x32_bf16 v[90:93], v[6:9], v[42:45], v[90:93]
	v_add_f32_e32 v158, v158, v159
	s_nop 1
	v_permlane32_swap_b32_e32 v156, v158
	v_ashrrev_i32_e32 v164, 31, v156
	v_mfma_f32_16x16x32_bf16 v[94:97], v[6:9], v[46:49], v[94:97]
	v_ashrrev_i32_e32 v165, 31, v158
	v_or_b32_e32 v164, 0x80000000, v164
	v_or_b32_e32 v165, 0x80000000, v165
	v_xor_b32_e32 v164, v156, v164
	v_mfma_f32_16x16x32_bf16 v[98:101], v[6:9], v[50:53], v[98:101]
	v_xor_b32_e32 v165, v158, v165
	v_and_b32_e32 v164, 0xffffff00, v164
	v_and_b32_e32 v165, 0xffffff00, v165
	v_cmp_ge_i32_e32 vcc, s5, v242
	v_mfma_f32_16x16x32_bf16 v[102:105], v[6:9], v[54:57], v[102:105]
	s_nop 1
	v_cndmask_b32_e32 v135, 0, v164, vcc
	v_cmp_ge_i32_e32 vcc, s67, v242
	s_nop 1
	v_cndmask_b32_e32 v165, 0, v165, vcc
	global_store_dword v168, v165, s[46:47] offset:3840
	ds_read_b128 v[26:29], v124 offset:16384
	ds_read_b128 v[30:33], v124 offset:18432
	ds_read_b128 v[34:37], v124 offset:20480
	ds_read_b128 v[38:41], v124 offset:22528
	ds_read_b128 v[42:45], v125 offset:16384
	ds_read_b128 v[46:49], v125 offset:18432
	ds_read_b128 v[50:53], v125 offset:20480
	ds_read_b128 v[54:57], v125 offset:22528
	s_waitcnt lgkmcnt(8)
	v_mfma_f32_16x16x32_bf16 v[106:109], v[10:13], v[58:61], 0
	s_sub_i32 s5, s57, 3072
	s_add_i32 s67, s5, 1
	v_med3_f32 v90, v90, 0, v240
	v_med3_f32 v91, v91, 0, v240
	v_med3_f32 v92, v92, 0, v240
	v_med3_f32 v93, v93, 0, v240
	v_mul_f32_e32 v160, v2, v90
	v_mul_f32_e32 v161, v3, v91
	v_mfma_f32_16x16x32_bf16 v[110:113], v[10:13], v[62:65], 0
	v_mul_f32_e32 v162, v4, v92
	v_mul_f32_e32 v163, v5, v93
	v_add_f32_e32 v156, v160, v161
	v_add_f32_e32 v156, v162, v156
	v_add_f32_e32 v156, v163, v156
	v_med3_f32 v94, v94, 0, v240
	v_med3_f32 v95, v95, 0, v240
	v_med3_f32 v96, v96, 0, v240
	v_mfma_f32_16x16x32_bf16 v[114:117], v[10:13], v[66:69], 0
	v_med3_f32 v97, v97, 0, v240
	v_mul_f32_e32 v160, v2, v94
	v_mul_f32_e32 v161, v3, v95
	v_mul_f32_e32 v162, v4, v96
	v_mul_f32_e32 v163, v5, v97
	v_add_f32_e32 v157, v160, v161
	v_add_f32_e32 v157, v162, v157
	v_add_f32_e32 v157, v163, v157
	v_mfma_f32_16x16x32_bf16 v[118:121], v[10:13], v[70:73], 0
	v_med3_f32 v98, v98, 0, v240
	v_med3_f32 v99, v99, 0, v240
	v_med3_f32 v100, v100, 0, v240
	v_med3_f32 v101, v101, 0, v240
	v_mul_f32_e32 v160, v2, v98
	v_mul_f32_e32 v161, v3, v99
	v_mul_f32_e32 v162, v4, v100
	v_mul_f32_e32 v163, v5, v101
	v_mfma_f32_16x16x32_bf16 v[106:109], v[6:9], v[74:77], v[106:109]
	v_add_f32_e32 v158, v160, v161
	v_add_f32_e32 v158, v162, v158
	v_add_f32_e32 v158, v163, v158
	v_med3_f32 v102, v102, 0, v240
	v_med3_f32 v103, v103, 0, v240
	v_med3_f32 v104, v104, 0, v240
	v_med3_f32 v105, v105, 0, v240
	v_mul_f32_e32 v160, v2, v102
	v_mfma_f32_16x16x32_bf16 v[110:113], v[6:9], v[78:81], v[110:113]
	v_mul_f32_e32 v161, v3, v103
	v_mul_f32_e32 v162, v4, v104
	v_mul_f32_e32 v163, v5, v105
	v_add_f32_e32 v159, v160, v161
	v_add_f32_e32 v159, v162, v159
	v_add_f32_e32 v159, v163, v159
	s_nop 1
	v_permlane16_swap_b32_e32 v156, v157
	v_mfma_f32_16x16x32_bf16 v[114:117], v[6:9], v[82:85], v[114:117]
	v_permlane16_swap_b32_e32 v158, v159
	v_add_f32_e32 v156, v156, v157
	v_add_f32_e32 v158, v158, v159
	s_nop 1
	v_permlane32_swap_b32_e32 v156, v158
	v_ashrrev_i32_e32 v164, 31, v156
	v_ashrrev_i32_e32 v165, 31, v158
	v_or_b32_e32 v164, 0x80000000, v164
	v_mfma_f32_16x16x32_bf16 v[118:121], v[6:9], v[86:89], v[118:121]
	v_or_b32_e32 v165, 0x80000000, v165
	v_xor_b32_e32 v164, v156, v164
	v_xor_b32_e32 v165, v158, v165
	v_and_b32_e32 v164, 0xffffff00, v164
	v_and_b32_e32 v165, 0xffffff00, v165
	v_cmp_ge_i32_e32 vcc, s5, v242
	s_nop 1
	v_cndmask_b32_e32 v136, 0, v164, vcc
	v_cmp_ge_i32_e32 vcc, s67, v242
	s_nop 1
	v_cndmask_b32_e32 v165, 0, v165, vcc
	global_store_dword v168, v165, s[68:69]
	ds_read_b128 v[58:61], v124 offset:24576
	ds_read_b128 v[62:65], v124 offset:26624
	ds_read_b128 v[66:69], v124 offset:28672
	ds_read_b128 v[70:73], v124 offset:30720
	ds_read_b128 v[74:77], v125 offset:24576
	ds_read_b128 v[78:81], v125 offset:26624
	ds_read_b128 v[82:85], v125 offset:28672
	ds_read_b128 v[86:89], v125 offset:30720
	s_waitcnt lgkmcnt(8)
	v_mfma_f32_16x16x32_bf16 v[90:93], v[10:13], v[26:29], 0
	s_sub_i32 s5, s57, 3136
	s_add_i32 s67, s5, 1
	v_med3_f32 v106, v106, 0, v240
	v_med3_f32 v107, v107, 0, v240
	v_med3_f32 v108, v108, 0, v240
	v_med3_f32 v109, v109, 0, v240
	v_mul_f32_e32 v160, v2, v106
	v_mul_f32_e32 v161, v3, v107
	v_mfma_f32_16x16x32_bf16 v[94:97], v[10:13], v[30:33], 0
	v_mul_f32_e32 v162, v4, v108
	v_mul_f32_e32 v163, v5, v109
	v_add_f32_e32 v156, v160, v161
	v_add_f32_e32 v156, v162, v156
	v_add_f32_e32 v156, v163, v156
	v_med3_f32 v110, v110, 0, v240
	v_med3_f32 v111, v111, 0, v240
	v_med3_f32 v112, v112, 0, v240
	v_mfma_f32_16x16x32_bf16 v[98:101], v[10:13], v[34:37], 0
	v_med3_f32 v113, v113, 0, v240
	v_mul_f32_e32 v160, v2, v110
	v_mul_f32_e32 v161, v3, v111
	v_mul_f32_e32 v162, v4, v112
	v_mul_f32_e32 v163, v5, v113
	v_add_f32_e32 v157, v160, v161
	v_add_f32_e32 v157, v162, v157
	v_add_f32_e32 v157, v163, v157
	v_mfma_f32_16x16x32_bf16 v[102:105], v[10:13], v[38:41], 0
	v_med3_f32 v114, v114, 0, v240
	v_med3_f32 v115, v115, 0, v240
	v_med3_f32 v116, v116, 0, v240
	v_med3_f32 v117, v117, 0, v240
	v_mul_f32_e32 v160, v2, v114
	v_mul_f32_e32 v161, v3, v115
	v_mul_f32_e32 v162, v4, v116
	v_mul_f32_e32 v163, v5, v117
	v_mfma_f32_16x16x32_bf16 v[90:93], v[6:9], v[42:45], v[90:93]
	v_add_f32_e32 v158, v160, v161
	v_add_f32_e32 v158, v162, v158
	v_add_f32_e32 v158, v163, v158
	v_med3_f32 v118, v118, 0, v240
	v_med3_f32 v119, v119, 0, v240
	v_med3_f32 v120, v120, 0, v240
	v_med3_f32 v121, v121, 0, v240
	v_mul_f32_e32 v160, v2, v118
	v_mfma_f32_16x16x32_bf16 v[94:97], v[6:9], v[46:49], v[94:97]
	v_mul_f32_e32 v161, v3, v119
	v_mul_f32_e32 v162, v4, v120
	v_mul_f32_e32 v163, v5, v121
	v_add_f32_e32 v159, v160, v161
	v_add_f32_e32 v159, v162, v159
	v_add_f32_e32 v159, v163, v159
	s_nop 1
	v_permlane16_swap_b32_e32 v156, v157
	v_mfma_f32_16x16x32_bf16 v[98:101], v[6:9], v[50:53], v[98:101]
	v_permlane16_swap_b32_e32 v158, v159
	v_add_f32_e32 v156, v156, v157
	v_add_f32_e32 v158, v158, v159
	s_nop 1
	v_permlane32_swap_b32_e32 v156, v158
	v_ashrrev_i32_e32 v164, 31, v156
	v_ashrrev_i32_e32 v165, 31, v158
	v_or_b32_e32 v164, 0x80000000, v164
	v_mfma_f32_16x16x32_bf16 v[102:105], v[6:9], v[54:57], v[102:105]
	v_or_b32_e32 v165, 0x80000000, v165
	v_xor_b32_e32 v164, v156, v164
	v_xor_b32_e32 v165, v158, v165
	v_and_b32_e32 v164, 0xffffff00, v164
	v_and_b32_e32 v165, 0xffffff00, v165
	v_cmp_ge_i32_e32 vcc, s5, v242
	s_nop 1
	v_cndmask_b32_e32 v137, 0, v164, vcc
	v_cmp_ge_i32_e32 vcc, s67, v242
	s_nop 1
	v_cndmask_b32_e32 v165, 0, v165, vcc
	global_store_dword v168, v165, s[68:69] offset:256
	s_waitcnt lgkmcnt(0)
	v_mfma_f32_16x16x32_bf16 v[106:109], v[10:13], v[58:61], 0
	s_sub_i32 s5, s57, 3200
	s_add_i32 s67, s5, 1
	v_med3_f32 v90, v90, 0, v240
	v_med3_f32 v91, v91, 0, v240
	v_med3_f32 v92, v92, 0, v240
	v_med3_f32 v93, v93, 0, v240
	v_mul_f32_e32 v160, v2, v90
	v_mul_f32_e32 v161, v3, v91
	v_mfma_f32_16x16x32_bf16 v[110:113], v[10:13], v[62:65], 0
	v_mul_f32_e32 v162, v4, v92
	v_mul_f32_e32 v163, v5, v93
	v_add_f32_e32 v156, v160, v161
	v_add_f32_e32 v156, v162, v156
	v_add_f32_e32 v156, v163, v156
	v_med3_f32 v94, v94, 0, v240
	v_med3_f32 v95, v95, 0, v240
	v_med3_f32 v96, v96, 0, v240
	v_mfma_f32_16x16x32_bf16 v[114:117], v[10:13], v[66:69], 0
	v_med3_f32 v97, v97, 0, v240
	v_mul_f32_e32 v160, v2, v94
	v_mul_f32_e32 v161, v3, v95
	v_mul_f32_e32 v162, v4, v96
	v_mul_f32_e32 v163, v5, v97
	v_add_f32_e32 v157, v160, v161
	v_add_f32_e32 v157, v162, v157
	v_add_f32_e32 v157, v163, v157
	v_mfma_f32_16x16x32_bf16 v[118:121], v[10:13], v[70:73], 0
	v_med3_f32 v98, v98, 0, v240
	v_med3_f32 v99, v99, 0, v240
	v_med3_f32 v100, v100, 0, v240
	v_med3_f32 v101, v101, 0, v240
	v_mul_f32_e32 v160, v2, v98
	v_mul_f32_e32 v161, v3, v99
	v_mul_f32_e32 v162, v4, v100
	v_mul_f32_e32 v163, v5, v101
	v_mfma_f32_16x16x32_bf16 v[106:109], v[6:9], v[74:77], v[106:109]
	v_add_f32_e32 v158, v160, v161
	v_add_f32_e32 v158, v162, v158
	v_add_f32_e32 v158, v163, v158
	v_med3_f32 v102, v102, 0, v240
	v_med3_f32 v103, v103, 0, v240
	v_med3_f32 v104, v104, 0, v240
	v_med3_f32 v105, v105, 0, v240
	v_mul_f32_e32 v160, v2, v102
	v_mfma_f32_16x16x32_bf16 v[110:113], v[6:9], v[78:81], v[110:113]
	v_mul_f32_e32 v161, v3, v103
	v_mul_f32_e32 v162, v4, v104
	v_mul_f32_e32 v163, v5, v105
	v_add_f32_e32 v159, v160, v161
	v_add_f32_e32 v159, v162, v159
	v_add_f32_e32 v159, v163, v159
	s_nop 1
	v_permlane16_swap_b32_e32 v156, v157
	v_mfma_f32_16x16x32_bf16 v[114:117], v[6:9], v[82:85], v[114:117]
	v_permlane16_swap_b32_e32 v158, v159
	v_add_f32_e32 v156, v156, v157
	v_add_f32_e32 v158, v158, v159
	s_nop 1
	v_permlane32_swap_b32_e32 v156, v158
	v_ashrrev_i32_e32 v164, 31, v156
	v_ashrrev_i32_e32 v165, 31, v158
	v_or_b32_e32 v164, 0x80000000, v164
	v_mfma_f32_16x16x32_bf16 v[118:121], v[6:9], v[86:89], v[118:121]
	v_or_b32_e32 v165, 0x80000000, v165
	v_xor_b32_e32 v164, v156, v164
	v_xor_b32_e32 v165, v158, v165
	v_and_b32_e32 v164, 0xffffff00, v164
	v_and_b32_e32 v165, 0xffffff00, v165
	v_cmp_ge_i32_e32 vcc, s5, v242
	s_nop 1
	v_cndmask_b32_e32 v138, 0, v164, vcc
	v_cmp_ge_i32_e32 vcc, s67, v242
	s_nop 1
	v_cndmask_b32_e32 v165, 0, v165, vcc
	global_store_dword v168, v165, s[68:69] offset:512
.Lsc_h13:
	s_cmp_le_u32 s4, 13
	s_cbranch_scc1 .Lsc_drain13
	s_cmp_gt_u32 s4, 15
	s_cbranch_scc0 .Lsc_ni13
	v_lshl_add_u64 v[170:171], s[48:49], 0, v[0:1]
	s_add_i32 m0, s1, 0x18000
	s_nop 0
	global_load_lds_dwordx4 v[170:171], off
	v_lshl_add_u64 v[170:171], s[48:49], 0, v[18:19]
	s_add_i32 m0, s1, 0x1a000
	s_nop 0
	global_load_lds_dwordx4 v[170:171], off
	v_lshl_add_u64 v[170:171], s[48:49], 0, v[20:21]
	s_add_i32 m0, s1, 0x1c000
	s_nop 0
	global_load_lds_dwordx4 v[170:171], off
	v_lshl_add_u64 v[170:171], s[48:49], 0, v[22:23]
	s_add_i32 m0, s1, 0x1e000
	s_nop 0
	global_load_lds_dwordx4 v[170:171], off
	s_add_u32 s48, s48, 0x8000
	s_addc_u32 s49, s49, 0
	s_waitcnt vmcnt(8)
	s_branch .Lsc_b13
.Lsc_ni13:
	s_cmp_gt_u32 s4, 14
	s_cbranch_scc0 .Lsc_w013
	s_waitcnt vmcnt(4)
	s_branch .Lsc_b13

.Lsc_b13:
	s_barrier
	ds_read_b128 v[26:29], v124 offset:32768
	ds_read_b128 v[30:33], v124 offset:34816
	ds_read_b128 v[34:37], v124 offset:36864
	ds_read_b128 v[38:41], v124 offset:38912
	ds_read_b128 v[42:45], v125 offset:32768
	ds_read_b128 v[46:49], v125 offset:34816
	ds_read_b128 v[50:53], v125 offset:36864
	ds_read_b128 v[54:57], v125 offset:38912
	ds_read_b128 v[58:61], v124 offset:40960
	ds_read_b128 v[62:65], v124 offset:43008
	ds_read_b128 v[66:69], v124 offset:45056
	ds_read_b128 v[70:73], v124 offset:47104
	ds_read_b128 v[74:77], v125 offset:40960
	ds_read_b128 v[78:81], v125 offset:43008
	ds_read_b128 v[82:85], v125 offset:45056
	ds_read_b128 v[86:89], v125 offset:47104
	s_sub_i32 s5, s57, 3264
	s_add_i32 s67, s5, 1
	v_med3_f32 v106, v106, 0, v240
	v_med3_f32 v107, v107, 0, v240
	v_med3_f32 v108, v108, 0, v240
	v_med3_f32 v109, v109, 0, v240
	v_mul_f32_e32 v160, v2, v106
	v_mul_f32_e32 v161, v3, v107
	v_mul_f32_e32 v162, v4, v108
	v_mul_f32_e32 v163, v5, v109
	v_add_f32_e32 v156, v160, v161
	v_add_f32_e32 v156, v162, v156
	v_add_f32_e32 v156, v163, v156
	v_med3_f32 v110, v110, 0, v240
	v_med3_f32 v111, v111, 0, v240
	v_med3_f32 v112, v112, 0, v240
	v_med3_f32 v113, v113, 0, v240
	v_mul_f32_e32 v160, v2, v110
	v_mul_f32_e32 v161, v3, v111
	v_mul_f32_e32 v162, v4, v112
	v_mul_f32_e32 v163, v5, v113
	v_add_f32_e32 v157, v160, v161
	v_add_f32_e32 v157, v162, v157
	v_add_f32_e32 v157, v163, v157
	v_med3_f32 v114, v114, 0, v240
	v_med3_f32 v115, v115, 0, v240
	v_med3_f32 v116, v116, 0, v240
	v_med3_f32 v117, v117, 0, v240
	v_mul_f32_e32 v160, v2, v114
	v_mul_f32_e32 v161, v3, v115
	v_mul_f32_e32 v162, v4, v116
	v_mul_f32_e32 v163, v5, v117
	v_add_f32_e32 v158, v160, v161
	v_add_f32_e32 v158, v162, v158
	s_waitcnt lgkmcnt(8)
	v_mfma_f32_16x16x32_bf16 v[90:93], v[10:13], v[26:29], 0
	v_add_f32_e32 v158, v163, v158
	v_med3_f32 v118, v118, 0, v240
	v_med3_f32 v119, v119, 0, v240
	v_med3_f32 v120, v120, 0, v240
	v_mfma_f32_16x16x32_bf16 v[94:97], v[10:13], v[30:33], 0
	v_med3_f32 v121, v121, 0, v240
	v_mul_f32_e32 v160, v2, v118
	v_mul_f32_e32 v161, v3, v119
	v_mul_f32_e32 v162, v4, v120
	v_mfma_f32_16x16x32_bf16 v[98:101], v[10:13], v[34:37], 0
	v_mul_f32_e32 v163, v5, v121
	v_add_f32_e32 v159, v160, v161
	v_add_f32_e32 v159, v162, v159
	v_add_f32_e32 v159, v163, v159
	v_mfma_f32_16x16x32_bf16 v[102:105], v[10:13], v[38:41], 0
	s_nop 1
	v_permlane16_swap_b32_e32 v156, v157
	v_permlane16_swap_b32_e32 v158, v159
	v_add_f32_e32 v156, v156, v157
	v_mfma_f32_16x16x32_bf16 v[90:93], v[6:9], v[42:45], v[90:93]
	v_add_f32_e32 v158, v158, v159
	s_nop 1
	v_permlane32_swap_b32_e32 v156, v158
	v_ashrrev_i32_e32 v164, 31, v156
	v_mfma_f32_16x16x32_bf16 v[94:97], v[6:9], v[46:49], v[94:97]
	v_ashrrev_i32_e32 v165, 31, v158
	v_or_b32_e32 v164, 0x80000000, v164
	v_or_b32_e32 v165, 0x80000000, v165
	v_xor_b32_e32 v164, v156, v164
	v_mfma_f32_16x16x32_bf16 v[98:101], v[6:9], v[50:53], v[98:101]
	v_xor_b32_e32 v165, v158, v165
	v_and_b32_e32 v164, 0xffffff00, v164
	v_and_b32_e32 v165, 0xffffff00, v165
	v_cmp_ge_i32_e32 vcc, s5, v242
	v_mfma_f32_16x16x32_bf16 v[102:105], v[6:9], v[54:57], v[102:105]
	s_nop 1
	v_cndmask_b32_e32 v139, 0, v164, vcc
	v_cmp_ge_i32_e32 vcc, s67, v242
	s_nop 1
	v_cndmask_b32_e32 v165, 0, v165, vcc
	global_store_dword v168, v165, s[68:69] offset:768
	ds_read_b128 v[26:29], v124 offset:49152
	ds_read_b128 v[30:33], v124 offset:51200
	ds_read_b128 v[34:37], v124 offset:53248
	ds_read_b128 v[38:41], v124 offset:55296
	ds_read_b128 v[42:45], v125 offset:49152
	ds_read_b128 v[46:49], v125 offset:51200
	ds_read_b128 v[50:53], v125 offset:53248
	ds_read_b128 v[54:57], v125 offset:55296
	s_waitcnt lgkmcnt(8)
	v_mfma_f32_16x16x32_bf16 v[106:109], v[10:13], v[58:61], 0
	s_sub_i32 s5, s57, 3328
	s_add_i32 s67, s5, 1
	v_med3_f32 v90, v90, 0, v240
	v_med3_f32 v91, v91, 0, v240
	v_med3_f32 v92, v92, 0, v240
	v_med3_f32 v93, v93, 0, v240
	v_mul_f32_e32 v160, v2, v90
	v_mul_f32_e32 v161, v3, v91
	v_mfma_f32_16x16x32_bf16 v[110:113], v[10:13], v[62:65], 0
	v_mul_f32_e32 v162, v4, v92
	v_mul_f32_e32 v163, v5, v93
	v_add_f32_e32 v156, v160, v161
	v_add_f32_e32 v156, v162, v156
	v_add_f32_e32 v156, v163, v156
	v_med3_f32 v94, v94, 0, v240
	v_med3_f32 v95, v95, 0, v240
	v_med3_f32 v96, v96, 0, v240
	v_mfma_f32_16x16x32_bf16 v[114:117], v[10:13], v[66:69], 0
	v_med3_f32 v97, v97, 0, v240
	v_mul_f32_e32 v160, v2, v94
	v_mul_f32_e32 v161, v3, v95
	v_mul_f32_e32 v162, v4, v96
	v_mul_f32_e32 v163, v5, v97
	v_add_f32_e32 v157, v160, v161
	v_add_f32_e32 v157, v162, v157
	v_add_f32_e32 v157, v163, v157
	v_mfma_f32_16x16x32_bf16 v[118:121], v[10:13], v[70:73], 0
	v_med3_f32 v98, v98, 0, v240
	v_med3_f32 v99, v99, 0, v240
	v_med3_f32 v100, v100, 0, v240
	v_med3_f32 v101, v101, 0, v240
	v_mul_f32_e32 v160, v2, v98
	v_mul_f32_e32 v161, v3, v99
	v_mul_f32_e32 v162, v4, v100
	v_mul_f32_e32 v163, v5, v101
	v_mfma_f32_16x16x32_bf16 v[106:109], v[6:9], v[74:77], v[106:109]
	v_add_f32_e32 v158, v160, v161
	v_add_f32_e32 v158, v162, v158
	v_add_f32_e32 v158, v163, v158
	v_med3_f32 v102, v102, 0, v240
	v_med3_f32 v103, v103, 0, v240
	v_med3_f32 v104, v104, 0, v240
	v_med3_f32 v105, v105, 0, v240
	v_mul_f32_e32 v160, v2, v102
	v_mfma_f32_16x16x32_bf16 v[110:113], v[6:9], v[78:81], v[110:113]
	v_mul_f32_e32 v161, v3, v103
	v_mul_f32_e32 v162, v4, v104
	v_mul_f32_e32 v163, v5, v105
	v_add_f32_e32 v159, v160, v161
	v_add_f32_e32 v159, v162, v159
	v_add_f32_e32 v159, v163, v159
	s_nop 1
	v_permlane16_swap_b32_e32 v156, v157
	v_mfma_f32_16x16x32_bf16 v[114:117], v[6:9], v[82:85], v[114:117]
	v_permlane16_swap_b32_e32 v158, v159
	v_add_f32_e32 v156, v156, v157
	v_add_f32_e32 v158, v158, v159
	s_nop 1
	v_permlane32_swap_b32_e32 v156, v158
	v_ashrrev_i32_e32 v164, 31, v156
	v_ashrrev_i32_e32 v165, 31, v158
	v_or_b32_e32 v164, 0x80000000, v164
	v_mfma_f32_16x16x32_bf16 v[118:121], v[6:9], v[86:89], v[118:121]
	v_or_b32_e32 v165, 0x80000000, v165
	v_xor_b32_e32 v164, v156, v164
	v_xor_b32_e32 v165, v158, v165
	v_and_b32_e32 v164, 0xffffff00, v164
	v_and_b32_e32 v165, 0xffffff00, v165
	v_cmp_ge_i32_e32 vcc, s5, v242
	s_nop 1
	v_cndmask_b32_e32 v140, 0, v164, vcc
	v_cmp_ge_i32_e32 vcc, s67, v242
	s_nop 1
	v_cndmask_b32_e32 v165, 0, v165, vcc
	global_store_dword v168, v165, s[68:69] offset:1024
	ds_read_b128 v[58:61], v124 offset:57344
	ds_read_b128 v[62:65], v124 offset:59392
	ds_read_b128 v[66:69], v124 offset:61440
	ds_read_b128 v[70:73], v124 offset:63488
	ds_read_b128 v[74:77], v125 offset:57344
	ds_read_b128 v[78:81], v125 offset:59392
	ds_read_b128 v[82:85], v125 offset:61440
	ds_read_b128 v[86:89], v125 offset:63488
	s_waitcnt lgkmcnt(8)
	v_mfma_f32_16x16x32_bf16 v[90:93], v[10:13], v[26:29], 0
	s_sub_i32 s5, s57, 3392
	s_add_i32 s67, s5, 1
	v_med3_f32 v106, v106, 0, v240
	v_med3_f32 v107, v107, 0, v240
	v_med3_f32 v108, v108, 0, v240
	v_med3_f32 v109, v109, 0, v240
	v_mul_f32_e32 v160, v2, v106
	v_mul_f32_e32 v161, v3, v107
	v_mfma_f32_16x16x32_bf16 v[94:97], v[10:13], v[30:33], 0
	v_mul_f32_e32 v162, v4, v108
	v_mul_f32_e32 v163, v5, v109
	v_add_f32_e32 v156, v160, v161
	v_add_f32_e32 v156, v162, v156
	v_add_f32_e32 v156, v163, v156
	v_med3_f32 v110, v110, 0, v240
	v_med3_f32 v111, v111, 0, v240
	v_med3_f32 v112, v112, 0, v240
	v_mfma_f32_16x16x32_bf16 v[98:101], v[10:13], v[34:37], 0
	v_med3_f32 v113, v113, 0, v240
	v_mul_f32_e32 v160, v2, v110
	v_mul_f32_e32 v161, v3, v111
	v_mul_f32_e32 v162, v4, v112
	v_mul_f32_e32 v163, v5, v113
	v_add_f32_e32 v157, v160, v161
	v_add_f32_e32 v157, v162, v157
	v_add_f32_e32 v157, v163, v157
	v_mfma_f32_16x16x32_bf16 v[102:105], v[10:13], v[38:41], 0
	v_med3_f32 v114, v114, 0, v240
	v_med3_f32 v115, v115, 0, v240
	v_med3_f32 v116, v116, 0, v240
	v_med3_f32 v117, v117, 0, v240
	v_mul_f32_e32 v160, v2, v114
	v_mul_f32_e32 v161, v3, v115
	v_mul_f32_e32 v162, v4, v116
	v_mul_f32_e32 v163, v5, v117
	v_mfma_f32_16x16x32_bf16 v[90:93], v[6:9], v[42:45], v[90:93]
	v_add_f32_e32 v158, v160, v161
	v_add_f32_e32 v158, v162, v158
	v_add_f32_e32 v158, v163, v158
	v_med3_f32 v118, v118, 0, v240
	v_med3_f32 v119, v119, 0, v240
	v_med3_f32 v120, v120, 0, v240
	v_med3_f32 v121, v121, 0, v240
	v_mul_f32_e32 v160, v2, v118
	v_mfma_f32_16x16x32_bf16 v[94:97], v[6:9], v[46:49], v[94:97]
	v_mul_f32_e32 v161, v3, v119
	v_mul_f32_e32 v162, v4, v120
	v_mul_f32_e32 v163, v5, v121
	v_add_f32_e32 v159, v160, v161
	v_add_f32_e32 v159, v162, v159
	v_add_f32_e32 v159, v163, v159
	s_nop 1
	v_permlane16_swap_b32_e32 v156, v157
	v_mfma_f32_16x16x32_bf16 v[98:101], v[6:9], v[50:53], v[98:101]
	v_permlane16_swap_b32_e32 v158, v159
	v_add_f32_e32 v156, v156, v157
	v_add_f32_e32 v158, v158, v159
	s_nop 1
	v_permlane32_swap_b32_e32 v156, v158
	v_ashrrev_i32_e32 v164, 31, v156
	v_ashrrev_i32_e32 v165, 31, v158
	v_or_b32_e32 v164, 0x80000000, v164
	v_mfma_f32_16x16x32_bf16 v[102:105], v[6:9], v[54:57], v[102:105]
	v_or_b32_e32 v165, 0x80000000, v165
	v_xor_b32_e32 v164, v156, v164
	v_xor_b32_e32 v165, v158, v165
	v_and_b32_e32 v164, 0xffffff00, v164
	v_and_b32_e32 v165, 0xffffff00, v165
	v_cmp_ge_i32_e32 vcc, s5, v242
	s_nop 1
	v_cndmask_b32_e32 v141, 0, v164, vcc
	v_cmp_ge_i32_e32 vcc, s67, v242
	s_nop 1
	v_cndmask_b32_e32 v165, 0, v165, vcc
	global_store_dword v168, v165, s[68:69] offset:1280
	s_waitcnt lgkmcnt(0)
	v_mfma_f32_16x16x32_bf16 v[106:109], v[10:13], v[58:61], 0
	s_sub_i32 s5, s57, 3456
	s_add_i32 s67, s5, 1
	v_med3_f32 v90, v90, 0, v240
	v_med3_f32 v91, v91, 0, v240
	v_med3_f32 v92, v92, 0, v240
	v_med3_f32 v93, v93, 0, v240
	v_mul_f32_e32 v160, v2, v90
	v_mul_f32_e32 v161, v3, v91
	v_mfma_f32_16x16x32_bf16 v[110:113], v[10:13], v[62:65], 0
	v_mul_f32_e32 v162, v4, v92
	v_mul_f32_e32 v163, v5, v93
	v_add_f32_e32 v156, v160, v161
	v_add_f32_e32 v156, v162, v156
	v_add_f32_e32 v156, v163, v156
	v_med3_f32 v94, v94, 0, v240
	v_med3_f32 v95, v95, 0, v240
	v_med3_f32 v96, v96, 0, v240
	v_mfma_f32_16x16x32_bf16 v[114:117], v[10:13], v[66:69], 0
	v_med3_f32 v97, v97, 0, v240
	v_mul_f32_e32 v160, v2, v94
	v_mul_f32_e32 v161, v3, v95
	v_mul_f32_e32 v162, v4, v96
	v_mul_f32_e32 v163, v5, v97
	v_add_f32_e32 v157, v160, v161
	v_add_f32_e32 v157, v162, v157
	v_add_f32_e32 v157, v163, v157
	v_mfma_f32_16x16x32_bf16 v[118:121], v[10:13], v[70:73], 0
	v_med3_f32 v98, v98, 0, v240
	v_med3_f32 v99, v99, 0, v240
	v_med3_f32 v100, v100, 0, v240
	v_med3_f32 v101, v101, 0, v240
	v_mul_f32_e32 v160, v2, v98
	v_mul_f32_e32 v161, v3, v99
	v_mul_f32_e32 v162, v4, v100
	v_mul_f32_e32 v163, v5, v101
	v_mfma_f32_16x16x32_bf16 v[106:109], v[6:9], v[74:77], v[106:109]
	v_add_f32_e32 v158, v160, v161
	v_add_f32_e32 v158, v162, v158
	v_add_f32_e32 v158, v163, v158
	v_med3_f32 v102, v102, 0, v240
	v_med3_f32 v103, v103, 0, v240
	v_med3_f32 v104, v104, 0, v240
	v_med3_f32 v105, v105, 0, v240
	v_mul_f32_e32 v160, v2, v102
	v_mfma_f32_16x16x32_bf16 v[110:113], v[6:9], v[78:81], v[110:113]
	v_mul_f32_e32 v161, v3, v103
	v_mul_f32_e32 v162, v4, v104
	v_mul_f32_e32 v163, v5, v105
	v_add_f32_e32 v159, v160, v161
	v_add_f32_e32 v159, v162, v159
	v_add_f32_e32 v159, v163, v159
	s_nop 1
	v_permlane16_swap_b32_e32 v156, v157
	v_mfma_f32_16x16x32_bf16 v[114:117], v[6:9], v[82:85], v[114:117]
	v_permlane16_swap_b32_e32 v158, v159
	v_add_f32_e32 v156, v156, v157
	v_add_f32_e32 v158, v158, v159
	s_nop 1
	v_permlane32_swap_b32_e32 v156, v158
	v_ashrrev_i32_e32 v164, 31, v156
	v_ashrrev_i32_e32 v165, 31, v158
	v_or_b32_e32 v164, 0x80000000, v164
	v_mfma_f32_16x16x32_bf16 v[118:121], v[6:9], v[86:89], v[118:121]
	v_or_b32_e32 v165, 0x80000000, v165
	v_xor_b32_e32 v164, v156, v164
	v_xor_b32_e32 v165, v158, v165
	v_and_b32_e32 v164, 0xffffff00, v164
	v_and_b32_e32 v165, 0xffffff00, v165
	v_cmp_ge_i32_e32 vcc, s5, v242
	s_nop 1
	v_cndmask_b32_e32 v142, 0, v164, vcc
	v_cmp_ge_i32_e32 vcc, s67, v242
	s_nop 1
	v_cndmask_b32_e32 v165, 0, v165, vcc
	global_store_dword v168, v165, s[68:69] offset:1536
.Lsc_h14:
	s_cmp_le_u32 s4, 14
	s_cbranch_scc1 .Lsc_drain14
	s_cmp_gt_u32 s4, 15
	s_cbranch_scc0 .Lsc_w014
	s_waitcnt vmcnt(4)
	s_branch .Lsc_b14

.Lsc_b14:
	s_barrier
	ds_read_b128 v[26:29], v166
	ds_read_b128 v[30:33], v166 offset:2048
	ds_read_b128 v[34:37], v166 offset:4096
	ds_read_b128 v[38:41], v166 offset:6144
	ds_read_b128 v[42:45], v167
	ds_read_b128 v[46:49], v167 offset:2048
	ds_read_b128 v[50:53], v167 offset:4096
	ds_read_b128 v[54:57], v167 offset:6144
	ds_read_b128 v[58:61], v166 offset:8192
	ds_read_b128 v[62:65], v166 offset:10240
	ds_read_b128 v[66:69], v166 offset:12288
	ds_read_b128 v[70:73], v166 offset:14336
	ds_read_b128 v[74:77], v167 offset:8192
	ds_read_b128 v[78:81], v167 offset:10240
	ds_read_b128 v[82:85], v167 offset:12288
	ds_read_b128 v[86:89], v167 offset:14336
	s_sub_i32 s5, s57, 3520
	s_add_i32 s67, s5, 1
	v_med3_f32 v106, v106, 0, v240
	v_med3_f32 v107, v107, 0, v240
	v_med3_f32 v108, v108, 0, v240
	v_med3_f32 v109, v109, 0, v240
	v_mul_f32_e32 v160, v2, v106
	v_mul_f32_e32 v161, v3, v107
	v_mul_f32_e32 v162, v4, v108
	v_mul_f32_e32 v163, v5, v109
	v_add_f32_e32 v156, v160, v161
	v_add_f32_e32 v156, v162, v156
	v_add_f32_e32 v156, v163, v156
	v_med3_f32 v110, v110, 0, v240
	v_med3_f32 v111, v111, 0, v240
	v_med3_f32 v112, v112, 0, v240
	v_med3_f32 v113, v113, 0, v240
	v_mul_f32_e32 v160, v2, v110
	v_mul_f32_e32 v161, v3, v111
	v_mul_f32_e32 v162, v4, v112
	v_mul_f32_e32 v163, v5, v113
	v_add_f32_e32 v157, v160, v161
	v_add_f32_e32 v157, v162, v157
	v_add_f32_e32 v157, v163, v157
	v_med3_f32 v114, v114, 0, v240
	v_med3_f32 v115, v115, 0, v240
	v_med3_f32 v116, v116, 0, v240
	v_med3_f32 v117, v117, 0, v240
	v_mul_f32_e32 v160, v2, v114
	v_mul_f32_e32 v161, v3, v115
	v_mul_f32_e32 v162, v4, v116
	v_mul_f32_e32 v163, v5, v117
	v_add_f32_e32 v158, v160, v161
	v_add_f32_e32 v158, v162, v158
	s_waitcnt lgkmcnt(8)
	v_mfma_f32_16x16x32_bf16 v[90:93], v[10:13], v[26:29], 0
	v_add_f32_e32 v158, v163, v158
	v_med3_f32 v118, v118, 0, v240
	v_med3_f32 v119, v119, 0, v240
	v_med3_f32 v120, v120, 0, v240
	v_mfma_f32_16x16x32_bf16 v[94:97], v[10:13], v[30:33], 0
	v_med3_f32 v121, v121, 0, v240
	v_mul_f32_e32 v160, v2, v118
	v_mul_f32_e32 v161, v3, v119
	v_mul_f32_e32 v162, v4, v120
	v_mfma_f32_16x16x32_bf16 v[98:101], v[10:13], v[34:37], 0
	v_mul_f32_e32 v163, v5, v121
	v_add_f32_e32 v159, v160, v161
	v_add_f32_e32 v159, v162, v159
	v_add_f32_e32 v159, v163, v159
	v_mfma_f32_16x16x32_bf16 v[102:105], v[10:13], v[38:41], 0
	s_nop 1
	v_permlane16_swap_b32_e32 v156, v157
	v_permlane16_swap_b32_e32 v158, v159
	v_add_f32_e32 v156, v156, v157
	v_mfma_f32_16x16x32_bf16 v[90:93], v[6:9], v[42:45], v[90:93]
	v_add_f32_e32 v158, v158, v159
	s_nop 1
	v_permlane32_swap_b32_e32 v156, v158
	v_ashrrev_i32_e32 v164, 31, v156
	v_mfma_f32_16x16x32_bf16 v[94:97], v[6:9], v[46:49], v[94:97]
	v_ashrrev_i32_e32 v165, 31, v158
	v_or_b32_e32 v164, 0x80000000, v164
	v_or_b32_e32 v165, 0x80000000, v165
	v_xor_b32_e32 v164, v156, v164
	v_mfma_f32_16x16x32_bf16 v[98:101], v[6:9], v[50:53], v[98:101]
	v_xor_b32_e32 v165, v158, v165
	v_and_b32_e32 v164, 0xffffff00, v164
	v_and_b32_e32 v165, 0xffffff00, v165
	v_cmp_ge_i32_e32 vcc, s5, v242
	v_mfma_f32_16x16x32_bf16 v[102:105], v[6:9], v[54:57], v[102:105]
	s_nop 1
	v_cndmask_b32_e32 v143, 0, v164, vcc
	v_cmp_ge_i32_e32 vcc, s67, v242
	s_nop 1
	v_cndmask_b32_e32 v165, 0, v165, vcc
	global_store_dword v168, v165, s[68:69] offset:1792
	ds_read_b128 v[26:29], v166 offset:16384
	ds_read_b128 v[30:33], v166 offset:18432
	ds_read_b128 v[34:37], v166 offset:20480
	ds_read_b128 v[38:41], v166 offset:22528
	ds_read_b128 v[42:45], v167 offset:16384
	ds_read_b128 v[46:49], v167 offset:18432
	ds_read_b128 v[50:53], v167 offset:20480
	ds_read_b128 v[54:57], v167 offset:22528
	s_waitcnt lgkmcnt(8)
	v_mfma_f32_16x16x32_bf16 v[106:109], v[10:13], v[58:61], 0
	s_sub_i32 s5, s57, 3584
	s_add_i32 s67, s5, 1
	v_med3_f32 v90, v90, 0, v240
	v_med3_f32 v91, v91, 0, v240
	v_med3_f32 v92, v92, 0, v240
	v_med3_f32 v93, v93, 0, v240
	v_mul_f32_e32 v160, v2, v90
	v_mul_f32_e32 v161, v3, v91
	v_mfma_f32_16x16x32_bf16 v[110:113], v[10:13], v[62:65], 0
	v_mul_f32_e32 v162, v4, v92
	v_mul_f32_e32 v163, v5, v93
	v_add_f32_e32 v156, v160, v161
	v_add_f32_e32 v156, v162, v156
	v_add_f32_e32 v156, v163, v156
	v_med3_f32 v94, v94, 0, v240
	v_med3_f32 v95, v95, 0, v240
	v_med3_f32 v96, v96, 0, v240
	v_mfma_f32_16x16x32_bf16 v[114:117], v[10:13], v[66:69], 0
	v_med3_f32 v97, v97, 0, v240
	v_mul_f32_e32 v160, v2, v94
	v_mul_f32_e32 v161, v3, v95
	v_mul_f32_e32 v162, v4, v96
	v_mul_f32_e32 v163, v5, v97
	v_add_f32_e32 v157, v160, v161
	v_add_f32_e32 v157, v162, v157
	v_add_f32_e32 v157, v163, v157
	v_mfma_f32_16x16x32_bf16 v[118:121], v[10:13], v[70:73], 0
	v_med3_f32 v98, v98, 0, v240
	v_med3_f32 v99, v99, 0, v240
	v_med3_f32 v100, v100, 0, v240
	v_med3_f32 v101, v101, 0, v240
	v_mul_f32_e32 v160, v2, v98
	v_mul_f32_e32 v161, v3, v99
	v_mul_f32_e32 v162, v4, v100
	v_mul_f32_e32 v163, v5, v101
	v_mfma_f32_16x16x32_bf16 v[106:109], v[6:9], v[74:77], v[106:109]
	v_add_f32_e32 v158, v160, v161
	v_add_f32_e32 v158, v162, v158
	v_add_f32_e32 v158, v163, v158
	v_med3_f32 v102, v102, 0, v240
	v_med3_f32 v103, v103, 0, v240
	v_med3_f32 v104, v104, 0, v240
	v_med3_f32 v105, v105, 0, v240
	v_mul_f32_e32 v160, v2, v102
	v_mfma_f32_16x16x32_bf16 v[110:113], v[6:9], v[78:81], v[110:113]
	v_mul_f32_e32 v161, v3, v103
	v_mul_f32_e32 v162, v4, v104
	v_mul_f32_e32 v163, v5, v105
	v_add_f32_e32 v159, v160, v161
	v_add_f32_e32 v159, v162, v159
	v_add_f32_e32 v159, v163, v159
	s_nop 1
	v_permlane16_swap_b32_e32 v156, v157
	v_mfma_f32_16x16x32_bf16 v[114:117], v[6:9], v[82:85], v[114:117]
	v_permlane16_swap_b32_e32 v158, v159
	v_add_f32_e32 v156, v156, v157
	v_add_f32_e32 v158, v158, v159
	s_nop 1
	v_permlane32_swap_b32_e32 v156, v158
	v_ashrrev_i32_e32 v164, 31, v156
	v_ashrrev_i32_e32 v165, 31, v158
	v_or_b32_e32 v164, 0x80000000, v164
	v_mfma_f32_16x16x32_bf16 v[118:121], v[6:9], v[86:89], v[118:121]
	v_or_b32_e32 v165, 0x80000000, v165
	v_xor_b32_e32 v164, v156, v164
	v_xor_b32_e32 v165, v158, v165
	v_and_b32_e32 v164, 0xffffff00, v164
	v_and_b32_e32 v165, 0xffffff00, v165
	v_cmp_ge_i32_e32 vcc, s5, v242
	s_nop 1
	v_cndmask_b32_e32 v144, 0, v164, vcc
	v_cmp_ge_i32_e32 vcc, s67, v242
	s_nop 1
	v_cndmask_b32_e32 v165, 0, v165, vcc
	global_store_dword v168, v165, s[68:69] offset:2048
	ds_read_b128 v[58:61], v166 offset:24576
	ds_read_b128 v[62:65], v166 offset:26624
	ds_read_b128 v[66:69], v166 offset:28672
	ds_read_b128 v[70:73], v166 offset:30720
	ds_read_b128 v[74:77], v167 offset:24576
	ds_read_b128 v[78:81], v167 offset:26624
	ds_read_b128 v[82:85], v167 offset:28672
	ds_read_b128 v[86:89], v167 offset:30720
	s_waitcnt lgkmcnt(8)
	v_mfma_f32_16x16x32_bf16 v[90:93], v[10:13], v[26:29], 0
	s_sub_i32 s5, s57, 3648
	s_add_i32 s67, s5, 1
	v_med3_f32 v106, v106, 0, v240
	v_med3_f32 v107, v107, 0, v240
	v_med3_f32 v108, v108, 0, v240
	v_med3_f32 v109, v109, 0, v240
	v_mul_f32_e32 v160, v2, v106
	v_mul_f32_e32 v161, v3, v107
	v_mfma_f32_16x16x32_bf16 v[94:97], v[10:13], v[30:33], 0
	v_mul_f32_e32 v162, v4, v108
	v_mul_f32_e32 v163, v5, v109
	v_add_f32_e32 v156, v160, v161
	v_add_f32_e32 v156, v162, v156
	v_add_f32_e32 v156, v163, v156
	v_med3_f32 v110, v110, 0, v240
	v_med3_f32 v111, v111, 0, v240
	v_med3_f32 v112, v112, 0, v240
	v_mfma_f32_16x16x32_bf16 v[98:101], v[10:13], v[34:37], 0
	v_med3_f32 v113, v113, 0, v240
	v_mul_f32_e32 v160, v2, v110
	v_mul_f32_e32 v161, v3, v111
	v_mul_f32_e32 v162, v4, v112
	v_mul_f32_e32 v163, v5, v113
	v_add_f32_e32 v157, v160, v161
	v_add_f32_e32 v157, v162, v157
	v_add_f32_e32 v157, v163, v157
	v_mfma_f32_16x16x32_bf16 v[102:105], v[10:13], v[38:41], 0
	v_med3_f32 v114, v114, 0, v240
	v_med3_f32 v115, v115, 0, v240
	v_med3_f32 v116, v116, 0, v240
	v_med3_f32 v117, v117, 0, v240
	v_mul_f32_e32 v160, v2, v114
	v_mul_f32_e32 v161, v3, v115
	v_mul_f32_e32 v162, v4, v116
	v_mul_f32_e32 v163, v5, v117
	v_mfma_f32_16x16x32_bf16 v[90:93], v[6:9], v[42:45], v[90:93]
	v_add_f32_e32 v158, v160, v161
	v_add_f32_e32 v158, v162, v158
	v_add_f32_e32 v158, v163, v158
	v_med3_f32 v118, v118, 0, v240
	v_med3_f32 v119, v119, 0, v240
	v_med3_f32 v120, v120, 0, v240
	v_med3_f32 v121, v121, 0, v240
	v_mul_f32_e32 v160, v2, v118
	v_mfma_f32_16x16x32_bf16 v[94:97], v[6:9], v[46:49], v[94:97]
	v_mul_f32_e32 v161, v3, v119
	v_mul_f32_e32 v162, v4, v120
	v_mul_f32_e32 v163, v5, v121
	v_add_f32_e32 v159, v160, v161
	v_add_f32_e32 v159, v162, v159
	v_add_f32_e32 v159, v163, v159
	s_nop 1
	v_permlane16_swap_b32_e32 v156, v157
	v_mfma_f32_16x16x32_bf16 v[98:101], v[6:9], v[50:53], v[98:101]
	v_permlane16_swap_b32_e32 v158, v159
	v_add_f32_e32 v156, v156, v157
	v_add_f32_e32 v158, v158, v159
	s_nop 1
	v_permlane32_swap_b32_e32 v156, v158
	v_ashrrev_i32_e32 v164, 31, v156
	v_ashrrev_i32_e32 v165, 31, v158
	v_or_b32_e32 v164, 0x80000000, v164
	v_mfma_f32_16x16x32_bf16 v[102:105], v[6:9], v[54:57], v[102:105]
	v_or_b32_e32 v165, 0x80000000, v165
	v_xor_b32_e32 v164, v156, v164
	v_xor_b32_e32 v165, v158, v165
	v_and_b32_e32 v164, 0xffffff00, v164
	v_and_b32_e32 v165, 0xffffff00, v165
	v_cmp_ge_i32_e32 vcc, s5, v242
	s_nop 1
	v_cndmask_b32_e32 v145, 0, v164, vcc
	v_cmp_ge_i32_e32 vcc, s67, v242
	s_nop 1
	v_cndmask_b32_e32 v165, 0, v165, vcc
	global_store_dword v168, v165, s[68:69] offset:2304
	s_waitcnt lgkmcnt(0)
	v_mfma_f32_16x16x32_bf16 v[106:109], v[10:13], v[58:61], 0
	s_sub_i32 s5, s57, 3712
	s_add_i32 s67, s5, 1
	v_med3_f32 v90, v90, 0, v240
	v_med3_f32 v91, v91, 0, v240
	v_med3_f32 v92, v92, 0, v240
	v_med3_f32 v93, v93, 0, v240
	v_mul_f32_e32 v160, v2, v90
	v_mul_f32_e32 v161, v3, v91
	v_mfma_f32_16x16x32_bf16 v[110:113], v[10:13], v[62:65], 0
	v_mul_f32_e32 v162, v4, v92
	v_mul_f32_e32 v163, v5, v93
	v_add_f32_e32 v156, v160, v161
	v_add_f32_e32 v156, v162, v156
	v_add_f32_e32 v156, v163, v156
	v_med3_f32 v94, v94, 0, v240
	v_med3_f32 v95, v95, 0, v240
	v_med3_f32 v96, v96, 0, v240
	v_mfma_f32_16x16x32_bf16 v[114:117], v[10:13], v[66:69], 0
	v_med3_f32 v97, v97, 0, v240
	v_mul_f32_e32 v160, v2, v94
	v_mul_f32_e32 v161, v3, v95
	v_mul_f32_e32 v162, v4, v96
	v_mul_f32_e32 v163, v5, v97
	v_add_f32_e32 v157, v160, v161
	v_add_f32_e32 v157, v162, v157
	v_add_f32_e32 v157, v163, v157
	v_mfma_f32_16x16x32_bf16 v[118:121], v[10:13], v[70:73], 0
	v_med3_f32 v98, v98, 0, v240
	v_med3_f32 v99, v99, 0, v240
	v_med3_f32 v100, v100, 0, v240
	v_med3_f32 v101, v101, 0, v240
	v_mul_f32_e32 v160, v2, v98
	v_mul_f32_e32 v161, v3, v99
	v_mul_f32_e32 v162, v4, v100
	v_mul_f32_e32 v163, v5, v101
	v_mfma_f32_16x16x32_bf16 v[106:109], v[6:9], v[74:77], v[106:109]
	v_add_f32_e32 v158, v160, v161
	v_add_f32_e32 v158, v162, v158
	v_add_f32_e32 v158, v163, v158
	v_med3_f32 v102, v102, 0, v240
	v_med3_f32 v103, v103, 0, v240
	v_med3_f32 v104, v104, 0, v240
	v_med3_f32 v105, v105, 0, v240
	v_mul_f32_e32 v160, v2, v102
	v_mfma_f32_16x16x32_bf16 v[110:113], v[6:9], v[78:81], v[110:113]
	v_mul_f32_e32 v161, v3, v103
	v_mul_f32_e32 v162, v4, v104
	v_mul_f32_e32 v163, v5, v105
	v_add_f32_e32 v159, v160, v161
	v_add_f32_e32 v159, v162, v159
	v_add_f32_e32 v159, v163, v159
	s_nop 1
	v_permlane16_swap_b32_e32 v156, v157
	v_mfma_f32_16x16x32_bf16 v[114:117], v[6:9], v[82:85], v[114:117]
	v_permlane16_swap_b32_e32 v158, v159
	v_add_f32_e32 v156, v156, v157
	v_add_f32_e32 v158, v158, v159
	s_nop 1
	v_permlane32_swap_b32_e32 v156, v158
	v_ashrrev_i32_e32 v164, 31, v156
	v_ashrrev_i32_e32 v165, 31, v158
	v_or_b32_e32 v164, 0x80000000, v164
	v_mfma_f32_16x16x32_bf16 v[118:121], v[6:9], v[86:89], v[118:121]
	v_or_b32_e32 v165, 0x80000000, v165
	v_xor_b32_e32 v164, v156, v164
	v_xor_b32_e32 v165, v158, v165
	v_and_b32_e32 v164, 0xffffff00, v164
	v_and_b32_e32 v165, 0xffffff00, v165
	v_cmp_ge_i32_e32 vcc, s5, v242
	s_nop 1
	v_cndmask_b32_e32 v146, 0, v164, vcc
	v_cmp_ge_i32_e32 vcc, s67, v242
	s_nop 1
	v_cndmask_b32_e32 v165, 0, v165, vcc
	global_store_dword v168, v165, s[68:69] offset:2560
.Lsc_h15:
	s_cmp_le_u32 s4, 15
	s_cbranch_scc1 .Lsc_drain15
	s_waitcnt vmcnt(0)
.Lsc_b15:
	s_barrier
	ds_read_b128 v[26:29], v166 offset:32768
	ds_read_b128 v[30:33], v166 offset:34816
	ds_read_b128 v[34:37], v166 offset:36864
	ds_read_b128 v[38:41], v166 offset:38912
	ds_read_b128 v[42:45], v167 offset:32768
	ds_read_b128 v[46:49], v167 offset:34816
	ds_read_b128 v[50:53], v167 offset:36864
	ds_read_b128 v[54:57], v167 offset:38912
	ds_read_b128 v[58:61], v166 offset:40960
	ds_read_b128 v[62:65], v166 offset:43008
	ds_read_b128 v[66:69], v166 offset:45056
	ds_read_b128 v[70:73], v166 offset:47104
	ds_read_b128 v[74:77], v167 offset:40960
	ds_read_b128 v[78:81], v167 offset:43008
	ds_read_b128 v[82:85], v167 offset:45056
	ds_read_b128 v[86:89], v167 offset:47104
	s_sub_i32 s5, s57, 3776
	s_add_i32 s67, s5, 1
	v_med3_f32 v106, v106, 0, v240
	v_med3_f32 v107, v107, 0, v240
	v_med3_f32 v108, v108, 0, v240
	v_med3_f32 v109, v109, 0, v240
	v_mul_f32_e32 v160, v2, v106
	v_mul_f32_e32 v161, v3, v107
	v_mul_f32_e32 v162, v4, v108
	v_mul_f32_e32 v163, v5, v109
	v_add_f32_e32 v156, v160, v161
	v_add_f32_e32 v156, v162, v156
	v_add_f32_e32 v156, v163, v156
	v_med3_f32 v110, v110, 0, v240
	v_med3_f32 v111, v111, 0, v240
	v_med3_f32 v112, v112, 0, v240
	v_med3_f32 v113, v113, 0, v240
	v_mul_f32_e32 v160, v2, v110
	v_mul_f32_e32 v161, v3, v111
	v_mul_f32_e32 v162, v4, v112
	v_mul_f32_e32 v163, v5, v113
	v_add_f32_e32 v157, v160, v161
	v_add_f32_e32 v157, v162, v157
	v_add_f32_e32 v157, v163, v157
	v_med3_f32 v114, v114, 0, v240
	v_med3_f32 v115, v115, 0, v240
	v_med3_f32 v116, v116, 0, v240
	v_med3_f32 v117, v117, 0, v240
	v_mul_f32_e32 v160, v2, v114
	v_mul_f32_e32 v161, v3, v115
	v_mul_f32_e32 v162, v4, v116
	v_mul_f32_e32 v163, v5, v117
	v_add_f32_e32 v158, v160, v161
	v_add_f32_e32 v158, v162, v158
	s_waitcnt lgkmcnt(8)
	v_mfma_f32_16x16x32_bf16 v[90:93], v[10:13], v[26:29], 0
	v_add_f32_e32 v158, v163, v158
	v_med3_f32 v118, v118, 0, v240
	v_med3_f32 v119, v119, 0, v240
	v_med3_f32 v120, v120, 0, v240
	v_mfma_f32_16x16x32_bf16 v[94:97], v[10:13], v[30:33], 0
	v_med3_f32 v121, v121, 0, v240
	v_mul_f32_e32 v160, v2, v118
	v_mul_f32_e32 v161, v3, v119
	v_mul_f32_e32 v162, v4, v120
	v_mfma_f32_16x16x32_bf16 v[98:101], v[10:13], v[34:37], 0
	v_mul_f32_e32 v163, v5, v121
	v_add_f32_e32 v159, v160, v161
	v_add_f32_e32 v159, v162, v159
	v_add_f32_e32 v159, v163, v159
	v_mfma_f32_16x16x32_bf16 v[102:105], v[10:13], v[38:41], 0
	s_nop 1
	v_permlane16_swap_b32_e32 v156, v157
	v_permlane16_swap_b32_e32 v158, v159
	v_add_f32_e32 v156, v156, v157
	v_mfma_f32_16x16x32_bf16 v[90:93], v[6:9], v[42:45], v[90:93]
	v_add_f32_e32 v158, v158, v159
	s_nop 1
	v_permlane32_swap_b32_e32 v156, v158
	v_ashrrev_i32_e32 v164, 31, v156
	v_mfma_f32_16x16x32_bf16 v[94:97], v[6:9], v[46:49], v[94:97]
	v_ashrrev_i32_e32 v165, 31, v158
	v_or_b32_e32 v164, 0x80000000, v164
	v_or_b32_e32 v165, 0x80000000, v165
	v_xor_b32_e32 v164, v156, v164
	v_mfma_f32_16x16x32_bf16 v[98:101], v[6:9], v[50:53], v[98:101]
	v_xor_b32_e32 v165, v158, v165
	v_and_b32_e32 v164, 0xffffff00, v164
	v_and_b32_e32 v165, 0xffffff00, v165
	v_cmp_ge_i32_e32 vcc, s5, v242
	v_mfma_f32_16x16x32_bf16 v[102:105], v[6:9], v[54:57], v[102:105]
	s_nop 1
	v_cndmask_b32_e32 v147, 0, v164, vcc
	v_cmp_ge_i32_e32 vcc, s67, v242
	s_nop 1
	v_cndmask_b32_e32 v165, 0, v165, vcc
	global_store_dword v168, v165, s[68:69] offset:2816
	ds_read_b128 v[26:29], v166 offset:49152
	ds_read_b128 v[30:33], v166 offset:51200
	ds_read_b128 v[34:37], v166 offset:53248
	ds_read_b128 v[38:41], v166 offset:55296
	ds_read_b128 v[42:45], v167 offset:49152
	ds_read_b128 v[46:49], v167 offset:51200
	ds_read_b128 v[50:53], v167 offset:53248
	ds_read_b128 v[54:57], v167 offset:55296
	s_waitcnt lgkmcnt(8)
	v_mfma_f32_16x16x32_bf16 v[106:109], v[10:13], v[58:61], 0
	s_sub_i32 s5, s57, 3840
	s_add_i32 s67, s5, 1
	v_med3_f32 v90, v90, 0, v240
	v_med3_f32 v91, v91, 0, v240
	v_med3_f32 v92, v92, 0, v240
	v_med3_f32 v93, v93, 0, v240
	v_mul_f32_e32 v160, v2, v90
	v_mul_f32_e32 v161, v3, v91
	v_mfma_f32_16x16x32_bf16 v[110:113], v[10:13], v[62:65], 0
	v_mul_f32_e32 v162, v4, v92
	v_mul_f32_e32 v163, v5, v93
	v_add_f32_e32 v156, v160, v161
	v_add_f32_e32 v156, v162, v156
	v_add_f32_e32 v156, v163, v156
	v_med3_f32 v94, v94, 0, v240
	v_med3_f32 v95, v95, 0, v240
	v_med3_f32 v96, v96, 0, v240
	v_mfma_f32_16x16x32_bf16 v[114:117], v[10:13], v[66:69], 0
	v_med3_f32 v97, v97, 0, v240
	v_mul_f32_e32 v160, v2, v94
	v_mul_f32_e32 v161, v3, v95
	v_mul_f32_e32 v162, v4, v96
	v_mul_f32_e32 v163, v5, v97
	v_add_f32_e32 v157, v160, v161
	v_add_f32_e32 v157, v162, v157
	v_add_f32_e32 v157, v163, v157
	v_mfma_f32_16x16x32_bf16 v[118:121], v[10:13], v[70:73], 0
	v_med3_f32 v98, v98, 0, v240
	v_med3_f32 v99, v99, 0, v240
	v_med3_f32 v100, v100, 0, v240
	v_med3_f32 v101, v101, 0, v240
	v_mul_f32_e32 v160, v2, v98
	v_mul_f32_e32 v161, v3, v99
	v_mul_f32_e32 v162, v4, v100
	v_mul_f32_e32 v163, v5, v101
	v_mfma_f32_16x16x32_bf16 v[106:109], v[6:9], v[74:77], v[106:109]
	v_add_f32_e32 v158, v160, v161
	v_add_f32_e32 v158, v162, v158
	v_add_f32_e32 v158, v163, v158
	v_med3_f32 v102, v102, 0, v240
	v_med3_f32 v103, v103, 0, v240
	v_med3_f32 v104, v104, 0, v240
	v_med3_f32 v105, v105, 0, v240
	v_mul_f32_e32 v160, v2, v102
	v_mfma_f32_16x16x32_bf16 v[110:113], v[6:9], v[78:81], v[110:113]
	v_mul_f32_e32 v161, v3, v103
	v_mul_f32_e32 v162, v4, v104
	v_mul_f32_e32 v163, v5, v105
	v_add_f32_e32 v159, v160, v161
	v_add_f32_e32 v159, v162, v159
	v_add_f32_e32 v159, v163, v159
	s_nop 1
	v_permlane16_swap_b32_e32 v156, v157
	v_mfma_f32_16x16x32_bf16 v[114:117], v[6:9], v[82:85], v[114:117]
	v_permlane16_swap_b32_e32 v158, v159
	v_add_f32_e32 v156, v156, v157
	v_add_f32_e32 v158, v158, v159
	s_nop 1
	v_permlane32_swap_b32_e32 v156, v158
	v_ashrrev_i32_e32 v164, 31, v156
	v_ashrrev_i32_e32 v165, 31, v158
	v_or_b32_e32 v164, 0x80000000, v164
	v_mfma_f32_16x16x32_bf16 v[118:121], v[6:9], v[86:89], v[118:121]
	v_or_b32_e32 v165, 0x80000000, v165
	v_xor_b32_e32 v164, v156, v164
	v_xor_b32_e32 v165, v158, v165
	v_and_b32_e32 v164, 0xffffff00, v164
	v_and_b32_e32 v165, 0xffffff00, v165
	v_cmp_ge_i32_e32 vcc, s5, v242
	s_nop 1
	v_cndmask_b32_e32 v148, 0, v164, vcc
	v_cmp_ge_i32_e32 vcc, s67, v242
	s_nop 1
	v_cndmask_b32_e32 v165, 0, v165, vcc
	global_store_dword v168, v165, s[68:69] offset:3072
	ds_read_b128 v[58:61], v166 offset:57344
	ds_read_b128 v[62:65], v166 offset:59392
	ds_read_b128 v[66:69], v166 offset:61440
	ds_read_b128 v[70:73], v166 offset:63488
	ds_read_b128 v[74:77], v167 offset:57344
	ds_read_b128 v[78:81], v167 offset:59392
	ds_read_b128 v[82:85], v167 offset:61440
	ds_read_b128 v[86:89], v167 offset:63488
	s_waitcnt lgkmcnt(8)
	v_mfma_f32_16x16x32_bf16 v[90:93], v[10:13], v[26:29], 0
	s_sub_i32 s5, s57, 3904
	s_add_i32 s67, s5, 1
	v_med3_f32 v106, v106, 0, v240
	v_med3_f32 v107, v107, 0, v240
	v_med3_f32 v108, v108, 0, v240
	v_med3_f32 v109, v109, 0, v240
	v_mul_f32_e32 v160, v2, v106
	v_mul_f32_e32 v161, v3, v107
	v_mfma_f32_16x16x32_bf16 v[94:97], v[10:13], v[30:33], 0
	v_mul_f32_e32 v162, v4, v108
	v_mul_f32_e32 v163, v5, v109
	v_add_f32_e32 v156, v160, v161
	v_add_f32_e32 v156, v162, v156
	v_add_f32_e32 v156, v163, v156
	v_med3_f32 v110, v110, 0, v240
	v_med3_f32 v111, v111, 0, v240
	v_med3_f32 v112, v112, 0, v240
	v_mfma_f32_16x16x32_bf16 v[98:101], v[10:13], v[34:37], 0
	v_med3_f32 v113, v113, 0, v240
	v_mul_f32_e32 v160, v2, v110
	v_mul_f32_e32 v161, v3, v111
	v_mul_f32_e32 v162, v4, v112
	v_mul_f32_e32 v163, v5, v113
	v_add_f32_e32 v157, v160, v161
	v_add_f32_e32 v157, v162, v157
	v_add_f32_e32 v157, v163, v157
	v_mfma_f32_16x16x32_bf16 v[102:105], v[10:13], v[38:41], 0
	v_med3_f32 v114, v114, 0, v240
	v_med3_f32 v115, v115, 0, v240
	v_med3_f32 v116, v116, 0, v240
	v_med3_f32 v117, v117, 0, v240
	v_mul_f32_e32 v160, v2, v114
	v_mul_f32_e32 v161, v3, v115
	v_mul_f32_e32 v162, v4, v116
	v_mul_f32_e32 v163, v5, v117
	v_mfma_f32_16x16x32_bf16 v[90:93], v[6:9], v[42:45], v[90:93]
	v_add_f32_e32 v158, v160, v161
	v_add_f32_e32 v158, v162, v158
	v_add_f32_e32 v158, v163, v158
	v_med3_f32 v118, v118, 0, v240
	v_med3_f32 v119, v119, 0, v240
	v_med3_f32 v120, v120, 0, v240
	v_med3_f32 v121, v121, 0, v240
	v_mul_f32_e32 v160, v2, v118
	v_mfma_f32_16x16x32_bf16 v[94:97], v[6:9], v[46:49], v[94:97]
	v_mul_f32_e32 v161, v3, v119
	v_mul_f32_e32 v162, v4, v120
	v_mul_f32_e32 v163, v5, v121
	v_add_f32_e32 v159, v160, v161
	v_add_f32_e32 v159, v162, v159
	v_add_f32_e32 v159, v163, v159
	s_nop 1
	v_permlane16_swap_b32_e32 v156, v157
	v_mfma_f32_16x16x32_bf16 v[98:101], v[6:9], v[50:53], v[98:101]
	v_permlane16_swap_b32_e32 v158, v159
	v_add_f32_e32 v156, v156, v157
	v_add_f32_e32 v158, v158, v159
	s_nop 1
	v_permlane32_swap_b32_e32 v156, v158
	v_ashrrev_i32_e32 v164, 31, v156
	v_ashrrev_i32_e32 v165, 31, v158
	v_or_b32_e32 v164, 0x80000000, v164
	v_mfma_f32_16x16x32_bf16 v[102:105], v[6:9], v[54:57], v[102:105]
	v_or_b32_e32 v165, 0x80000000, v165
	v_xor_b32_e32 v164, v156, v164
	v_xor_b32_e32 v165, v158, v165
	v_and_b32_e32 v164, 0xffffff00, v164
	v_and_b32_e32 v165, 0xffffff00, v165
	v_cmp_ge_i32_e32 vcc, s5, v242
	s_nop 1
	v_cndmask_b32_e32 v149, 0, v164, vcc
	v_cmp_ge_i32_e32 vcc, s67, v242
	s_nop 1
	v_cndmask_b32_e32 v165, 0, v165, vcc
	global_store_dword v168, v165, s[68:69] offset:3328
	s_waitcnt lgkmcnt(0)
	v_mfma_f32_16x16x32_bf16 v[106:109], v[10:13], v[58:61], 0
	s_sub_i32 s5, s57, 3968
	s_add_i32 s67, s5, 1
	v_med3_f32 v90, v90, 0, v240
	v_med3_f32 v91, v91, 0, v240
	v_med3_f32 v92, v92, 0, v240
	v_med3_f32 v93, v93, 0, v240
	v_mul_f32_e32 v160, v2, v90
	v_mul_f32_e32 v161, v3, v91
	v_mfma_f32_16x16x32_bf16 v[110:113], v[10:13], v[62:65], 0
	v_mul_f32_e32 v162, v4, v92
	v_mul_f32_e32 v163, v5, v93
	v_add_f32_e32 v156, v160, v161
	v_add_f32_e32 v156, v162, v156
	v_add_f32_e32 v156, v163, v156
	v_med3_f32 v94, v94, 0, v240
	v_med3_f32 v95, v95, 0, v240
	v_med3_f32 v96, v96, 0, v240
	v_mfma_f32_16x16x32_bf16 v[114:117], v[10:13], v[66:69], 0
	v_med3_f32 v97, v97, 0, v240
	v_mul_f32_e32 v160, v2, v94
	v_mul_f32_e32 v161, v3, v95
	v_mul_f32_e32 v162, v4, v96
	v_mul_f32_e32 v163, v5, v97
	v_add_f32_e32 v157, v160, v161
	v_add_f32_e32 v157, v162, v157
	v_add_f32_e32 v157, v163, v157
	v_mfma_f32_16x16x32_bf16 v[118:121], v[10:13], v[70:73], 0
	v_med3_f32 v98, v98, 0, v240
	v_med3_f32 v99, v99, 0, v240
	v_med3_f32 v100, v100, 0, v240
	v_med3_f32 v101, v101, 0, v240
	v_mul_f32_e32 v160, v2, v98
	v_mul_f32_e32 v161, v3, v99
	v_mul_f32_e32 v162, v4, v100
	v_mul_f32_e32 v163, v5, v101
	v_mfma_f32_16x16x32_bf16 v[106:109], v[6:9], v[74:77], v[106:109]
	v_add_f32_e32 v158, v160, v161
	v_add_f32_e32 v158, v162, v158
	v_add_f32_e32 v158, v163, v158
	v_med3_f32 v102, v102, 0, v240
	v_med3_f32 v103, v103, 0, v240
	v_med3_f32 v104, v104, 0, v240
	v_med3_f32 v105, v105, 0, v240
	v_mul_f32_e32 v160, v2, v102
	v_mfma_f32_16x16x32_bf16 v[110:113], v[6:9], v[78:81], v[110:113]
	v_mul_f32_e32 v161, v3, v103
	v_mul_f32_e32 v162, v4, v104
	v_mul_f32_e32 v163, v5, v105
	v_add_f32_e32 v159, v160, v161
	v_add_f32_e32 v159, v162, v159
	v_add_f32_e32 v159, v163, v159
	s_nop 1
	v_permlane16_swap_b32_e32 v156, v157
	v_mfma_f32_16x16x32_bf16 v[114:117], v[6:9], v[82:85], v[114:117]
	v_permlane16_swap_b32_e32 v158, v159
	v_add_f32_e32 v156, v156, v157
	v_add_f32_e32 v158, v158, v159
	s_nop 1
	v_permlane32_swap_b32_e32 v156, v158
	v_ashrrev_i32_e32 v164, 31, v156
	v_ashrrev_i32_e32 v165, 31, v158
	v_or_b32_e32 v164, 0x80000000, v164
	v_mfma_f32_16x16x32_bf16 v[118:121], v[6:9], v[86:89], v[118:121]
	v_or_b32_e32 v165, 0x80000000, v165
	v_xor_b32_e32 v164, v156, v164
	v_xor_b32_e32 v165, v158, v165
	v_and_b32_e32 v164, 0xffffff00, v164
	v_and_b32_e32 v165, 0xffffff00, v165
	v_cmp_ge_i32_e32 vcc, s5, v242
	s_nop 1
	v_cndmask_b32_e32 v150, 0, v164, vcc
	v_cmp_ge_i32_e32 vcc, s67, v242
	s_nop 1
	v_cndmask_b32_e32 v165, 0, v165, vcc
	global_store_dword v168, v165, s[68:69] offset:3584
.Lsc_drain16:
	s_nop 7
	s_nop 7
	s_sub_i32 s5, s57, 4032
	s_add_i32 s67, s5, 1
	v_med3_f32 v106, v106, 0, v240
	v_med3_f32 v107, v107, 0, v240
	v_med3_f32 v108, v108, 0, v240
	v_med3_f32 v109, v109, 0, v240
	v_mul_f32_e32 v160, v2, v106
	v_mul_f32_e32 v161, v3, v107
	v_mul_f32_e32 v162, v4, v108
	v_mul_f32_e32 v163, v5, v109
	v_add_f32_e32 v156, v160, v161
	v_add_f32_e32 v156, v162, v156
	v_add_f32_e32 v156, v163, v156
	v_med3_f32 v110, v110, 0, v240
	v_med3_f32 v111, v111, 0, v240
	v_med3_f32 v112, v112, 0, v240
	v_med3_f32 v113, v113, 0, v240
	v_mul_f32_e32 v160, v2, v110
	v_mul_f32_e32 v161, v3, v111
	v_mul_f32_e32 v162, v4, v112
	v_mul_f32_e32 v163, v5, v113
	v_add_f32_e32 v157, v160, v161
	v_add_f32_e32 v157, v162, v157
	v_add_f32_e32 v157, v163, v157
	v_med3_f32 v114, v114, 0, v240
	v_med3_f32 v115, v115, 0, v240
	v_med3_f32 v116, v116, 0, v240
	v_med3_f32 v117, v117, 0, v240
	v_mul_f32_e32 v160, v2, v114
	v_mul_f32_e32 v161, v3, v115
	v_mul_f32_e32 v162, v4, v116
	v_mul_f32_e32 v163, v5, v117
	v_add_f32_e32 v158, v160, v161
	v_add_f32_e32 v158, v162, v158
	v_add_f32_e32 v158, v163, v158
	v_med3_f32 v118, v118, 0, v240
	v_med3_f32 v119, v119, 0, v240
	v_med3_f32 v120, v120, 0, v240
	v_med3_f32 v121, v121, 0, v240
	v_mul_f32_e32 v160, v2, v118
	v_mul_f32_e32 v161, v3, v119
	v_mul_f32_e32 v162, v4, v120
	v_mul_f32_e32 v163, v5, v121
	v_add_f32_e32 v159, v160, v161
	v_add_f32_e32 v159, v162, v159
	v_add_f32_e32 v159, v163, v159
	s_nop 1
	v_permlane16_swap_b32_e32 v156, v157
	v_permlane16_swap_b32_e32 v158, v159
	v_add_f32_e32 v156, v156, v157
	v_add_f32_e32 v158, v158, v159
	s_nop 1
	v_permlane32_swap_b32_e32 v156, v158
	v_ashrrev_i32_e32 v164, 31, v156
	v_ashrrev_i32_e32 v165, 31, v158
	v_or_b32_e32 v164, 0x80000000, v164
	v_or_b32_e32 v165, 0x80000000, v165
	v_xor_b32_e32 v164, v156, v164
	v_xor_b32_e32 v165, v158, v165
	v_and_b32_e32 v164, 0xffffff00, v164
	v_and_b32_e32 v165, 0xffffff00, v165
	v_cmp_ge_i32_e32 vcc, s5, v242
	s_nop 1
	v_cndmask_b32_e32 v151, 0, v164, vcc
	v_cmp_ge_i32_e32 vcc, s67, v242
	s_nop 1
	v_cndmask_b32_e32 v165, 0, v165, vcc
	global_store_dword v168, v165, s[68:69] offset:3840
	s_branch .Lsc_tail
.Lsc_drain15:
	s_nop 7
	s_nop 7
	s_sub_i32 s5, s57, 3776
	s_add_i32 s67, s5, 1
	v_med3_f32 v106, v106, 0, v240
	v_med3_f32 v107, v107, 0, v240
	v_med3_f32 v108, v108, 0, v240
	v_med3_f32 v109, v109, 0, v240
	v_mul_f32_e32 v160, v2, v106
	v_mul_f32_e32 v161, v3, v107
	v_mul_f32_e32 v162, v4, v108
	v_mul_f32_e32 v163, v5, v109
	v_add_f32_e32 v156, v160, v161
	v_add_f32_e32 v156, v162, v156
	v_add_f32_e32 v156, v163, v156
	v_med3_f32 v110, v110, 0, v240
	v_med3_f32 v111, v111, 0, v240
	v_med3_f32 v112, v112, 0, v240
	v_med3_f32 v113, v113, 0, v240
	v_mul_f32_e32 v160, v2, v110
	v_mul_f32_e32 v161, v3, v111
	v_mul_f32_e32 v162, v4, v112
	v_mul_f32_e32 v163, v5, v113
	v_add_f32_e32 v157, v160, v161
	v_add_f32_e32 v157, v162, v157
	v_add_f32_e32 v157, v163, v157
	v_med3_f32 v114, v114, 0, v240
	v_med3_f32 v115, v115, 0, v240
	v_med3_f32 v116, v116, 0, v240
	v_med3_f32 v117, v117, 0, v240
	v_mul_f32_e32 v160, v2, v114
	v_mul_f32_e32 v161, v3, v115
	v_mul_f32_e32 v162, v4, v116
	v_mul_f32_e32 v163, v5, v117
	v_add_f32_e32 v158, v160, v161
	v_add_f32_e32 v158, v162, v158
	v_add_f32_e32 v158, v163, v158
	v_med3_f32 v118, v118, 0, v240
	v_med3_f32 v119, v119, 0, v240
	v_med3_f32 v120, v120, 0, v240
	v_med3_f32 v121, v121, 0, v240
	v_mul_f32_e32 v160, v2, v118
	v_mul_f32_e32 v161, v3, v119
	v_mul_f32_e32 v162, v4, v120
	v_mul_f32_e32 v163, v5, v121
	v_add_f32_e32 v159, v160, v161
	v_add_f32_e32 v159, v162, v159
	v_add_f32_e32 v159, v163, v159
	s_nop 1
	v_permlane16_swap_b32_e32 v156, v157
	v_permlane16_swap_b32_e32 v158, v159
	v_add_f32_e32 v156, v156, v157
	v_add_f32_e32 v158, v158, v159
	s_nop 1
	v_permlane32_swap_b32_e32 v156, v158
	v_ashrrev_i32_e32 v164, 31, v156
	v_ashrrev_i32_e32 v165, 31, v158
	v_or_b32_e32 v164, 0x80000000, v164
	v_or_b32_e32 v165, 0x80000000, v165
	v_xor_b32_e32 v164, v156, v164
	v_xor_b32_e32 v165, v158, v165
	v_and_b32_e32 v164, 0xffffff00, v164
	v_and_b32_e32 v165, 0xffffff00, v165
	v_cmp_ge_i32_e32 vcc, s5, v242
	s_nop 1
	v_cndmask_b32_e32 v147, 0, v164, vcc
	v_cmp_ge_i32_e32 vcc, s67, v242
	s_nop 1
	v_cndmask_b32_e32 v165, 0, v165, vcc
	global_store_dword v168, v165, s[68:69] offset:2816
	s_branch .Lsc_zero15
.Lsc_drain14:
	s_nop 7
	s_nop 7
	s_sub_i32 s5, s57, 3520
	s_add_i32 s67, s5, 1
	v_med3_f32 v106, v106, 0, v240
	v_med3_f32 v107, v107, 0, v240
	v_med3_f32 v108, v108, 0, v240
	v_med3_f32 v109, v109, 0, v240
	v_mul_f32_e32 v160, v2, v106
	v_mul_f32_e32 v161, v3, v107
	v_mul_f32_e32 v162, v4, v108
	v_mul_f32_e32 v163, v5, v109
	v_add_f32_e32 v156, v160, v161
	v_add_f32_e32 v156, v162, v156
	v_add_f32_e32 v156, v163, v156
	v_med3_f32 v110, v110, 0, v240
	v_med3_f32 v111, v111, 0, v240
	v_med3_f32 v112, v112, 0, v240
	v_med3_f32 v113, v113, 0, v240
	v_mul_f32_e32 v160, v2, v110
	v_mul_f32_e32 v161, v3, v111
	v_mul_f32_e32 v162, v4, v112
	v_mul_f32_e32 v163, v5, v113
	v_add_f32_e32 v157, v160, v161
	v_add_f32_e32 v157, v162, v157
	v_add_f32_e32 v157, v163, v157
	v_med3_f32 v114, v114, 0, v240
	v_med3_f32 v115, v115, 0, v240
	v_med3_f32 v116, v116, 0, v240
	v_med3_f32 v117, v117, 0, v240
	v_mul_f32_e32 v160, v2, v114
	v_mul_f32_e32 v161, v3, v115
	v_mul_f32_e32 v162, v4, v116
	v_mul_f32_e32 v163, v5, v117
	v_add_f32_e32 v158, v160, v161
	v_add_f32_e32 v158, v162, v158
	v_add_f32_e32 v158, v163, v158
	v_med3_f32 v118, v118, 0, v240
	v_med3_f32 v119, v119, 0, v240
	v_med3_f32 v120, v120, 0, v240
	v_med3_f32 v121, v121, 0, v240
	v_mul_f32_e32 v160, v2, v118
	v_mul_f32_e32 v161, v3, v119
	v_mul_f32_e32 v162, v4, v120
	v_mul_f32_e32 v163, v5, v121
	v_add_f32_e32 v159, v160, v161
	v_add_f32_e32 v159, v162, v159
	v_add_f32_e32 v159, v163, v159
	s_nop 1
	v_permlane16_swap_b32_e32 v156, v157
	v_permlane16_swap_b32_e32 v158, v159
	v_add_f32_e32 v156, v156, v157
	v_add_f32_e32 v158, v158, v159
	s_nop 1
	v_permlane32_swap_b32_e32 v156, v158
	v_ashrrev_i32_e32 v164, 31, v156
	v_ashrrev_i32_e32 v165, 31, v158
	v_or_b32_e32 v164, 0x80000000, v164
	v_or_b32_e32 v165, 0x80000000, v165
	v_xor_b32_e32 v164, v156, v164
	v_xor_b32_e32 v165, v158, v165
	v_and_b32_e32 v164, 0xffffff00, v164
	v_and_b32_e32 v165, 0xffffff00, v165
	v_cmp_ge_i32_e32 vcc, s5, v242
	s_nop 1
	v_cndmask_b32_e32 v143, 0, v164, vcc
	v_cmp_ge_i32_e32 vcc, s67, v242
	s_nop 1
	v_cndmask_b32_e32 v165, 0, v165, vcc
	global_store_dword v168, v165, s[68:69] offset:1792
	s_branch .Lsc_zero14
.Lsc_drain13:
	s_nop 7
	s_nop 7
	s_sub_i32 s5, s57, 3264
	s_add_i32 s67, s5, 1
	v_med3_f32 v106, v106, 0, v240
	v_med3_f32 v107, v107, 0, v240
	v_med3_f32 v108, v108, 0, v240
	v_med3_f32 v109, v109, 0, v240
	v_mul_f32_e32 v160, v2, v106
	v_mul_f32_e32 v161, v3, v107
	v_mul_f32_e32 v162, v4, v108
	v_mul_f32_e32 v163, v5, v109
	v_add_f32_e32 v156, v160, v161
	v_add_f32_e32 v156, v162, v156
	v_add_f32_e32 v156, v163, v156
	v_med3_f32 v110, v110, 0, v240
	v_med3_f32 v111, v111, 0, v240
	v_med3_f32 v112, v112, 0, v240
	v_med3_f32 v113, v113, 0, v240
	v_mul_f32_e32 v160, v2, v110
	v_mul_f32_e32 v161, v3, v111
	v_mul_f32_e32 v162, v4, v112
	v_mul_f32_e32 v163, v5, v113
	v_add_f32_e32 v157, v160, v161
	v_add_f32_e32 v157, v162, v157
	v_add_f32_e32 v157, v163, v157
	v_med3_f32 v114, v114, 0, v240
	v_med3_f32 v115, v115, 0, v240
	v_med3_f32 v116, v116, 0, v240
	v_med3_f32 v117, v117, 0, v240
	v_mul_f32_e32 v160, v2, v114
	v_mul_f32_e32 v161, v3, v115
	v_mul_f32_e32 v162, v4, v116
	v_mul_f32_e32 v163, v5, v117
	v_add_f32_e32 v158, v160, v161
	v_add_f32_e32 v158, v162, v158
	v_add_f32_e32 v158, v163, v158
	v_med3_f32 v118, v118, 0, v240
	v_med3_f32 v119, v119, 0, v240
	v_med3_f32 v120, v120, 0, v240
	v_med3_f32 v121, v121, 0, v240
	v_mul_f32_e32 v160, v2, v118
	v_mul_f32_e32 v161, v3, v119
	v_mul_f32_e32 v162, v4, v120
	v_mul_f32_e32 v163, v5, v121
	v_add_f32_e32 v159, v160, v161
	v_add_f32_e32 v159, v162, v159
	v_add_f32_e32 v159, v163, v159
	s_nop 1
	v_permlane16_swap_b32_e32 v156, v157
	v_permlane16_swap_b32_e32 v158, v159
	v_add_f32_e32 v156, v156, v157
	v_add_f32_e32 v158, v158, v159
	s_nop 1
	v_permlane32_swap_b32_e32 v156, v158
	v_ashrrev_i32_e32 v164, 31, v156
	v_ashrrev_i32_e32 v165, 31, v158
	v_or_b32_e32 v164, 0x80000000, v164
	v_or_b32_e32 v165, 0x80000000, v165
	v_xor_b32_e32 v164, v156, v164
	v_xor_b32_e32 v165, v158, v165
	v_and_b32_e32 v164, 0xffffff00, v164
	v_and_b32_e32 v165, 0xffffff00, v165
	v_cmp_ge_i32_e32 vcc, s5, v242
	s_nop 1
	v_cndmask_b32_e32 v139, 0, v164, vcc
	v_cmp_ge_i32_e32 vcc, s67, v242
	s_nop 1
	v_cndmask_b32_e32 v165, 0, v165, vcc
	global_store_dword v168, v165, s[68:69] offset:768
	s_branch .Lsc_zero13
.Lsc_drain12:
	s_nop 7
	s_nop 7
	s_sub_i32 s5, s57, 3008
	s_add_i32 s67, s5, 1
	v_med3_f32 v106, v106, 0, v240
	v_med3_f32 v107, v107, 0, v240
	v_med3_f32 v108, v108, 0, v240
	v_med3_f32 v109, v109, 0, v240
	v_mul_f32_e32 v160, v2, v106
	v_mul_f32_e32 v161, v3, v107
	v_mul_f32_e32 v162, v4, v108
	v_mul_f32_e32 v163, v5, v109
	v_add_f32_e32 v156, v160, v161
	v_add_f32_e32 v156, v162, v156
	v_add_f32_e32 v156, v163, v156
	v_med3_f32 v110, v110, 0, v240
	v_med3_f32 v111, v111, 0, v240
	v_med3_f32 v112, v112, 0, v240
	v_med3_f32 v113, v113, 0, v240
	v_mul_f32_e32 v160, v2, v110
	v_mul_f32_e32 v161, v3, v111
	v_mul_f32_e32 v162, v4, v112
	v_mul_f32_e32 v163, v5, v113
	v_add_f32_e32 v157, v160, v161
	v_add_f32_e32 v157, v162, v157
	v_add_f32_e32 v157, v163, v157
	v_med3_f32 v114, v114, 0, v240
	v_med3_f32 v115, v115, 0, v240
	v_med3_f32 v116, v116, 0, v240
	v_med3_f32 v117, v117, 0, v240
	v_mul_f32_e32 v160, v2, v114
	v_mul_f32_e32 v161, v3, v115
	v_mul_f32_e32 v162, v4, v116
	v_mul_f32_e32 v163, v5, v117
	v_add_f32_e32 v158, v160, v161
	v_add_f32_e32 v158, v162, v158
	v_add_f32_e32 v158, v163, v158
	v_med3_f32 v118, v118, 0, v240
	v_med3_f32 v119, v119, 0, v240
	v_med3_f32 v120, v120, 0, v240
	v_med3_f32 v121, v121, 0, v240
	v_mul_f32_e32 v160, v2, v118
	v_mul_f32_e32 v161, v3, v119
	v_mul_f32_e32 v162, v4, v120
	v_mul_f32_e32 v163, v5, v121
	v_add_f32_e32 v159, v160, v161
	v_add_f32_e32 v159, v162, v159
	v_add_f32_e32 v159, v163, v159
	s_nop 1
	v_permlane16_swap_b32_e32 v156, v157
	v_permlane16_swap_b32_e32 v158, v159
	v_add_f32_e32 v156, v156, v157
	v_add_f32_e32 v158, v158, v159
	s_nop 1
	v_permlane32_swap_b32_e32 v156, v158
	v_ashrrev_i32_e32 v164, 31, v156
	v_ashrrev_i32_e32 v165, 31, v158
	v_or_b32_e32 v164, 0x80000000, v164
	v_or_b32_e32 v165, 0x80000000, v165
	v_xor_b32_e32 v164, v156, v164
	v_xor_b32_e32 v165, v158, v165
	v_and_b32_e32 v164, 0xffffff00, v164
	v_and_b32_e32 v165, 0xffffff00, v165
	v_cmp_ge_i32_e32 vcc, s5, v242
	s_nop 1
	v_cndmask_b32_e32 v135, 0, v164, vcc
	v_cmp_ge_i32_e32 vcc, s67, v242
	s_nop 1
	v_cndmask_b32_e32 v165, 0, v165, vcc
	global_store_dword v168, v165, s[46:47] offset:3840
	s_branch .Lsc_zero12
.Lsc_drain11:
	s_nop 7
	s_nop 7
	s_sub_i32 s5, s57, 2752
	s_add_i32 s67, s5, 1
	v_med3_f32 v106, v106, 0, v240
	v_med3_f32 v107, v107, 0, v240
	v_med3_f32 v108, v108, 0, v240
	v_med3_f32 v109, v109, 0, v240
	v_mul_f32_e32 v160, v2, v106
	v_mul_f32_e32 v161, v3, v107
	v_mul_f32_e32 v162, v4, v108
	v_mul_f32_e32 v163, v5, v109
	v_add_f32_e32 v156, v160, v161
	v_add_f32_e32 v156, v162, v156
	v_add_f32_e32 v156, v163, v156
	v_med3_f32 v110, v110, 0, v240
	v_med3_f32 v111, v111, 0, v240
	v_med3_f32 v112, v112, 0, v240
	v_med3_f32 v113, v113, 0, v240
	v_mul_f32_e32 v160, v2, v110
	v_mul_f32_e32 v161, v3, v111
	v_mul_f32_e32 v162, v4, v112
	v_mul_f32_e32 v163, v5, v113
	v_add_f32_e32 v157, v160, v161
	v_add_f32_e32 v157, v162, v157
	v_add_f32_e32 v157, v163, v157
	v_med3_f32 v114, v114, 0, v240
	v_med3_f32 v115, v115, 0, v240
	v_med3_f32 v116, v116, 0, v240
	v_med3_f32 v117, v117, 0, v240
	v_mul_f32_e32 v160, v2, v114
	v_mul_f32_e32 v161, v3, v115
	v_mul_f32_e32 v162, v4, v116
	v_mul_f32_e32 v163, v5, v117
	v_add_f32_e32 v158, v160, v161
	v_add_f32_e32 v158, v162, v158
	v_add_f32_e32 v158, v163, v158
	v_med3_f32 v118, v118, 0, v240
	v_med3_f32 v119, v119, 0, v240
	v_med3_f32 v120, v120, 0, v240
	v_med3_f32 v121, v121, 0, v240
	v_mul_f32_e32 v160, v2, v118
	v_mul_f32_e32 v161, v3, v119
	v_mul_f32_e32 v162, v4, v120
	v_mul_f32_e32 v163, v5, v121
	v_add_f32_e32 v159, v160, v161
	v_add_f32_e32 v159, v162, v159
	v_add_f32_e32 v159, v163, v159
	s_nop 1
	v_permlane16_swap_b32_e32 v156, v157
	v_permlane16_swap_b32_e32 v158, v159
	v_add_f32_e32 v156, v156, v157
	v_add_f32_e32 v158, v158, v159
	s_nop 1
	v_permlane32_swap_b32_e32 v156, v158
	v_ashrrev_i32_e32 v164, 31, v156
	v_ashrrev_i32_e32 v165, 31, v158
	v_or_b32_e32 v164, 0x80000000, v164
	v_or_b32_e32 v165, 0x80000000, v165
	v_xor_b32_e32 v164, v156, v164
	v_xor_b32_e32 v165, v158, v165
	v_and_b32_e32 v164, 0xffffff00, v164
	v_and_b32_e32 v165, 0xffffff00, v165
	v_cmp_ge_i32_e32 vcc, s5, v242
	s_nop 1
	v_cndmask_b32_e32 v131, 0, v164, vcc
	v_cmp_ge_i32_e32 vcc, s67, v242
	s_nop 1
	v_cndmask_b32_e32 v165, 0, v165, vcc
	global_store_dword v168, v165, s[46:47] offset:2816
	s_branch .Lsc_zero11
.Lsc_drain10:
	s_nop 7
	s_nop 7
	s_sub_i32 s5, s57, 2496
	s_add_i32 s67, s5, 1
	v_med3_f32 v106, v106, 0, v240
	v_med3_f32 v107, v107, 0, v240
	v_med3_f32 v108, v108, 0, v240
	v_med3_f32 v109, v109, 0, v240
	v_mul_f32_e32 v160, v2, v106
	v_mul_f32_e32 v161, v3, v107
	v_mul_f32_e32 v162, v4, v108
	v_mul_f32_e32 v163, v5, v109
	v_add_f32_e32 v156, v160, v161
	v_add_f32_e32 v156, v162, v156
	v_add_f32_e32 v156, v163, v156
	v_med3_f32 v110, v110, 0, v240
	v_med3_f32 v111, v111, 0, v240
	v_med3_f32 v112, v112, 0, v240
	v_med3_f32 v113, v113, 0, v240
	v_mul_f32_e32 v160, v2, v110
	v_mul_f32_e32 v161, v3, v111
	v_mul_f32_e32 v162, v4, v112
	v_mul_f32_e32 v163, v5, v113
	v_add_f32_e32 v157, v160, v161
	v_add_f32_e32 v157, v162, v157
	v_add_f32_e32 v157, v163, v157
	v_med3_f32 v114, v114, 0, v240
	v_med3_f32 v115, v115, 0, v240
	v_med3_f32 v116, v116, 0, v240
	v_med3_f32 v117, v117, 0, v240
	v_mul_f32_e32 v160, v2, v114
	v_mul_f32_e32 v161, v3, v115
	v_mul_f32_e32 v162, v4, v116
	v_mul_f32_e32 v163, v5, v117
	v_add_f32_e32 v158, v160, v161
	v_add_f32_e32 v158, v162, v158
	v_add_f32_e32 v158, v163, v158
	v_med3_f32 v118, v118, 0, v240
	v_med3_f32 v119, v119, 0, v240
	v_med3_f32 v120, v120, 0, v240
	v_med3_f32 v121, v121, 0, v240
	v_mul_f32_e32 v160, v2, v118
	v_mul_f32_e32 v161, v3, v119
	v_mul_f32_e32 v162, v4, v120
	v_mul_f32_e32 v163, v5, v121
	v_add_f32_e32 v159, v160, v161
	v_add_f32_e32 v159, v162, v159
	v_add_f32_e32 v159, v163, v159
	s_nop 1
	v_permlane16_swap_b32_e32 v156, v157
	v_permlane16_swap_b32_e32 v158, v159
	v_add_f32_e32 v156, v156, v157
	v_add_f32_e32 v158, v158, v159
	s_nop 1
	v_permlane32_swap_b32_e32 v156, v158
	v_ashrrev_i32_e32 v164, 31, v156
	v_ashrrev_i32_e32 v165, 31, v158
	v_or_b32_e32 v164, 0x80000000, v164
	v_or_b32_e32 v165, 0x80000000, v165
	v_xor_b32_e32 v164, v156, v164
	v_xor_b32_e32 v165, v158, v165
	v_and_b32_e32 v164, 0xffffff00, v164
	v_and_b32_e32 v165, 0xffffff00, v165
	v_cmp_ge_i32_e32 vcc, s5, v242
	s_nop 1
	v_cndmask_b32_e32 v199, 0, v164, vcc
	v_cmp_ge_i32_e32 vcc, s67, v242
	s_nop 1
	v_cndmask_b32_e32 v165, 0, v165, vcc
	global_store_dword v168, v165, s[46:47] offset:1792
	s_branch .Lsc_zero10
.Lsc_drain9:
	s_nop 7
	s_nop 7
	s_sub_i32 s5, s57, 2240
	s_add_i32 s67, s5, 1
	v_med3_f32 v106, v106, 0, v240
	v_med3_f32 v107, v107, 0, v240
	v_med3_f32 v108, v108, 0, v240
	v_med3_f32 v109, v109, 0, v240
	v_mul_f32_e32 v160, v2, v106
	v_mul_f32_e32 v161, v3, v107
	v_mul_f32_e32 v162, v4, v108
	v_mul_f32_e32 v163, v5, v109
	v_add_f32_e32 v156, v160, v161
	v_add_f32_e32 v156, v162, v156
	v_add_f32_e32 v156, v163, v156
	v_med3_f32 v110, v110, 0, v240
	v_med3_f32 v111, v111, 0, v240
	v_med3_f32 v112, v112, 0, v240
	v_med3_f32 v113, v113, 0, v240
	v_mul_f32_e32 v160, v2, v110
	v_mul_f32_e32 v161, v3, v111
	v_mul_f32_e32 v162, v4, v112
	v_mul_f32_e32 v163, v5, v113
	v_add_f32_e32 v157, v160, v161
	v_add_f32_e32 v157, v162, v157
	v_add_f32_e32 v157, v163, v157
	v_med3_f32 v114, v114, 0, v240
	v_med3_f32 v115, v115, 0, v240
	v_med3_f32 v116, v116, 0, v240
	v_med3_f32 v117, v117, 0, v240
	v_mul_f32_e32 v160, v2, v114
	v_mul_f32_e32 v161, v3, v115
	v_mul_f32_e32 v162, v4, v116
	v_mul_f32_e32 v163, v5, v117
	v_add_f32_e32 v158, v160, v161
	v_add_f32_e32 v158, v162, v158
	v_add_f32_e32 v158, v163, v158
	v_med3_f32 v118, v118, 0, v240
	v_med3_f32 v119, v119, 0, v240
	v_med3_f32 v120, v120, 0, v240
	v_med3_f32 v121, v121, 0, v240
	v_mul_f32_e32 v160, v2, v118
	v_mul_f32_e32 v161, v3, v119
	v_mul_f32_e32 v162, v4, v120
	v_mul_f32_e32 v163, v5, v121
	v_add_f32_e32 v159, v160, v161
	v_add_f32_e32 v159, v162, v159
	v_add_f32_e32 v159, v163, v159
	s_nop 1
	v_permlane16_swap_b32_e32 v156, v157
	v_permlane16_swap_b32_e32 v158, v159
	v_add_f32_e32 v156, v156, v157
	v_add_f32_e32 v158, v158, v159
	s_nop 1
	v_permlane32_swap_b32_e32 v156, v158
	v_ashrrev_i32_e32 v164, 31, v156
	v_ashrrev_i32_e32 v165, 31, v158
	v_or_b32_e32 v164, 0x80000000, v164
	v_or_b32_e32 v165, 0x80000000, v165
	v_xor_b32_e32 v164, v156, v164
	v_xor_b32_e32 v165, v158, v165
	v_and_b32_e32 v164, 0xffffff00, v164
	v_and_b32_e32 v165, 0xffffff00, v165
	v_cmp_ge_i32_e32 vcc, s5, v242
	s_nop 1
	v_cndmask_b32_e32 v253, 0, v164, vcc
	v_cmp_ge_i32_e32 vcc, s67, v242
	s_nop 1
	v_cndmask_b32_e32 v165, 0, v165, vcc
	global_store_dword v168, v165, s[46:47] offset:768
	s_branch .Lsc_zero9
.Lsc_drain8:
	s_nop 7
	s_nop 7
	s_sub_i32 s5, s57, 1984
	s_add_i32 s67, s5, 1
	v_med3_f32 v106, v106, 0, v240
	v_med3_f32 v107, v107, 0, v240
	v_med3_f32 v108, v108, 0, v240
	v_med3_f32 v109, v109, 0, v240
	v_mul_f32_e32 v160, v2, v106
	v_mul_f32_e32 v161, v3, v107
	v_mul_f32_e32 v162, v4, v108
	v_mul_f32_e32 v163, v5, v109
	v_add_f32_e32 v156, v160, v161
	v_add_f32_e32 v156, v162, v156
	v_add_f32_e32 v156, v163, v156
	v_med3_f32 v110, v110, 0, v240
	v_med3_f32 v111, v111, 0, v240
	v_med3_f32 v112, v112, 0, v240
	v_med3_f32 v113, v113, 0, v240
	v_mul_f32_e32 v160, v2, v110
	v_mul_f32_e32 v161, v3, v111
	v_mul_f32_e32 v162, v4, v112
	v_mul_f32_e32 v163, v5, v113
	v_add_f32_e32 v157, v160, v161
	v_add_f32_e32 v157, v162, v157
	v_add_f32_e32 v157, v163, v157
	v_med3_f32 v114, v114, 0, v240
	v_med3_f32 v115, v115, 0, v240
	v_med3_f32 v116, v116, 0, v240
	v_med3_f32 v117, v117, 0, v240
	v_mul_f32_e32 v160, v2, v114
	v_mul_f32_e32 v161, v3, v115
	v_mul_f32_e32 v162, v4, v116
	v_mul_f32_e32 v163, v5, v117
	v_add_f32_e32 v158, v160, v161
	v_add_f32_e32 v158, v162, v158
	v_add_f32_e32 v158, v163, v158
	v_med3_f32 v118, v118, 0, v240
	v_med3_f32 v119, v119, 0, v240
	v_med3_f32 v120, v120, 0, v240
	v_med3_f32 v121, v121, 0, v240
	v_mul_f32_e32 v160, v2, v118
	v_mul_f32_e32 v161, v3, v119
	v_mul_f32_e32 v162, v4, v120
	v_mul_f32_e32 v163, v5, v121
	v_add_f32_e32 v159, v160, v161
	v_add_f32_e32 v159, v162, v159
	v_add_f32_e32 v159, v163, v159
	s_nop 1
	v_permlane16_swap_b32_e32 v156, v157
	v_permlane16_swap_b32_e32 v158, v159
	v_add_f32_e32 v156, v156, v157
	v_add_f32_e32 v158, v158, v159
	s_nop 1
	v_permlane32_swap_b32_e32 v156, v158
	v_ashrrev_i32_e32 v164, 31, v156
	v_ashrrev_i32_e32 v165, 31, v158
	v_or_b32_e32 v164, 0x80000000, v164
	v_or_b32_e32 v165, 0x80000000, v165
	v_xor_b32_e32 v164, v156, v164
	v_xor_b32_e32 v165, v158, v165
	v_and_b32_e32 v164, 0xffffff00, v164
	v_and_b32_e32 v165, 0xffffff00, v165
	v_cmp_ge_i32_e32 vcc, s5, v242
	s_nop 1
	v_cndmask_b32_e32 v249, 0, v164, vcc
	v_cmp_ge_i32_e32 vcc, s67, v242
	s_nop 1
	v_cndmask_b32_e32 v165, 0, v165, vcc
	global_store_dword v168, v165, s[14:15] offset:3840
	s_branch .Lsc_zero8
.Lsc_drain7:
	s_nop 7
	s_nop 7
	s_sub_i32 s5, s57, 1728
	s_add_i32 s67, s5, 1
	v_med3_f32 v106, v106, 0, v240
	v_med3_f32 v107, v107, 0, v240
	v_med3_f32 v108, v108, 0, v240
	v_med3_f32 v109, v109, 0, v240
	v_mul_f32_e32 v160, v2, v106
	v_mul_f32_e32 v161, v3, v107
	v_mul_f32_e32 v162, v4, v108
	v_mul_f32_e32 v163, v5, v109
	v_add_f32_e32 v156, v160, v161
	v_add_f32_e32 v156, v162, v156
	v_add_f32_e32 v156, v163, v156
	v_med3_f32 v110, v110, 0, v240
	v_med3_f32 v111, v111, 0, v240
	v_med3_f32 v112, v112, 0, v240
	v_med3_f32 v113, v113, 0, v240
	v_mul_f32_e32 v160, v2, v110
	v_mul_f32_e32 v161, v3, v111
	v_mul_f32_e32 v162, v4, v112
	v_mul_f32_e32 v163, v5, v113
	v_add_f32_e32 v157, v160, v161
	v_add_f32_e32 v157, v162, v157
	v_add_f32_e32 v157, v163, v157
	v_med3_f32 v114, v114, 0, v240
	v_med3_f32 v115, v115, 0, v240
	v_med3_f32 v116, v116, 0, v240
	v_med3_f32 v117, v117, 0, v240
	v_mul_f32_e32 v160, v2, v114
	v_mul_f32_e32 v161, v3, v115
	v_mul_f32_e32 v162, v4, v116
	v_mul_f32_e32 v163, v5, v117
	v_add_f32_e32 v158, v160, v161
	v_add_f32_e32 v158, v162, v158
	v_add_f32_e32 v158, v163, v158
	v_med3_f32 v118, v118, 0, v240
	v_med3_f32 v119, v119, 0, v240
	v_med3_f32 v120, v120, 0, v240
	v_med3_f32 v121, v121, 0, v240
	v_mul_f32_e32 v160, v2, v118
	v_mul_f32_e32 v161, v3, v119
	v_mul_f32_e32 v162, v4, v120
	v_mul_f32_e32 v163, v5, v121
	v_add_f32_e32 v159, v160, v161
	v_add_f32_e32 v159, v162, v159
	v_add_f32_e32 v159, v163, v159
	s_nop 1
	v_permlane16_swap_b32_e32 v156, v157
	v_permlane16_swap_b32_e32 v158, v159
	v_add_f32_e32 v156, v156, v157
	v_add_f32_e32 v158, v158, v159
	s_nop 1
	v_permlane32_swap_b32_e32 v156, v158
	v_ashrrev_i32_e32 v164, 31, v156
	v_ashrrev_i32_e32 v165, 31, v158
	v_or_b32_e32 v164, 0x80000000, v164
	v_or_b32_e32 v165, 0x80000000, v165
	v_xor_b32_e32 v164, v156, v164
	v_xor_b32_e32 v165, v158, v165
	v_and_b32_e32 v164, 0xffffff00, v164
	v_and_b32_e32 v165, 0xffffff00, v165
	v_cmp_ge_i32_e32 vcc, s5, v242
	s_nop 1
	v_cndmask_b32_e32 v245, 0, v164, vcc
	v_cmp_ge_i32_e32 vcc, s67, v242
	s_nop 1
	v_cndmask_b32_e32 v165, 0, v165, vcc
	global_store_dword v168, v165, s[14:15] offset:2816
	s_branch .Lsc_zero7
.Lsc_drain6:
	s_nop 7
	s_nop 7
	s_sub_i32 s5, s57, 1472
	s_add_i32 s67, s5, 1
	v_med3_f32 v106, v106, 0, v240
	v_med3_f32 v107, v107, 0, v240
	v_med3_f32 v108, v108, 0, v240
	v_med3_f32 v109, v109, 0, v240
	v_mul_f32_e32 v160, v2, v106
	v_mul_f32_e32 v161, v3, v107
	v_mul_f32_e32 v162, v4, v108
	v_mul_f32_e32 v163, v5, v109
	v_add_f32_e32 v156, v160, v161
	v_add_f32_e32 v156, v162, v156
	v_add_f32_e32 v156, v163, v156
	v_med3_f32 v110, v110, 0, v240
	v_med3_f32 v111, v111, 0, v240
	v_med3_f32 v112, v112, 0, v240
	v_med3_f32 v113, v113, 0, v240
	v_mul_f32_e32 v160, v2, v110
	v_mul_f32_e32 v161, v3, v111
	v_mul_f32_e32 v162, v4, v112
	v_mul_f32_e32 v163, v5, v113
	v_add_f32_e32 v157, v160, v161
	v_add_f32_e32 v157, v162, v157
	v_add_f32_e32 v157, v163, v157
	v_med3_f32 v114, v114, 0, v240
	v_med3_f32 v115, v115, 0, v240
	v_med3_f32 v116, v116, 0, v240
	v_med3_f32 v117, v117, 0, v240
	v_mul_f32_e32 v160, v2, v114
	v_mul_f32_e32 v161, v3, v115
	v_mul_f32_e32 v162, v4, v116
	v_mul_f32_e32 v163, v5, v117
	v_add_f32_e32 v158, v160, v161
	v_add_f32_e32 v158, v162, v158
	v_add_f32_e32 v158, v163, v158
	v_med3_f32 v118, v118, 0, v240
	v_med3_f32 v119, v119, 0, v240
	v_med3_f32 v120, v120, 0, v240
	v_med3_f32 v121, v121, 0, v240
	v_mul_f32_e32 v160, v2, v118
	v_mul_f32_e32 v161, v3, v119
	v_mul_f32_e32 v162, v4, v120
	v_mul_f32_e32 v163, v5, v121
	v_add_f32_e32 v159, v160, v161
	v_add_f32_e32 v159, v162, v159
	v_add_f32_e32 v159, v163, v159
	s_nop 1
	v_permlane16_swap_b32_e32 v156, v157
	v_permlane16_swap_b32_e32 v158, v159
	v_add_f32_e32 v156, v156, v157
	v_add_f32_e32 v158, v158, v159
	s_nop 1
	v_permlane32_swap_b32_e32 v156, v158
	v_ashrrev_i32_e32 v164, 31, v156
	v_ashrrev_i32_e32 v165, 31, v158
	v_or_b32_e32 v164, 0x80000000, v164
	v_or_b32_e32 v165, 0x80000000, v165
	v_xor_b32_e32 v164, v156, v164
	v_xor_b32_e32 v165, v158, v165
	v_and_b32_e32 v164, 0xffffff00, v164
	v_and_b32_e32 v165, 0xffffff00, v165
	v_cmp_ge_i32_e32 vcc, s5, v242
	s_nop 1
	v_cndmask_b32_e32 v235, 0, v164, vcc
	v_cmp_ge_i32_e32 vcc, s67, v242
	s_nop 1
	v_cndmask_b32_e32 v165, 0, v165, vcc
	global_store_dword v168, v165, s[14:15] offset:1792
	s_branch .Lsc_zero6
.Lsc_drain5:
	s_nop 7
	s_nop 7
	s_sub_i32 s5, s57, 1216
	s_add_i32 s67, s5, 1
	v_med3_f32 v106, v106, 0, v240
	v_med3_f32 v107, v107, 0, v240
	v_med3_f32 v108, v108, 0, v240
	v_med3_f32 v109, v109, 0, v240
	v_mul_f32_e32 v160, v2, v106
	v_mul_f32_e32 v161, v3, v107
	v_mul_f32_e32 v162, v4, v108
	v_mul_f32_e32 v163, v5, v109
	v_add_f32_e32 v156, v160, v161
	v_add_f32_e32 v156, v162, v156
	v_add_f32_e32 v156, v163, v156
	v_med3_f32 v110, v110, 0, v240
	v_med3_f32 v111, v111, 0, v240
	v_med3_f32 v112, v112, 0, v240
	v_med3_f32 v113, v113, 0, v240
	v_mul_f32_e32 v160, v2, v110
	v_mul_f32_e32 v161, v3, v111
	v_mul_f32_e32 v162, v4, v112
	v_mul_f32_e32 v163, v5, v113
	v_add_f32_e32 v157, v160, v161
	v_add_f32_e32 v157, v162, v157
	v_add_f32_e32 v157, v163, v157
	v_med3_f32 v114, v114, 0, v240
	v_med3_f32 v115, v115, 0, v240
	v_med3_f32 v116, v116, 0, v240
	v_med3_f32 v117, v117, 0, v240
	v_mul_f32_e32 v160, v2, v114
	v_mul_f32_e32 v161, v3, v115
	v_mul_f32_e32 v162, v4, v116
	v_mul_f32_e32 v163, v5, v117
	v_add_f32_e32 v158, v160, v161
	v_add_f32_e32 v158, v162, v158
	v_add_f32_e32 v158, v163, v158
	v_med3_f32 v118, v118, 0, v240
	v_med3_f32 v119, v119, 0, v240
	v_med3_f32 v120, v120, 0, v240
	v_med3_f32 v121, v121, 0, v240
	v_mul_f32_e32 v160, v2, v118
	v_mul_f32_e32 v161, v3, v119
	v_mul_f32_e32 v162, v4, v120
	v_mul_f32_e32 v163, v5, v121
	v_add_f32_e32 v159, v160, v161
	v_add_f32_e32 v159, v162, v159
	v_add_f32_e32 v159, v163, v159
	s_nop 1
	v_permlane16_swap_b32_e32 v156, v157
	v_permlane16_swap_b32_e32 v158, v159
	v_add_f32_e32 v156, v156, v157
	v_add_f32_e32 v158, v158, v159
	s_nop 1
	v_permlane32_swap_b32_e32 v156, v158
	v_ashrrev_i32_e32 v164, 31, v156
	v_ashrrev_i32_e32 v165, 31, v158
	v_or_b32_e32 v164, 0x80000000, v164
	v_or_b32_e32 v165, 0x80000000, v165
	v_xor_b32_e32 v164, v156, v164
	v_xor_b32_e32 v165, v158, v165
	v_and_b32_e32 v164, 0xffffff00, v164
	v_and_b32_e32 v165, 0xffffff00, v165
	v_cmp_ge_i32_e32 vcc, s5, v242
	s_nop 1
	v_cndmask_b32_e32 v231, 0, v164, vcc
	v_cmp_ge_i32_e32 vcc, s67, v242
	s_nop 1
	v_cndmask_b32_e32 v165, 0, v165, vcc
	global_store_dword v168, v165, s[14:15] offset:768
	s_branch .Lsc_zero5
.Lsc_drain4:
	s_nop 7
	s_nop 7
	s_sub_i32 s5, s57, 960
	s_add_i32 s67, s5, 1
	v_med3_f32 v106, v106, 0, v240
	v_med3_f32 v107, v107, 0, v240
	v_med3_f32 v108, v108, 0, v240
	v_med3_f32 v109, v109, 0, v240
	v_mul_f32_e32 v160, v2, v106
	v_mul_f32_e32 v161, v3, v107
	v_mul_f32_e32 v162, v4, v108
	v_mul_f32_e32 v163, v5, v109
	v_add_f32_e32 v156, v160, v161
	v_add_f32_e32 v156, v162, v156
	v_add_f32_e32 v156, v163, v156
	v_med3_f32 v110, v110, 0, v240
	v_med3_f32 v111, v111, 0, v240
	v_med3_f32 v112, v112, 0, v240
	v_med3_f32 v113, v113, 0, v240
	v_mul_f32_e32 v160, v2, v110
	v_mul_f32_e32 v161, v3, v111
	v_mul_f32_e32 v162, v4, v112
	v_mul_f32_e32 v163, v5, v113
	v_add_f32_e32 v157, v160, v161
	v_add_f32_e32 v157, v162, v157
	v_add_f32_e32 v157, v163, v157
	v_med3_f32 v114, v114, 0, v240
	v_med3_f32 v115, v115, 0, v240
	v_med3_f32 v116, v116, 0, v240
	v_med3_f32 v117, v117, 0, v240
	v_mul_f32_e32 v160, v2, v114
	v_mul_f32_e32 v161, v3, v115
	v_mul_f32_e32 v162, v4, v116
	v_mul_f32_e32 v163, v5, v117
	v_add_f32_e32 v158, v160, v161
	v_add_f32_e32 v158, v162, v158
	v_add_f32_e32 v158, v163, v158
	v_med3_f32 v118, v118, 0, v240
	v_med3_f32 v119, v119, 0, v240
	v_med3_f32 v120, v120, 0, v240
	v_med3_f32 v121, v121, 0, v240
	v_mul_f32_e32 v160, v2, v118
	v_mul_f32_e32 v161, v3, v119
	v_mul_f32_e32 v162, v4, v120
	v_mul_f32_e32 v163, v5, v121
	v_add_f32_e32 v159, v160, v161
	v_add_f32_e32 v159, v162, v159
	v_add_f32_e32 v159, v163, v159
	s_nop 1
	v_permlane16_swap_b32_e32 v156, v157
	v_permlane16_swap_b32_e32 v158, v159
	v_add_f32_e32 v156, v156, v157
	v_add_f32_e32 v158, v158, v159
	s_nop 1
	v_permlane32_swap_b32_e32 v156, v158
	v_ashrrev_i32_e32 v164, 31, v156
	v_ashrrev_i32_e32 v165, 31, v158
	v_or_b32_e32 v164, 0x80000000, v164
	v_or_b32_e32 v165, 0x80000000, v165
	v_xor_b32_e32 v164, v156, v164
	v_xor_b32_e32 v165, v158, v165
	v_and_b32_e32 v164, 0xffffff00, v164
	v_and_b32_e32 v165, 0xffffff00, v165
	v_cmp_ge_i32_e32 vcc, s5, v242
	s_nop 1
	v_cndmask_b32_e32 v227, 0, v164, vcc
	v_cmp_ge_i32_e32 vcc, s67, v242
	s_nop 1
	v_cndmask_b32_e32 v165, 0, v165, vcc
	global_store_dword v168, v165, s[8:9] offset:3840
	s_branch .Lsc_zero4
.Lsc_drain3:
	s_nop 7
	s_nop 7
	s_sub_i32 s5, s57, 704
	s_add_i32 s67, s5, 1
	v_med3_f32 v106, v106, 0, v240
	v_med3_f32 v107, v107, 0, v240
	v_med3_f32 v108, v108, 0, v240
	v_med3_f32 v109, v109, 0, v240
	v_mul_f32_e32 v160, v2, v106
	v_mul_f32_e32 v161, v3, v107
	v_mul_f32_e32 v162, v4, v108
	v_mul_f32_e32 v163, v5, v109
	v_add_f32_e32 v156, v160, v161
	v_add_f32_e32 v156, v162, v156
	v_add_f32_e32 v156, v163, v156
	v_med3_f32 v110, v110, 0, v240
	v_med3_f32 v111, v111, 0, v240
	v_med3_f32 v112, v112, 0, v240
	v_med3_f32 v113, v113, 0, v240
	v_mul_f32_e32 v160, v2, v110
	v_mul_f32_e32 v161, v3, v111
	v_mul_f32_e32 v162, v4, v112
	v_mul_f32_e32 v163, v5, v113
	v_add_f32_e32 v157, v160, v161
	v_add_f32_e32 v157, v162, v157
	v_add_f32_e32 v157, v163, v157
	v_med3_f32 v114, v114, 0, v240
	v_med3_f32 v115, v115, 0, v240
	v_med3_f32 v116, v116, 0, v240
	v_med3_f32 v117, v117, 0, v240
	v_mul_f32_e32 v160, v2, v114
	v_mul_f32_e32 v161, v3, v115
	v_mul_f32_e32 v162, v4, v116
	v_mul_f32_e32 v163, v5, v117
	v_add_f32_e32 v158, v160, v161
	v_add_f32_e32 v158, v162, v158
	v_add_f32_e32 v158, v163, v158
	v_med3_f32 v118, v118, 0, v240
	v_med3_f32 v119, v119, 0, v240
	v_med3_f32 v120, v120, 0, v240
	v_med3_f32 v121, v121, 0, v240
	v_mul_f32_e32 v160, v2, v118
	v_mul_f32_e32 v161, v3, v119
	v_mul_f32_e32 v162, v4, v120
	v_mul_f32_e32 v163, v5, v121
	v_add_f32_e32 v159, v160, v161
	v_add_f32_e32 v159, v162, v159
	v_add_f32_e32 v159, v163, v159
	s_nop 1
	v_permlane16_swap_b32_e32 v156, v157
	v_permlane16_swap_b32_e32 v158, v159
	v_add_f32_e32 v156, v156, v157
	v_add_f32_e32 v158, v158, v159
	s_nop 1
	v_permlane32_swap_b32_e32 v156, v158
	v_ashrrev_i32_e32 v164, 31, v156
	v_ashrrev_i32_e32 v165, 31, v158
	v_or_b32_e32 v164, 0x80000000, v164
	v_or_b32_e32 v165, 0x80000000, v165
	v_xor_b32_e32 v164, v156, v164
	v_xor_b32_e32 v165, v158, v165
	v_and_b32_e32 v164, 0xffffff00, v164
	v_and_b32_e32 v165, 0xffffff00, v165
	v_cmp_ge_i32_e32 vcc, s5, v242
	s_nop 1
	v_cndmask_b32_e32 v223, 0, v164, vcc
	v_cmp_ge_i32_e32 vcc, s67, v242
	s_nop 1
	v_cndmask_b32_e32 v165, 0, v165, vcc
	global_store_dword v168, v165, s[8:9] offset:2816
	s_branch .Lsc_zero3
.Lsc_drain2:
	s_nop 7
	s_nop 7
	s_sub_i32 s5, s57, 448
	s_add_i32 s67, s5, 1
	v_med3_f32 v106, v106, 0, v240
	v_med3_f32 v107, v107, 0, v240
	v_med3_f32 v108, v108, 0, v240
	v_med3_f32 v109, v109, 0, v240
	v_mul_f32_e32 v160, v2, v106
	v_mul_f32_e32 v161, v3, v107
	v_mul_f32_e32 v162, v4, v108
	v_mul_f32_e32 v163, v5, v109
	v_add_f32_e32 v156, v160, v161
	v_add_f32_e32 v156, v162, v156
	v_add_f32_e32 v156, v163, v156
	v_med3_f32 v110, v110, 0, v240
	v_med3_f32 v111, v111, 0, v240
	v_med3_f32 v112, v112, 0, v240
	v_med3_f32 v113, v113, 0, v240
	v_mul_f32_e32 v160, v2, v110
	v_mul_f32_e32 v161, v3, v111
	v_mul_f32_e32 v162, v4, v112
	v_mul_f32_e32 v163, v5, v113
	v_add_f32_e32 v157, v160, v161
	v_add_f32_e32 v157, v162, v157
	v_add_f32_e32 v157, v163, v157
	v_med3_f32 v114, v114, 0, v240
	v_med3_f32 v115, v115, 0, v240
	v_med3_f32 v116, v116, 0, v240
	v_med3_f32 v117, v117, 0, v240
	v_mul_f32_e32 v160, v2, v114
	v_mul_f32_e32 v161, v3, v115
	v_mul_f32_e32 v162, v4, v116
	v_mul_f32_e32 v163, v5, v117
	v_add_f32_e32 v158, v160, v161
	v_add_f32_e32 v158, v162, v158
	v_add_f32_e32 v158, v163, v158
	v_med3_f32 v118, v118, 0, v240
	v_med3_f32 v119, v119, 0, v240
	v_med3_f32 v120, v120, 0, v240
	v_med3_f32 v121, v121, 0, v240
	v_mul_f32_e32 v160, v2, v118
	v_mul_f32_e32 v161, v3, v119
	v_mul_f32_e32 v162, v4, v120
	v_mul_f32_e32 v163, v5, v121
	v_add_f32_e32 v159, v160, v161
	v_add_f32_e32 v159, v162, v159
	v_add_f32_e32 v159, v163, v159
	s_nop 1
	v_permlane16_swap_b32_e32 v156, v157
	v_permlane16_swap_b32_e32 v158, v159
	v_add_f32_e32 v156, v156, v157
	v_add_f32_e32 v158, v158, v159
	s_nop 1
	v_permlane32_swap_b32_e32 v156, v158
	v_ashrrev_i32_e32 v164, 31, v156
	v_ashrrev_i32_e32 v165, 31, v158
	v_or_b32_e32 v164, 0x80000000, v164
	v_or_b32_e32 v165, 0x80000000, v165
	v_xor_b32_e32 v164, v156, v164
	v_xor_b32_e32 v165, v158, v165
	v_and_b32_e32 v164, 0xffffff00, v164
	v_and_b32_e32 v165, 0xffffff00, v165
	v_cmp_ge_i32_e32 vcc, s5, v242
	s_nop 1
	v_cndmask_b32_e32 v219, 0, v164, vcc
	v_cmp_ge_i32_e32 vcc, s67, v242
	s_nop 1
	v_cndmask_b32_e32 v165, 0, v165, vcc
	global_store_dword v168, v165, s[8:9] offset:1792
	s_branch .Lsc_zero2
.Lsc_drain1:
	s_nop 7
	s_nop 7
	s_sub_i32 s5, s57, 192
	s_add_i32 s67, s5, 1
	v_med3_f32 v106, v106, 0, v240
	v_med3_f32 v107, v107, 0, v240
	v_med3_f32 v108, v108, 0, v240
	v_med3_f32 v109, v109, 0, v240
	v_mul_f32_e32 v160, v2, v106
	v_mul_f32_e32 v161, v3, v107
	v_mul_f32_e32 v162, v4, v108
	v_mul_f32_e32 v163, v5, v109
	v_add_f32_e32 v156, v160, v161
	v_add_f32_e32 v156, v162, v156
	v_add_f32_e32 v156, v163, v156
	v_med3_f32 v110, v110, 0, v240
	v_med3_f32 v111, v111, 0, v240
	v_med3_f32 v112, v112, 0, v240
	v_med3_f32 v113, v113, 0, v240
	v_mul_f32_e32 v160, v2, v110
	v_mul_f32_e32 v161, v3, v111
	v_mul_f32_e32 v162, v4, v112
	v_mul_f32_e32 v163, v5, v113
	v_add_f32_e32 v157, v160, v161
	v_add_f32_e32 v157, v162, v157
	v_add_f32_e32 v157, v163, v157
	v_med3_f32 v114, v114, 0, v240
	v_med3_f32 v115, v115, 0, v240
	v_med3_f32 v116, v116, 0, v240
	v_med3_f32 v117, v117, 0, v240
	v_mul_f32_e32 v160, v2, v114
	v_mul_f32_e32 v161, v3, v115
	v_mul_f32_e32 v162, v4, v116
	v_mul_f32_e32 v163, v5, v117
	v_add_f32_e32 v158, v160, v161
	v_add_f32_e32 v158, v162, v158
	v_add_f32_e32 v158, v163, v158
	v_med3_f32 v118, v118, 0, v240
	v_med3_f32 v119, v119, 0, v240
	v_med3_f32 v120, v120, 0, v240
	v_med3_f32 v121, v121, 0, v240
	v_mul_f32_e32 v160, v2, v118
	v_mul_f32_e32 v161, v3, v119
	v_mul_f32_e32 v162, v4, v120
	v_mul_f32_e32 v163, v5, v121
	v_add_f32_e32 v159, v160, v161
	v_add_f32_e32 v159, v162, v159
	v_add_f32_e32 v159, v163, v159
	s_nop 1
	v_permlane16_swap_b32_e32 v156, v157
	v_permlane16_swap_b32_e32 v158, v159
	v_add_f32_e32 v156, v156, v157
	v_add_f32_e32 v158, v158, v159
	s_nop 1
	v_permlane32_swap_b32_e32 v156, v158
	v_ashrrev_i32_e32 v164, 31, v156
	v_ashrrev_i32_e32 v165, 31, v158
	v_or_b32_e32 v164, 0x80000000, v164
	v_or_b32_e32 v165, 0x80000000, v165
	v_xor_b32_e32 v164, v156, v164
	v_xor_b32_e32 v165, v158, v165
	v_and_b32_e32 v164, 0xffffff00, v164
	v_and_b32_e32 v165, 0xffffff00, v165
	v_cmp_ge_i32_e32 vcc, s5, v242
	s_nop 1
	v_cndmask_b32_e32 v155, 0, v164, vcc
	v_cmp_ge_i32_e32 vcc, s67, v242
	s_nop 1
	v_cndmask_b32_e32 v165, 0, v165, vcc
	global_store_dword v168, v165, s[8:9] offset:768
	s_branch .Lsc_zero1
.Lsc_zero1:
	v_mov_b32_e32 v212, 0
	global_store_dword v168, v169, s[8:9] offset:1024
	v_mov_b32_e32 v217, 0
	global_store_dword v168, v169, s[8:9] offset:1280
	v_mov_b32_e32 v218, 0
	global_store_dword v168, v169, s[8:9] offset:1536
	v_mov_b32_e32 v219, 0
	global_store_dword v168, v169, s[8:9] offset:1792
.Lsc_zero2:
	v_mov_b32_e32 v220, 0
	global_store_dword v168, v169, s[8:9] offset:2048
	v_mov_b32_e32 v221, 0
	global_store_dword v168, v169, s[8:9] offset:2304
	v_mov_b32_e32 v222, 0
	global_store_dword v168, v169, s[8:9] offset:2560
	v_mov_b32_e32 v223, 0
	global_store_dword v168, v169, s[8:9] offset:2816
.Lsc_zero3:
	v_mov_b32_e32 v224, 0
	global_store_dword v168, v169, s[8:9] offset:3072
	v_mov_b32_e32 v225, 0
	global_store_dword v168, v169, s[8:9] offset:3328
	v_mov_b32_e32 v226, 0
	global_store_dword v168, v169, s[8:9] offset:3584
	v_mov_b32_e32 v227, 0
	global_store_dword v168, v169, s[8:9] offset:3840
.Lsc_zero4:
	v_mov_b32_e32 v228, 0
	global_store_dword v168, v169, s[14:15]
	v_mov_b32_e32 v229, 0
	global_store_dword v168, v169, s[14:15] offset:256
	v_mov_b32_e32 v230, 0
	global_store_dword v168, v169, s[14:15] offset:512
	v_mov_b32_e32 v231, 0
	global_store_dword v168, v169, s[14:15] offset:768
.Lsc_zero5:
	v_mov_b32_e32 v232, 0
	global_store_dword v168, v169, s[14:15] offset:1024
	v_mov_b32_e32 v233, 0
	global_store_dword v168, v169, s[14:15] offset:1280
	v_mov_b32_e32 v234, 0
	global_store_dword v168, v169, s[14:15] offset:1536
	v_mov_b32_e32 v235, 0
	global_store_dword v168, v169, s[14:15] offset:1792
.Lsc_zero6:
	v_mov_b32_e32 v236, 0
	global_store_dword v168, v169, s[14:15] offset:2048
	v_mov_b32_e32 v237, 0
	global_store_dword v168, v169, s[14:15] offset:2304
	v_mov_b32_e32 v244, 0
	global_store_dword v168, v169, s[14:15] offset:2560
	v_mov_b32_e32 v245, 0
	global_store_dword v168, v169, s[14:15] offset:2816
.Lsc_zero7:
	v_mov_b32_e32 v246, 0
	global_store_dword v168, v169, s[14:15] offset:3072
	v_mov_b32_e32 v247, 0
	global_store_dword v168, v169, s[14:15] offset:3328
	v_mov_b32_e32 v248, 0
	global_store_dword v168, v169, s[14:15] offset:3584
	v_mov_b32_e32 v249, 0
	global_store_dword v168, v169, s[14:15] offset:3840
.Lsc_zero8:
	v_mov_b32_e32 v250, 0
	global_store_dword v168, v169, s[46:47]
	v_mov_b32_e32 v251, 0
	global_store_dword v168, v169, s[46:47] offset:256
	v_mov_b32_e32 v252, 0
	global_store_dword v168, v169, s[46:47] offset:512
	v_mov_b32_e32 v253, 0
	global_store_dword v168, v169, s[46:47] offset:768
.Lsc_zero9:
	v_mov_b32_e32 v196, 0
	global_store_dword v168, v169, s[46:47] offset:1024
	v_mov_b32_e32 v197, 0
	global_store_dword v168, v169, s[46:47] offset:1280
	v_mov_b32_e32 v198, 0
	global_store_dword v168, v169, s[46:47] offset:1536
	v_mov_b32_e32 v199, 0
	global_store_dword v168, v169, s[46:47] offset:1792
.Lsc_zero10:
	v_mov_b32_e32 v201, 0
	global_store_dword v168, v169, s[46:47] offset:2048
	v_mov_b32_e32 v200, 0
	global_store_dword v168, v169, s[46:47] offset:2304
	v_mov_b32_e32 v238, 0
	global_store_dword v168, v169, s[46:47] offset:2560
	v_mov_b32_e32 v131, 0
	global_store_dword v168, v169, s[46:47] offset:2816
.Lsc_zero11:
	v_mov_b32_e32 v132, 0
	global_store_dword v168, v169, s[46:47] offset:3072
	v_mov_b32_e32 v133, 0
	global_store_dword v168, v169, s[46:47] offset:3328
	v_mov_b32_e32 v134, 0
	global_store_dword v168, v169, s[46:47] offset:3584
	v_mov_b32_e32 v135, 0
	global_store_dword v168, v169, s[46:47] offset:3840
.Lsc_zero12:
	v_mov_b32_e32 v136, 0
	global_store_dword v168, v169, s[68:69]
	v_mov_b32_e32 v137, 0
	global_store_dword v168, v169, s[68:69] offset:256
	v_mov_b32_e32 v138, 0
	global_store_dword v168, v169, s[68:69] offset:512
	v_mov_b32_e32 v139, 0
	global_store_dword v168, v169, s[68:69] offset:768
.Lsc_zero13:
	v_mov_b32_e32 v140, 0
	global_store_dword v168, v169, s[68:69] offset:1024
	v_mov_b32_e32 v141, 0
	global_store_dword v168, v169, s[68:69] offset:1280
	v_mov_b32_e32 v142, 0
	global_store_dword v168, v169, s[68:69] offset:1536
	v_mov_b32_e32 v143, 0
	global_store_dword v168, v169, s[68:69] offset:1792
.Lsc_zero14:
	v_mov_b32_e32 v144, 0
	global_store_dword v168, v169, s[68:69] offset:2048
	v_mov_b32_e32 v145, 0
	global_store_dword v168, v169, s[68:69] offset:2304
	v_mov_b32_e32 v146, 0
	global_store_dword v168, v169, s[68:69] offset:2560
	v_mov_b32_e32 v147, 0
	global_store_dword v168, v169, s[68:69] offset:2816
.Lsc_zero15:
	v_mov_b32_e32 v148, 0
	global_store_dword v168, v169, s[68:69] offset:3072
	v_mov_b32_e32 v149, 0
	global_store_dword v168, v169, s[68:69] offset:3328
	v_mov_b32_e32 v150, 0
	global_store_dword v168, v169, s[68:69] offset:3584
	v_mov_b32_e32 v151, 0
	global_store_dword v168, v169, s[68:69] offset:3840
.Lsc_tail:
	v_mov_b32_e32 v2, v152
	v_mov_b32_e32 v6, v153
	v_mov_b32_e32 v5, v154
	v_mov_b32_e32 v4, v155
	s_mov_b32 s14, 0
	s_mov_b32 s46, 32
	s_mov_b32 s18, 0
	s_branch .LBB0_1055

.LselA_done:
	s_lshl_b64 s[4:5], s[56:57], 9
	v_lshl_add_u64 v[4:5], v[122:123], 0, s[4:5]
	global_store_dwordx2 v[4:5], v[2:3], off
	v_readfirstlane_b32 s4, v24
	v_readfirstlane_b32 s5, v25
	v_lshlrev_b32_e32 v3, 2, v242
	s_nop 4
	global_load_dword v2, v3, s[4:5]
	global_load_dword v225, v3, s[4:5] offset:256
	global_load_dword v224, v3, s[4:5] offset:512
	global_load_dword v223, v3, s[4:5] offset:768
	global_load_dword v222, v3, s[4:5] offset:1024
	global_load_dword v221, v3, s[4:5] offset:1280
	global_load_dword v220, v3, s[4:5] offset:1536
	global_load_dword v219, v3, s[4:5] offset:1792
	global_load_dword v218, v3, s[4:5] offset:2048
	global_load_dword v217, v3, s[4:5] offset:2304
	global_load_dword v216, v3, s[4:5] offset:2560
	global_load_dword v215, v3, s[4:5] offset:2816
	global_load_dword v214, v3, s[4:5] offset:3072
	global_load_dword v213, v3, s[4:5] offset:3328
	global_load_dword v212, v3, s[4:5] offset:3584
	global_load_dword v211, v3, s[4:5] offset:3840
	s_add_u32 s4, s4, 0x1000
	s_addc_u32 s5, s5, 0
	s_nop 0
	global_load_dword v210, v3, s[4:5]
	global_load_dword v209, v3, s[4:5] offset:256
	global_load_dword v208, v3, s[4:5] offset:512
	global_load_dword v207, v3, s[4:5] offset:768
	global_load_dword v206, v3, s[4:5] offset:1024
	global_load_dword v205, v3, s[4:5] offset:1280
	global_load_dword v204, v3, s[4:5] offset:1536
	global_load_dword v201, v3, s[4:5] offset:1792
	global_load_dword v200, v3, s[4:5] offset:2048
	global_load_dword v199, v3, s[4:5] offset:2304
	global_load_dword v198, v3, s[4:5] offset:2560
	global_load_dword v197, v3, s[4:5] offset:2816
	global_load_dword v196, v3, s[4:5] offset:3072
	global_load_dword v194, v3, s[4:5] offset:3328
	global_load_dword v193, v3, s[4:5] offset:3584
	global_load_dword v192, v3, s[4:5] offset:3840
	s_add_u32 s4, s4, 0x1000
	s_addc_u32 s5, s5, 0
	s_nop 0
	global_load_dword v191, v3, s[4:5]
	global_load_dword v151, v3, s[4:5] offset:256
	global_load_dword v150, v3, s[4:5] offset:512
	global_load_dword v149, v3, s[4:5] offset:768
	global_load_dword v148, v3, s[4:5] offset:1024
	global_load_dword v147, v3, s[4:5] offset:1280
	global_load_dword v146, v3, s[4:5] offset:1536
	global_load_dword v145, v3, s[4:5] offset:1792
	global_load_dword v144, v3, s[4:5] offset:2048
	global_load_dword v143, v3, s[4:5] offset:2304
	global_load_dword v142, v3, s[4:5] offset:2560
	global_load_dword v141, v3, s[4:5] offset:2816
	global_load_dword v140, v3, s[4:5] offset:3072
	global_load_dword v139, v3, s[4:5] offset:3328
	global_load_dword v138, v3, s[4:5] offset:3584
	global_load_dword v137, v3, s[4:5] offset:3840
	s_add_u32 s4, s4, 0x1000
	s_addc_u32 s5, s5, 0
	s_nop 0
	global_load_dword v136, v3, s[4:5]
	global_load_dword v135, v3, s[4:5] offset:256
	global_load_dword v134, v3, s[4:5] offset:512
	global_load_dword v133, v3, s[4:5] offset:768
	global_load_dword v132, v3, s[4:5] offset:1024
	global_load_dword v131, v3, s[4:5] offset:1280
	global_load_dword v13, v3, s[4:5] offset:1536
	global_load_dword v12, v3, s[4:5] offset:1792
	global_load_dword v11, v3, s[4:5] offset:2048
	global_load_dword v10, v3, s[4:5] offset:2304
	global_load_dword v9, v3, s[4:5] offset:2560
	global_load_dword v8, v3, s[4:5] offset:2816
	global_load_dword v7, v3, s[4:5] offset:3072
	global_load_dword v6, v3, s[4:5] offset:3328
	global_load_dword v5, v3, s[4:5] offset:3584
	global_load_dword v4, v3, s[4:5] offset:3840
	s_mov_b32 s14, 0
	s_mov_b32 s46, 32
	s_mov_b32 s18, 0
	s_branch .LBB0_1223

.Llong_547:
	s_getpc_b64 s[98:99]
